# dilated window attention loops: removed 72 more compiler-inserted s_nop 0 pads after inline v_max3
# baseline (speedup 1.0000x reference)
; DI void attn_d6_loop(char* lds, const Params& p, int layer, int first, int stride, int total) {
;     ...
;   const float slope2 = exp2f(-(float)(2 * h + 2)) * LOG2E * (float)dl;
;   __syncthreads();
; #pragma unroll
;   for (int c = 0; c < 6; ++c) {
;     *(u32x4*)(lds + (64 * c + srow) * KST + sc * 16) = kr[c];
;     *(u32x4*)(lds + VOFF + (64 * c + srow) * KST + sc * 16) = vr[c];
;   }
;   __syncthreads();
;   if (u + stride < total) load_unit(u + stride);
;   f32x16 O0 = zero16(), O1 = zero16();
;   float m = -1e30f, l = 0.f;
; #pragma unroll
;   for (int cc_ = 0; cc_ < 3; ++cc_) { const int c = (wid >> 1) + cc_;
; #pragma unroll
;     for (int hf = 0; hf < 2; ++hf) {
;       const bool skip = (hf == 0) ? ((wid & 1) && c == (wid >> 1)) : (!(wid & 1) && c == (wid >> 1) + 2);
;       if (skip) continue;
;       const int key0 = q0 - 64 + 64 * c + 32 * hf;
;       f32x16 S = zero16();
.LBB0_501:
	s_and_saveexec_b64 s[82:83], s[70:71]
	s_xor_b64 s[82:83], exec, s[82:83]
	s_or_saveexec_b64 s[82:83], s[82:83]
	v_cndmask_b32_e64 v1, 0, v240, s[74:75]
	v_sub_f32_e32 v0, v1, v0
	v_exp_f32_e32 v0, v0
	s_lshl_b32 s4, 1, s1
	v_cvt_f32_u32_e32 v1, s4
	v_mov_b32_e32 v14, v113
	v_ldexp_f32 v0, v0, s81
	v_mul_f32_e32 v0, 0xbfb8aa3b, v0
	v_mov_b32_e32 v15, v113
	v_mul_f32_e32 v129, v0, v1
	v_mov_b32_e32 v0, v113
	v_mov_b32_e32 v1, v113
	v_mov_b32_e32 v2, v113
	v_mov_b32_e32 v3, v113
	v_mov_b32_e32 v4, v113
	v_mov_b32_e32 v5, v113
	v_mov_b32_e32 v6, v113
	v_mov_b32_e32 v7, v113
	v_mov_b32_e32 v8, v113
	v_mov_b32_e32 v9, v113
	v_mov_b32_e32 v10, v113
	v_mov_b32_e32 v11, v113
	v_mov_b32_e32 v12, v113
	v_mov_b32_e32 v13, v113
	v_mov_b64_e32 v[30:31], v[14:15]
	s_lshr_b32 s1, 0x1000, s1
	v_mov_b32_e32 v245, 0
	v_mov_b32_e32 v243, 0xf149f2ca
	v_mov_b64_e32 v[28:29], v[12:13]
	v_mov_b64_e32 v[26:27], v[10:11]
	v_mov_b64_e32 v[24:25], v[8:9]
	v_mov_b64_e32 v[22:23], v[6:7]
	v_mov_b64_e32 v[20:21], v[4:5]
	v_mov_b64_e32 v[18:19], v[2:3]
	v_mov_b64_e32 v[16:17], v[0:1]
	s_xor_b64 exec, exec, s[82:83]
	s_cbranch_execz .LBB0_506
; DI f32x16 mfma32(bf16x8 a, bf16x8 b, f32x16 c) { return __builtin_amdgcn_mfma_f32_32x32x16_bf16(a, b, c, 0, 0, 0); }
; DI float max3f(float a, float b, float c) { float d; asm("v_max3_f32 %0, %1, %2, %3" : "=v"(d) : "v"(a), "v"(b), "v"(c)); return d; }
; DI void attn_d6_loop(char* lds, const Params& p, int layer, int first, int stride, int total) {
;     ...
;       f32x16 S = zero16();
;       const char* kb = lds + (64 * c + 32 * hf + lr) * KST + lh * 16;
; #pragma unroll
;       for (int ks = 0; ks < 4; ++ks) S = mfma32(*(const bf16x8*)(kb + ks * 32), qf[ks], S);
;       const int rel0 = key0 + 4 * lh - qrow;
; #pragma unroll
;       for (int r2 = 0; r2 < 16; ++r2) { const int rel = rel0 + (r2 & 3) + 8 * (r2 >> 2), v = qrow + rel;
;         const bool ok = (rel >= -64) && (rel <= 64) && (v >= 0) && (v < L); S[r2] = ok ? fmaf(-slope2, fabsf((float)rel), S[r2]) : -1e30f; }
;       float mx = S[0];
; #pragma unroll
;       for (int r2 = 1; r2 < 15; r2 += 2) mx = max3f(mx, S[r2], S[r2 + 1]);
;       mx = fmaxf(mx, S[15]);
;       if (__any(mx > m + 8.f)) {
;         mx = fmaxf(mx, __shfl_xor(mx, 32));
;         const float mnew = fmaxf(m, mx);
;         const float al = __builtin_amdgcn_exp2f(m - mnew); l *= al; O0 *= al; O1 *= al;
;         m = mnew;
;       }
	ds_read_b128 v[0:3], v200
	ds_read_b128 v[16:19], v200 offset:32
	v_readlane_b32 s4, v251, 63
	v_readlane_b32 s5, v253, 0
	s_waitcnt vmcnt(3) lgkmcnt(1)
	v_mfma_f32_32x32x16_bf16 v[0:15], v[0:3], v[104:107], 0
	s_waitcnt vmcnt(2) lgkmcnt(0)
	v_mfma_f32_32x32x16_bf16 v[0:15], v[16:19], v[108:111], v[0:15]
	ds_read_b128 v[16:19], v200 offset:64
	s_waitcnt vmcnt(1) lgkmcnt(0)
	v_mfma_f32_32x32x16_bf16 v[0:15], v[16:19], v[100:103], v[0:15]
	ds_read_b128 v[16:19], v200 offset:96
	s_waitcnt vmcnt(0) lgkmcnt(0)
	v_mfma_f32_32x32x16_bf16 v[0:15], v[16:19], v[96:99], v[0:15]
	v_add_u32_e32 v16, v131, v136
	v_cmp_lt_i32_e32 vcc, -1, v16
	s_and_b64 s[74:75], s[4:5], vcc
	v_cmp_gt_i32_e32 vcc, s1, v16
	v_cvt_f32_i32_e32 v16, v136
	v_add_u32_e32 v17, 1, v136
	s_and_b64 vcc, s[74:75], vcc
	v_readlane_b32 s4, v253, 1
	s_nop 3
	v_fma_f32 v0, v129, |v16|, v0
	v_add_u32_e32 v16, v131, v17
	v_cndmask_b32_e32 v0, v241, v0, vcc
	v_cmp_lt_i32_e32 vcc, -1, v16
	v_readlane_b32 s5, v253, 2
	s_and_b64 s[74:75], s[4:5], vcc
	v_cmp_gt_i32_e32 vcc, s1, v16
	v_cvt_f32_i32_e32 v16, v17
	v_add_u32_e32 v17, 2, v136
	s_and_b64 vcc, s[74:75], vcc
	v_readlane_b32 s4, v253, 3
	v_fma_f32 v1, v129, |v16|, v1
	v_add_u32_e32 v16, v131, v17
	v_cndmask_b32_e32 v1, v241, v1, vcc
	v_cmp_lt_i32_e32 vcc, -1, v16
	v_readlane_b32 s5, v253, 4
	s_and_b64 s[74:75], s[4:5], vcc
	v_cmp_gt_i32_e32 vcc, s1, v16
	v_cvt_f32_i32_e32 v16, v17
	s_and_b64 vcc, s[74:75], vcc
	v_readlane_b32 s4, v253, 5
	v_readlane_b32 s5, v253, 6
	v_fma_f32 v2, v129, |v16|, v2
	v_add_u32_e32 v16, v131, v249
	v_cndmask_b32_e32 v2, v241, v2, vcc
	v_cmp_lt_i32_e32 vcc, -1, v16
	s_and_b64 s[74:75], s[4:5], vcc
	v_cmp_gt_i32_e32 vcc, s1, v16
	v_cvt_f32_i32_e32 v16, v249
	s_and_b64 vcc, s[74:75], vcc
	v_readlane_b32 s4, v253, 7
	v_readlane_b32 s5, v253, 8
	v_fma_f32 v3, v129, |v16|, v3
	v_add_u32_e32 v16, v131, v250
	v_cndmask_b32_e32 v3, v241, v3, vcc
	v_cmp_lt_i32_e32 vcc, -1, v16
	s_and_b64 s[74:75], s[4:5], vcc
	v_cmp_gt_i32_e32 vcc, s1, v16
	v_cvt_f32_i32_e32 v16, v250
	s_and_b64 vcc, s[74:75], vcc
	v_readlane_b32 s4, v253, 9
	v_readlane_b32 s5, v253, 10
	v_fma_f32 v4, v129, |v16|, v4
	v_add_u32_e32 v16, v131, v238
	v_cndmask_b32_e32 v4, v241, v4, vcc
	v_cmp_lt_i32_e32 vcc, -1, v16
	s_and_b64 s[74:75], s[4:5], vcc
	v_cmp_gt_i32_e32 vcc, s1, v16
	v_cvt_f32_i32_e32 v16, v238
	s_and_b64 vcc, s[74:75], vcc
	v_readlane_b32 s4, v253, 11
	v_readlane_b32 s5, v253, 12
	v_fma_f32 v5, v129, |v16|, v5
	v_add_u32_e32 v16, v131, v239
	v_cndmask_b32_e32 v5, v241, v5, vcc
	v_cmp_lt_i32_e32 vcc, -1, v16
	s_and_b64 s[74:75], s[4:5], vcc
	v_cmp_gt_i32_e32 vcc, s1, v16
	v_cvt_f32_i32_e32 v16, v239
	s_and_b64 vcc, s[74:75], vcc
	v_readlane_b32 s4, v253, 13
	v_readlane_b32 s5, v253, 14
	v_fma_f32 v6, v129, |v16|, v6
	v_add_u32_e32 v16, v131, v242
	v_cndmask_b32_e32 v6, v241, v6, vcc
	v_cmp_lt_i32_e32 vcc, -1, v16
	s_and_b64 s[74:75], s[4:5], vcc
	v_cmp_gt_i32_e32 vcc, s1, v16
	v_cvt_f32_i32_e32 v16, v242
	s_and_b64 vcc, s[74:75], vcc
	v_readlane_b32 s4, v253, 15
	v_readlane_b32 s5, v253, 16
	v_fma_f32 v7, v129, |v16|, v7
	v_add_u32_e32 v16, v131, v137
	v_cndmask_b32_e32 v7, v241, v7, vcc
	v_cmp_lt_i32_e32 vcc, -1, v16
	s_and_b64 s[74:75], s[4:5], vcc
	v_cmp_gt_i32_e32 vcc, s1, v16
	v_cvt_f32_i32_e32 v16, v137
	s_and_b64 vcc, s[74:75], vcc
	v_readlane_b32 s4, v253, 17
	v_readlane_b32 s5, v253, 18
	v_fma_f32 v8, v129, |v16|, v8
	v_add_u32_e32 v16, v131, v248
	v_cndmask_b32_e32 v8, v241, v8, vcc
	v_cmp_lt_i32_e32 vcc, -1, v16
	s_and_b64 s[74:75], s[4:5], vcc
	v_cmp_gt_i32_e32 vcc, s1, v16
	v_cvt_f32_i32_e32 v16, v248
	s_and_b64 vcc, s[74:75], vcc
	v_readlane_b32 s4, v253, 19
	v_readlane_b32 s5, v253, 20
	v_fma_f32 v9, v129, |v16|, v9
	v_add_u32_e32 v16, v131, v146
	v_cndmask_b32_e32 v9, v241, v9, vcc
	v_cmp_lt_i32_e32 vcc, -1, v16
	s_and_b64 s[74:75], s[4:5], vcc
	v_cmp_gt_i32_e32 vcc, s1, v16
	v_cvt_f32_i32_e32 v16, v146
	s_and_b64 vcc, s[74:75], vcc
	v_readlane_b32 s4, v253, 21
	v_readlane_b32 s5, v253, 22
	v_fma_f32 v10, v129, |v16|, v10
	v_add_u32_e32 v16, v131, v147
	v_cndmask_b32_e32 v10, v241, v10, vcc
	v_cmp_lt_i32_e32 vcc, -1, v16
	s_and_b64 s[74:75], s[4:5], vcc
	v_cmp_gt_i32_e32 vcc, s1, v16
	v_cvt_f32_i32_e32 v16, v147
	s_and_b64 vcc, s[74:75], vcc
	v_readlane_b32 s4, v253, 23
	v_readlane_b32 s5, v253, 24
	v_fma_f32 v11, v129, |v16|, v11
	v_add_u32_e32 v16, v131, v148
	v_cndmask_b32_e32 v11, v241, v11, vcc
	v_cmp_lt_i32_e32 vcc, -1, v16
	s_and_b64 s[74:75], s[4:5], vcc
	v_cmp_gt_i32_e32 vcc, s1, v16
	v_cvt_f32_i32_e32 v16, v148
	s_and_b64 vcc, s[74:75], vcc
	v_readlane_b32 s4, v253, 25
	v_readlane_b32 s5, v253, 26
	v_fma_f32 v12, v129, |v16|, v12
	v_add_u32_e32 v16, v131, v149
	v_cndmask_b32_e32 v12, v241, v12, vcc
	v_cmp_lt_i32_e32 vcc, -1, v16
	s_and_b64 s[74:75], s[4:5], vcc
	v_cmp_gt_i32_e32 vcc, s1, v16
	v_cvt_f32_i32_e32 v16, v149
	s_and_b64 vcc, s[74:75], vcc
	v_readlane_b32 s4, v253, 27
	v_readlane_b32 s5, v253, 28
	v_fma_f32 v13, v129, |v16|, v13
	v_add_u32_e32 v16, v131, v150
	v_cndmask_b32_e32 v13, v241, v13, vcc
	v_cmp_lt_i32_e32 vcc, -1, v16
	s_and_b64 s[74:75], s[4:5], vcc
	v_cmp_gt_i32_e32 vcc, s1, v16
	v_cvt_f32_i32_e32 v16, v150
	s_and_b64 vcc, s[74:75], vcc
	v_readlane_b32 s4, v253, 29
	v_readlane_b32 s5, v253, 30
	v_fma_f32 v14, v129, |v16|, v14
	v_add_u32_e32 v16, v131, v151
	v_cndmask_b32_e32 v14, v241, v14, vcc
	v_cmp_lt_i32_e32 vcc, -1, v16
	s_and_b64 s[74:75], s[4:5], vcc
	v_cmp_gt_i32_e32 vcc, s1, v16
	v_cvt_f32_i32_e32 v16, v151
	s_and_b64 vcc, s[74:75], vcc
	v_fma_f32 v15, v129, |v16|, v15
	v_max3_f32 v16, v0, v1, v2
	v_cndmask_b32_e32 v15, v241, v15, vcc
	v_max3_f32 v16, v16, v3, v4
	v_max3_f32 v16, v16, v5, v6
	v_max3_f32 v16, v16, v7, v8
	v_max3_f32 v16, v16, v9, v10
	v_max3_f32 v16, v16, v11, v12
	v_max3_f32 v16, v16, v13, v14
	v_max_f32_e32 v16, v16, v16
	v_max_f32_e32 v16, v16, v15
	v_cmp_lt_f32_e32 vcc, s37, v16
	s_cbranch_vccz .LBB0_504
	v_and_b32_e32 v18, 64, v226
	v_xor_b32_e32 v17, 32, v226
	v_add_u32_e32 v18, 64, v18
	v_cmp_lt_i32_e32 vcc, v17, v18
	s_nop 1
	v_cndmask_b32_e32 v17, v226, v17, vcc
	v_lshlrev_b32_e32 v17, 2, v17
	ds_bpermute_b32 v17, v17, v16
	s_waitcnt lgkmcnt(0)
	v_max3_f32 v243, v16, v17, s37
	v_sub_f32_e32 v16, 0xf149f2ca, v243
	v_exp_f32_e32 v16, v16
	s_nop 0
	v_mul_f32_e32 v32, 0, v16
	s_branch .LBB0_505

; DI f32x16 mfma32(bf16x8 a, bf16x8 b, f32x16 c) { return __builtin_amdgcn_mfma_f32_32x32x16_bf16(a, b, c, 0, 0, 0); }
; DI float max3f(float a, float b, float c) { float d; asm("v_max3_f32 %0, %1, %2, %3" : "=v"(d) : "v"(a), "v"(b), "v"(c)); return d; }
; DI void attn_d6_loop(char* lds, const Params& p, int layer, int first, int stride, int total) {
;     ...
;       const int key0 = q0 - 64 + 64 * c + 32 * hf;
;       f32x16 S = zero16();
;       const char* kb = lds + (64 * c + 32 * hf + lr) * KST + lh * 16;
; #pragma unroll
;       for (int ks = 0; ks < 4; ++ks) S = mfma32(*(const bf16x8*)(kb + ks * 32), qf[ks], S);
;       const int rel0 = key0 + 4 * lh - qrow;
; #pragma unroll
;       for (int r2 = 0; r2 < 16; ++r2) { const int rel = rel0 + (r2 & 3) + 8 * (r2 >> 2), v = qrow + rel;
;         const bool ok = (rel >= -64) && (rel <= 64) && (v >= 0) && (v < L); S[r2] = ok ? fmaf(-slope2, fabsf((float)rel), S[r2]) : -1e30f; }
;       float mx = S[0];
; #pragma unroll
;       for (int r2 = 1; r2 < 15; r2 += 2) mx = max3f(mx, S[r2], S[r2 + 1]);
;       mx = fmaxf(mx, S[15]);
;       if (__any(mx > m + 8.f)) {
.LBB0_506:
	s_or_b64 exec, exec, s[82:83]
	ds_read_b128 v[32:35], v201
	ds_read_b128 v[138:141], v201 offset:32
	v_readlane_b32 s4, v251, 47
	v_readlane_b32 s5, v251, 48
	v_add_f32_e32 v244, 0x41000000, v243
	s_waitcnt vmcnt(3) lgkmcnt(1)
	v_mfma_f32_32x32x16_bf16 v[32:47], v[32:35], v[104:107], 0
	v_ashrrev_i32_e32 v133, 31, v132
	s_lshl_b32 s14, s0, 6
	s_waitcnt vmcnt(2) lgkmcnt(0)
	v_mfma_f32_32x32x16_bf16 v[32:47], v[138:141], v[108:111], v[32:47]
	ds_read_b128 v[138:141], v201 offset:64
	s_waitcnt vmcnt(1) lgkmcnt(0)
	v_mfma_f32_32x32x16_bf16 v[32:47], v[138:141], v[100:103], v[32:47]
	ds_read_b128 v[138:141], v201 offset:96
	s_waitcnt vmcnt(0) lgkmcnt(0)
	v_mfma_f32_32x32x16_bf16 v[32:47], v[138:141], v[96:99], v[32:47]
	v_add_u32_e32 v138, v131, v117
	v_cmp_lt_i32_e32 vcc, -1, v138
	s_and_b64 s[74:75], s[34:35], vcc
	v_cmp_gt_i32_e32 vcc, s1, v138
	v_cvt_f32_i32_e32 v138, v117
	s_and_b64 vcc, s[74:75], vcc
	s_nop 5
	v_fma_f32 v32, v129, |v138|, v32
	v_add_u32_e32 v138, v131, v152
	v_cndmask_b32_e32 v32, v241, v32, vcc
	v_cmp_lt_i32_e32 vcc, -1, v138
	s_and_b64 s[74:75], s[38:39], vcc
	v_cmp_gt_i32_e32 vcc, s1, v138
	v_cvt_f32_i32_e32 v138, v152
	s_and_b64 vcc, s[74:75], vcc
	v_fma_f32 v33, v129, |v138|, v33
	v_add_u32_e32 v138, v131, v153
	v_cndmask_b32_e32 v33, v241, v33, vcc
	v_cmp_lt_i32_e32 vcc, -1, v138
	s_and_b64 s[74:75], s[40:41], vcc
	v_cmp_gt_i32_e32 vcc, s1, v138
	v_cvt_f32_i32_e32 v138, v153
	s_and_b64 vcc, s[74:75], vcc
	v_fma_f32 v34, v129, |v138|, v34
	v_add_u32_e32 v138, v131, v154
	v_cndmask_b32_e32 v34, v241, v34, vcc
	v_cmp_lt_i32_e32 vcc, -1, v138
	s_and_b64 s[74:75], s[42:43], vcc
	v_cmp_gt_i32_e32 vcc, s1, v138
	v_cvt_f32_i32_e32 v138, v154
	s_and_b64 vcc, s[74:75], vcc
	v_fma_f32 v35, v129, |v138|, v35
	v_add_u32_e32 v138, v131, v155
	v_cndmask_b32_e32 v35, v241, v35, vcc
	v_cmp_lt_i32_e32 vcc, -1, v138
	s_and_b64 s[74:75], s[84:85], vcc
	v_cmp_gt_i32_e32 vcc, s1, v138
	v_cvt_f32_i32_e32 v138, v155
	s_and_b64 vcc, s[74:75], vcc
	v_fma_f32 v36, v129, |v138|, v36
	v_add_u32_e32 v138, v131, v156
	v_cndmask_b32_e32 v36, v241, v36, vcc
	v_cmp_lt_i32_e32 vcc, -1, v138
	s_and_b64 s[74:75], s[86:87], vcc
	v_cmp_gt_i32_e32 vcc, s1, v138
	v_cvt_f32_i32_e32 v138, v156
	s_and_b64 vcc, s[74:75], vcc
	v_fma_f32 v37, v129, |v138|, v37
	v_add_u32_e32 v138, v131, v157
	v_cndmask_b32_e32 v37, v241, v37, vcc
	v_cmp_lt_i32_e32 vcc, -1, v138
	s_and_b64 s[74:75], s[88:89], vcc
	v_cmp_gt_i32_e32 vcc, s1, v138
	v_cvt_f32_i32_e32 v138, v157
	s_and_b64 vcc, s[74:75], vcc
	v_fma_f32 v38, v129, |v138|, v38
	v_add_u32_e32 v138, v131, v158
	v_cndmask_b32_e32 v38, v241, v38, vcc
	v_cmp_lt_i32_e32 vcc, -1, v138
	s_and_b64 s[74:75], s[90:91], vcc
	v_cmp_gt_i32_e32 vcc, s1, v138
	v_cvt_f32_i32_e32 v138, v158
	s_and_b64 vcc, s[74:75], vcc
	v_fma_f32 v39, v129, |v138|, v39
	v_add_u32_e32 v138, v131, v159
	v_cndmask_b32_e32 v39, v241, v39, vcc
	v_cmp_lt_i32_e32 vcc, -1, v138
	s_and_b64 s[74:75], s[4:5], vcc
	v_cmp_gt_i32_e32 vcc, s1, v138
	v_cvt_f32_i32_e32 v138, v159
	s_and_b64 vcc, s[74:75], vcc
	v_readlane_b32 s4, v251, 49
	v_readlane_b32 s5, v251, 50
	v_fma_f32 v40, v129, |v138|, v40
	v_add_u32_e32 v138, v131, v160
	v_cndmask_b32_e32 v40, v241, v40, vcc
	v_cmp_lt_i32_e32 vcc, -1, v138
	s_and_b64 s[74:75], s[4:5], vcc
	v_cmp_gt_i32_e32 vcc, s1, v138
	v_cvt_f32_i32_e32 v138, v160
	s_and_b64 vcc, s[74:75], vcc
	v_readlane_b32 s4, v251, 37
	v_readlane_b32 s5, v251, 38
	v_fma_f32 v41, v129, |v138|, v41
	v_add_u32_e32 v138, v131, v161
	v_cndmask_b32_e32 v41, v241, v41, vcc
	v_cmp_lt_i32_e32 vcc, -1, v138
	s_and_b64 s[74:75], s[4:5], vcc
	v_cmp_gt_i32_e32 vcc, s1, v138
	v_cvt_f32_i32_e32 v138, v161
	s_and_b64 vcc, s[74:75], vcc
	v_readlane_b32 s4, v251, 39
	v_readlane_b32 s5, v251, 40
	v_fma_f32 v42, v129, |v138|, v42
	v_add_u32_e32 v138, v131, v162
	v_cndmask_b32_e32 v42, v241, v42, vcc
	v_cmp_lt_i32_e32 vcc, -1, v138
	s_and_b64 s[74:75], s[4:5], vcc
	v_cmp_gt_i32_e32 vcc, s1, v138
	v_cvt_f32_i32_e32 v138, v162
	s_and_b64 vcc, s[74:75], vcc
	v_readlane_b32 s4, v251, 41
	v_readlane_b32 s5, v251, 42
	v_fma_f32 v43, v129, |v138|, v43
	v_add_u32_e32 v138, v131, v163
	v_cndmask_b32_e32 v43, v241, v43, vcc
	v_cmp_lt_i32_e32 vcc, -1, v138
	s_and_b64 s[74:75], s[4:5], vcc
	v_cmp_gt_i32_e32 vcc, s1, v138
	v_cvt_f32_i32_e32 v138, v163
	s_and_b64 vcc, s[74:75], vcc
	v_readlane_b32 s4, v251, 43
	v_readlane_b32 s5, v251, 44
	v_fma_f32 v44, v129, |v138|, v44
	v_add_u32_e32 v138, v131, v164
	v_cndmask_b32_e32 v44, v241, v44, vcc
	v_cmp_lt_i32_e32 vcc, -1, v138
	s_and_b64 s[74:75], s[4:5], vcc
	v_cmp_gt_i32_e32 vcc, s1, v138
	v_cvt_f32_i32_e32 v138, v164
	s_and_b64 vcc, s[74:75], vcc
	v_readlane_b32 s4, v251, 45
	v_readlane_b32 s5, v251, 46
	v_fma_f32 v45, v129, |v138|, v45
	v_add_u32_e32 v138, v131, v165
	v_cndmask_b32_e32 v45, v241, v45, vcc
	v_cmp_lt_i32_e32 vcc, -1, v138
	s_and_b64 s[74:75], s[4:5], vcc
	v_cmp_gt_i32_e32 vcc, s1, v138
	v_cvt_f32_i32_e32 v138, v165
	s_and_b64 vcc, s[74:75], vcc
	v_readlane_b32 s4, v253, 31
	v_readlane_b32 s5, v253, 32
	v_fma_f32 v46, v129, |v138|, v46
	v_add_u32_e32 v138, v131, v166
	v_cndmask_b32_e32 v46, v241, v46, vcc
	v_cmp_lt_i32_e32 vcc, -1, v138
	s_and_b64 s[74:75], s[4:5], vcc
	v_cmp_gt_i32_e32 vcc, s1, v138
	v_cvt_f32_i32_e32 v138, v166
	s_and_b64 vcc, s[74:75], vcc
	v_fma_f32 v47, v129, |v138|, v47
	v_max3_f32 v138, v32, v33, v34
	v_cndmask_b32_e32 v47, v241, v47, vcc
	v_max3_f32 v138, v138, v35, v36
	v_max3_f32 v138, v138, v37, v38
	v_max3_f32 v138, v138, v39, v40
	v_max3_f32 v138, v138, v41, v42
	v_max3_f32 v138, v138, v43, v44
	v_max3_f32 v138, v138, v45, v46
	v_max_f32_e32 v138, v138, v138
	v_max_f32_e32 v246, v138, v47
	v_cmp_gt_f32_e32 vcc, v246, v244
	s_cbranch_vccz .LBB0_508
; DI unsigned pk2(float a, float b) { f32x2 v = {a, b}; bf2_t r = __builtin_convertvector(v, bf2_t); return __builtin_bit_cast(unsigned, r); }
; DI f32x16 mfma32(bf16x8 a, bf16x8 b, f32x16 c) { return __builtin_amdgcn_mfma_f32_32x32x16_bf16(a, b, c, 0, 0, 0); }
; DI void attn_d6_loop(char* lds, const Params& p, int layer, int first, int stride, int total) {
;     ...
;       if (__any(mx > m + 8.f)) {
;         mx = fmaxf(mx, __shfl_xor(mx, 32));
;         const float mnew = fmaxf(m, mx);
;         const float al = __builtin_amdgcn_exp2f(m - mnew); l *= al; O0 *= al; O1 *= al;
;         m = mnew;
;       }
;       float ps = 0.f;
; #pragma unroll
;       for (int r2 = 0; r2 < 16; ++r2) { S[r2] = __builtin_amdgcn_exp2f(S[r2] - m); ps += S[r2]; }
;       l += ps;
;       bf16x8 pf[2];
; #pragma unroll
;       for (int s2 = 0; s2 < 2; ++s2) { u32x4 w; w[0] = pk2(S[8 * s2], S[8 * s2 + 1]); w[1] = pk2(S[8 * s2 + 2], S[8 * s2 + 3]); w[2] = pk2(S[8 * s2 + 4], S[8 * s2 + 5]); w[3] = pk2(S[8 * s2 + 6], S[8 * s2 + 7]);
;         pf[s2] = __builtin_bit_cast(bf16x8, w); }
;       { const int g = lane >> 4, i16 = lane & 15;
;         const unsigned vbase = (unsigned)(size_t)(lds + VOFF) + (unsigned)((64 * c + 32 * hf + 4 * (g >> 1) + (i16 >> 2)) * KST + ((g & 1) * 16 + 4 * (i16 & 3)) * 2);
; #pragma unroll
;         for (int s2 = 0; s2 < 2; ++s2) {
;           s16x4 l0, h0, l1, h1;
;           const unsigned a0 = vbase + (unsigned)(16 * s2 * KST), a1 = a0 + 8u * KST, a2 = a0 + 64u, a3 = a1 + 64u;
;           asm volatile("ds_read_b64_tr_b16 %0, %4\n\tds_read_b64_tr_b16 %1, %5\n\tds_read_b64_tr_b16 %2, %6\n\tds_read_b64_tr_b16 %3, %7\n\ts_waitcnt lgkmcnt(0)"
;                        : "=&v"(l0), "=&v"(h0), "=&v"(l1), "=&v"(h1) : "v"(a0), "v"(a1), "v"(a2), "v"(a3) : "memory");
;           O0 = mfma32(__builtin_shufflevector(l0, h0, 0, 1, 2, 3, 4, 5, 6, 7), pf[s2], O0);
;           O1 = mfma32(__builtin_shufflevector(l1, h1, 0, 1, 2, 3, 4, 5, 6, 7), pf[s2], O1);
;         } }
	v_and_b32_e32 v139, 64, v226
	v_xor_b32_e32 v138, 32, v226
	v_add_u32_e32 v139, 64, v139
	v_cmp_lt_i32_e32 vcc, v138, v139
	s_nop 1
	v_cndmask_b32_e32 v138, v226, v138, vcc
	v_lshlrev_b32_e32 v138, 2, v138
	ds_bpermute_b32 v138, v138, v246
	s_waitcnt lgkmcnt(0)
	v_max3_f32 v139, v243, v246, v138
	v_sub_f32_e32 v138, v243, v139
	v_exp_f32_e32 v138, v138
	v_add_f32_e32 v244, 0x41000000, v139
	v_mov_b32_e32 v243, v139
	v_mul_f32_e32 v245, v245, v138
	v_pk_mul_f32 v[14:15], v[14:15], v[138:139] op_sel_hi:[1,0]
	v_pk_mul_f32 v[12:13], v[12:13], v[138:139] op_sel_hi:[1,0]
	v_pk_mul_f32 v[10:11], v[10:11], v[138:139] op_sel_hi:[1,0]
	v_pk_mul_f32 v[8:9], v[8:9], v[138:139] op_sel_hi:[1,0]
	v_pk_mul_f32 v[6:7], v[6:7], v[138:139] op_sel_hi:[1,0]
	v_pk_mul_f32 v[4:5], v[4:5], v[138:139] op_sel_hi:[1,0]
	v_pk_mul_f32 v[2:3], v[2:3], v[138:139] op_sel_hi:[1,0]
	v_pk_mul_f32 v[0:1], v[0:1], v[138:139] op_sel_hi:[1,0]
	v_pk_mul_f32 v[30:31], v[30:31], v[138:139] op_sel_hi:[1,0]
	v_pk_mul_f32 v[28:29], v[28:29], v[138:139] op_sel_hi:[1,0]
	v_pk_mul_f32 v[26:27], v[26:27], v[138:139] op_sel_hi:[1,0]
	v_pk_mul_f32 v[24:25], v[24:25], v[138:139] op_sel_hi:[1,0]
	v_pk_mul_f32 v[22:23], v[22:23], v[138:139] op_sel_hi:[1,0]
	v_pk_mul_f32 v[20:21], v[20:21], v[138:139] op_sel_hi:[1,0]
	v_pk_mul_f32 v[18:19], v[18:19], v[138:139] op_sel_hi:[1,0]
	v_pk_mul_f32 v[16:17], v[16:17], v[138:139] op_sel_hi:[1,0]
.LBB0_508:
	v_sub_f32_e32 v32, v32, v243
	v_exp_f32_e32 v138, v32
	v_sub_f32_e32 v32, v33, v243
	v_exp_f32_e32 v139, v32
	v_sub_f32_e32 v32, v34, v243
	v_exp_f32_e32 v140, v32
	v_sub_f32_e32 v32, v35, v243
	v_exp_f32_e32 v141, v32
	v_sub_f32_e32 v32, v36, v243
	v_exp_f32_e32 v142, v32
	v_sub_f32_e32 v32, v37, v243
	v_exp_f32_e32 v143, v32
	v_sub_f32_e32 v32, v38, v243
	v_exp_f32_e32 v144, v32
	v_sub_f32_e32 v32, v39, v243
	v_exp_f32_e32 v145, v32
	v_sub_f32_e32 v32, v40, v243
	v_exp_f32_e32 v40, v32
	v_sub_f32_e32 v32, v41, v243
	v_exp_f32_e32 v41, v32
	v_sub_f32_e32 v32, v42, v243
	v_exp_f32_e32 v42, v32
	v_sub_f32_e32 v32, v43, v243
	v_exp_f32_e32 v43, v32
	v_sub_f32_e32 v32, v44, v243
	v_exp_f32_e32 v44, v32
	v_sub_f32_e32 v32, v45, v243
	v_exp_f32_e32 v45, v32
	v_sub_f32_e32 v32, v46, v243
	v_exp_f32_e32 v46, v32
	v_sub_f32_e32 v32, v47, v243
	v_exp_f32_e32 v47, v32
	v_cvt_pk_bf16_f32 v32, v138, v139
	v_add_f32_e32 v138, 0, v138
	v_add_f32_e32 v138, v139, v138
	v_add_f32_e32 v138, v140, v138
	v_add_f32_e32 v138, v141, v138
	v_add_f32_e32 v138, v142, v138
	v_add_f32_e32 v138, v143, v138
	v_add_f32_e32 v138, v144, v138
	v_add_f32_e32 v138, v145, v138
	v_cvt_pk_bf16_f32 v36, v40, v41
	v_add_f32_e32 v40, v40, v138
	v_add_f32_e32 v40, v41, v40
	v_add_f32_e32 v40, v42, v40
	v_add_f32_e32 v40, v43, v40
	v_add_f32_e32 v40, v44, v40
	v_add_f32_e32 v40, v45, v40
	v_cvt_pk_bf16_f32 v33, v140, v141
	v_cvt_pk_bf16_f32 v34, v142, v143
	v_cvt_pk_bf16_f32 v35, v144, v145
	v_add_f32_e32 v40, v46, v40
	v_cvt_pk_bf16_f32 v37, v42, v43
	v_cvt_pk_bf16_f32 v38, v44, v45
	v_cvt_pk_bf16_f32 v39, v46, v47
	v_add_f32_e32 v138, v47, v40
	v_add_u32_e32 v139, 0x480, v118
	v_add_u32_e32 v140, 64, v118
	v_add_u32_e32 v141, 0x4c0, v118
	ds_read_b64_tr_b16 v[44:45], v118
	ds_read_b64_tr_b16 v[46:47], v139
	ds_read_b64_tr_b16 v[40:41], v140
	ds_read_b64_tr_b16 v[42:43], v141
	s_waitcnt lgkmcnt(0)
	v_add_f32_e32 v245, v245, v138
	v_mfma_f32_32x32x16_bf16 v[16:31], v[40:43], v[32:35], v[16:31]
	v_readlane_b32 s4, v253, 33
	v_readlane_b32 s5, v253, 34
	v_mfma_f32_32x32x16_bf16 v[0:15], v[44:47], v[32:35], v[0:15]
	v_add_u32_e32 v44, 0x900, v118
	v_add_u32_e32 v45, 0xd80, v118
	v_add_u32_e32 v46, 0x940, v118
	v_add_u32_e32 v47, 0xdc0, v118
	ds_read_b64_tr_b16 v[40:41], v44
	ds_read_b64_tr_b16 v[42:43], v45
	ds_read_b64_tr_b16 v[32:33], v46
	ds_read_b64_tr_b16 v[34:35], v47
	s_waitcnt lgkmcnt(0)
	s_nop 0
	v_mfma_f32_32x32x16_bf16 v[16:31], v[32:35], v[36:39], v[16:31]
	ds_read_b128 v[32:35], v202
	ds_read_b128 v[138:141], v202 offset:32
	v_mfma_f32_32x32x16_bf16 v[0:15], v[40:43], v[36:39], v[0:15]
	s_waitcnt lgkmcnt(1)
	v_mfma_f32_32x32x16_bf16 v[32:47], v[32:35], v[104:107], 0
	s_waitcnt lgkmcnt(0)
	v_mfma_f32_32x32x16_bf16 v[32:47], v[138:141], v[108:111], v[32:47]
	ds_read_b128 v[138:141], v202 offset:64
	s_waitcnt lgkmcnt(0)
	v_mfma_f32_32x32x16_bf16 v[32:47], v[138:141], v[100:103], v[32:47]
	ds_read_b128 v[138:141], v202 offset:96
	s_waitcnt lgkmcnt(0)
; DI f32x16 mfma32(bf16x8 a, bf16x8 b, f32x16 c) { return __builtin_amdgcn_mfma_f32_32x32x16_bf16(a, b, c, 0, 0, 0); }
; DI float max3f(float a, float b, float c) { float d; asm("v_max3_f32 %0, %1, %2, %3" : "=v"(d) : "v"(a), "v"(b), "v"(c)); return d; }
; DI void attn_d6_loop(char* lds, const Params& p, int layer, int first, int stride, int total) {
;     ...
;       for (int ks = 0; ks < 4; ++ks) S = mfma32(*(const bf16x8*)(kb + ks * 32), qf[ks], S);
;       const int rel0 = key0 + 4 * lh - qrow;
; #pragma unroll
;       for (int r2 = 0; r2 < 16; ++r2) { const int rel = rel0 + (r2 & 3) + 8 * (r2 >> 2), v = qrow + rel;
;         const bool ok = (rel >= -64) && (rel <= 64) && (v >= 0) && (v < L); S[r2] = ok ? fmaf(-slope2, fabsf((float)rel), S[r2]) : -1e30f; }
;       float mx = S[0];
; #pragma unroll
;       for (int r2 = 1; r2 < 15; r2 += 2) mx = max3f(mx, S[r2], S[r2 + 1]);
;       mx = fmaxf(mx, S[15]);
;       if (__any(mx > m + 8.f)) {
;         mx = fmaxf(mx, __shfl_xor(mx, 32));
;         const float mnew = fmaxf(m, mx);
;         const float al = __builtin_amdgcn_exp2f(m - mnew); l *= al; O0 *= al; O1 *= al;
;         m = mnew;
;       }
	v_mfma_f32_32x32x16_bf16 v[32:47], v[138:141], v[96:99], v[32:47]
	v_add_u32_e32 v138, v131, v119
	v_cmp_lt_i32_e32 vcc, -1, v138
	s_and_b64 s[74:75], s[4:5], vcc
	v_cmp_gt_i32_e32 vcc, s1, v138
	v_cvt_f32_i32_e32 v138, v119
	s_and_b64 vcc, s[74:75], vcc
	v_readlane_b32 s4, v253, 35
	v_readlane_b32 s5, v253, 36
	s_nop 3
	v_fma_f32 v32, v129, |v138|, v32
	v_add_u32_e32 v138, v131, v167
	v_cndmask_b32_e32 v32, v241, v32, vcc
	v_cmp_lt_i32_e32 vcc, -1, v138
	s_and_b64 s[74:75], s[4:5], vcc
	v_cmp_gt_i32_e32 vcc, s1, v138
	v_cvt_f32_i32_e32 v138, v167
	s_and_b64 vcc, s[74:75], vcc
	v_readlane_b32 s4, v253, 37
	v_readlane_b32 s5, v253, 38
	v_fma_f32 v33, v129, |v138|, v33
	v_add_u32_e32 v138, v131, v168
	v_cndmask_b32_e32 v33, v241, v33, vcc
	v_cmp_lt_i32_e32 vcc, -1, v138
	s_and_b64 s[74:75], s[4:5], vcc
	v_cmp_gt_i32_e32 vcc, s1, v138
	v_cvt_f32_i32_e32 v138, v168
	s_and_b64 vcc, s[74:75], vcc
	v_readlane_b32 s4, v253, 39
	v_readlane_b32 s5, v253, 40
	v_fma_f32 v34, v129, |v138|, v34
	v_add_u32_e32 v138, v131, v121
	v_cndmask_b32_e32 v34, v241, v34, vcc
	v_cmp_lt_i32_e32 vcc, -1, v138
	s_and_b64 s[74:75], s[4:5], vcc
	v_cmp_gt_i32_e32 vcc, s1, v138
	v_cvt_f32_i32_e32 v138, v121
	s_and_b64 vcc, s[74:75], vcc
	v_readlane_b32 s4, v253, 41
	v_readlane_b32 s5, v253, 42
	v_fma_f32 v35, v129, |v138|, v35
	v_add_u32_e32 v138, v131, v123
	v_cndmask_b32_e32 v35, v241, v35, vcc
	v_cmp_lt_i32_e32 vcc, -1, v138
	s_and_b64 s[74:75], s[4:5], vcc
	v_cmp_gt_i32_e32 vcc, s1, v138
	v_cvt_f32_i32_e32 v138, v123
	s_and_b64 vcc, s[74:75], vcc
	v_readlane_b32 s4, v253, 43
	v_readlane_b32 s5, v253, 44
	v_fma_f32 v36, v129, |v138|, v36
	v_add_u32_e32 v138, v131, v125
	v_cndmask_b32_e32 v36, v241, v36, vcc
	v_cmp_lt_i32_e32 vcc, -1, v138
	s_and_b64 s[74:75], s[4:5], vcc
	v_cmp_gt_i32_e32 vcc, s1, v138
	v_cvt_f32_i32_e32 v138, v125
	s_and_b64 vcc, s[74:75], vcc
	v_readlane_b32 s4, v253, 45
	v_readlane_b32 s5, v253, 46
	v_fma_f32 v37, v129, |v138|, v37
	v_add_u32_e32 v138, v131, v127
	v_cndmask_b32_e32 v37, v241, v37, vcc
	v_cmp_lt_i32_e32 vcc, -1, v138
	s_and_b64 s[74:75], s[4:5], vcc
	v_cmp_gt_i32_e32 vcc, s1, v138
	v_cvt_f32_i32_e32 v138, v127
	s_and_b64 vcc, s[74:75], vcc
	v_readlane_b32 s4, v253, 47
	v_readlane_b32 s5, v253, 48
	v_fma_f32 v38, v129, |v138|, v38
	v_add_u32_e32 v138, v131, v169
	v_cndmask_b32_e32 v38, v241, v38, vcc
	v_cmp_lt_i32_e32 vcc, -1, v138
	s_and_b64 s[74:75], s[4:5], vcc
	v_cmp_gt_i32_e32 vcc, s1, v138
	v_cvt_f32_i32_e32 v138, v169
	s_and_b64 vcc, s[74:75], vcc
	v_readlane_b32 s4, v253, 49
	v_readlane_b32 s5, v253, 50
	v_fma_f32 v39, v129, |v138|, v39
	v_add_u32_e32 v138, v131, v170
	v_cndmask_b32_e32 v39, v241, v39, vcc
	v_cmp_lt_i32_e32 vcc, -1, v138
	s_and_b64 s[74:75], s[4:5], vcc
	v_cmp_gt_i32_e32 vcc, s1, v138
	v_cvt_f32_i32_e32 v138, v170
	s_and_b64 vcc, s[74:75], vcc
	v_readlane_b32 s4, v253, 51
	v_readlane_b32 s5, v253, 52
	v_fma_f32 v40, v129, |v138|, v40
	v_add_u32_e32 v138, v131, v171
	v_cndmask_b32_e32 v40, v241, v40, vcc
	v_cmp_lt_i32_e32 vcc, -1, v138
	s_and_b64 s[74:75], s[4:5], vcc
	v_cmp_gt_i32_e32 vcc, s1, v138
	v_cvt_f32_i32_e32 v138, v171
	s_and_b64 vcc, s[74:75], vcc
	v_readlane_b32 s4, v253, 53
	v_readlane_b32 s5, v253, 54
	v_fma_f32 v41, v129, |v138|, v41
	v_add_u32_e32 v138, v131, v172
	v_cndmask_b32_e32 v41, v241, v41, vcc
	v_cmp_lt_i32_e32 vcc, -1, v138
	s_and_b64 s[74:75], s[4:5], vcc
	v_cmp_gt_i32_e32 vcc, s1, v138
	v_cvt_f32_i32_e32 v138, v172
	s_and_b64 vcc, s[74:75], vcc
	v_readlane_b32 s4, v253, 55
	v_readlane_b32 s5, v253, 56
	v_fma_f32 v42, v129, |v138|, v42
	v_add_u32_e32 v138, v131, v173
	v_cndmask_b32_e32 v42, v241, v42, vcc
	v_cmp_lt_i32_e32 vcc, -1, v138
	s_and_b64 s[74:75], s[4:5], vcc
	v_cmp_gt_i32_e32 vcc, s1, v138
	v_cvt_f32_i32_e32 v138, v173
	s_and_b64 vcc, s[74:75], vcc
	v_readlane_b32 s4, v253, 57
	v_readlane_b32 s5, v253, 58
	v_fma_f32 v43, v129, |v138|, v43
	v_add_u32_e32 v138, v131, v174
	v_cndmask_b32_e32 v43, v241, v43, vcc
	v_cmp_lt_i32_e32 vcc, -1, v138
	s_and_b64 s[74:75], s[4:5], vcc
	v_cmp_gt_i32_e32 vcc, s1, v138
	v_cvt_f32_i32_e32 v138, v174
	s_and_b64 vcc, s[74:75], vcc
	v_readlane_b32 s4, v253, 59
	v_readlane_b32 s5, v253, 60
	v_fma_f32 v44, v129, |v138|, v44
	v_add_u32_e32 v138, v131, v175
	v_cndmask_b32_e32 v44, v241, v44, vcc
	v_cmp_lt_i32_e32 vcc, -1, v138
	s_and_b64 s[74:75], s[4:5], vcc
	v_cmp_gt_i32_e32 vcc, s1, v138
	v_cvt_f32_i32_e32 v138, v175
	s_and_b64 vcc, s[74:75], vcc
	v_readlane_b32 s4, v253, 61
	v_readlane_b32 s5, v253, 62
	v_fma_f32 v45, v129, |v138|, v45
	v_add_u32_e32 v138, v131, v176
	v_cndmask_b32_e32 v45, v241, v45, vcc
	v_cmp_lt_i32_e32 vcc, -1, v138
	s_and_b64 s[74:75], s[4:5], vcc
	v_cmp_gt_i32_e32 vcc, s1, v138
	v_cvt_f32_i32_e32 v138, v176
	s_and_b64 vcc, s[74:75], vcc
	v_readlane_b32 s4, v253, 63
	v_readlane_b32 s5, v254, 0
	v_fma_f32 v46, v129, |v138|, v46
	v_add_u32_e32 v138, v131, v177
	v_cndmask_b32_e32 v46, v241, v46, vcc
	v_cmp_lt_i32_e32 vcc, -1, v138
	s_and_b64 s[74:75], s[4:5], vcc
	v_cmp_gt_i32_e32 vcc, s1, v138
	v_cvt_f32_i32_e32 v138, v177
	s_and_b64 vcc, s[74:75], vcc
	v_fma_f32 v47, v129, |v138|, v47
	v_max3_f32 v138, v32, v33, v34
	v_cndmask_b32_e32 v47, v241, v47, vcc
	v_max3_f32 v138, v138, v35, v36
	v_max3_f32 v138, v138, v37, v38
	v_max3_f32 v138, v138, v39, v40
	v_max3_f32 v138, v138, v41, v42
	v_max3_f32 v138, v138, v43, v44
	v_max3_f32 v138, v138, v45, v46
	v_max_f32_e32 v138, v138, v138
	v_max_f32_e32 v246, v138, v47
	v_cmp_gt_f32_e32 vcc, v246, v244
	s_cbranch_vccz .LBB0_510
	v_and_b32_e32 v139, 64, v226
	v_xor_b32_e32 v138, 32, v226
	v_add_u32_e32 v139, 64, v139
	v_cmp_lt_i32_e32 vcc, v138, v139
	s_nop 1
	v_cndmask_b32_e32 v138, v226, v138, vcc
	v_lshlrev_b32_e32 v138, 2, v138
	ds_bpermute_b32 v138, v138, v246
	s_waitcnt lgkmcnt(0)
	v_max3_f32 v139, v243, v246, v138
	v_sub_f32_e32 v138, v243, v139
	v_exp_f32_e32 v138, v138
	v_add_f32_e32 v244, 0x41000000, v139
	v_mov_b32_e32 v243, v139
	v_mul_f32_e32 v245, v245, v138
	v_pk_mul_f32 v[14:15], v[14:15], v[138:139] op_sel_hi:[1,0]
	v_pk_mul_f32 v[12:13], v[12:13], v[138:139] op_sel_hi:[1,0]
	v_pk_mul_f32 v[10:11], v[10:11], v[138:139] op_sel_hi:[1,0]
	v_pk_mul_f32 v[8:9], v[8:9], v[138:139] op_sel_hi:[1,0]
	v_pk_mul_f32 v[6:7], v[6:7], v[138:139] op_sel_hi:[1,0]
	v_pk_mul_f32 v[4:5], v[4:5], v[138:139] op_sel_hi:[1,0]
	v_pk_mul_f32 v[2:3], v[2:3], v[138:139] op_sel_hi:[1,0]
	v_pk_mul_f32 v[0:1], v[0:1], v[138:139] op_sel_hi:[1,0]
	v_pk_mul_f32 v[30:31], v[30:31], v[138:139] op_sel_hi:[1,0]
	v_pk_mul_f32 v[28:29], v[28:29], v[138:139] op_sel_hi:[1,0]
	v_pk_mul_f32 v[26:27], v[26:27], v[138:139] op_sel_hi:[1,0]
	v_pk_mul_f32 v[24:25], v[24:25], v[138:139] op_sel_hi:[1,0]
	v_pk_mul_f32 v[22:23], v[22:23], v[138:139] op_sel_hi:[1,0]
	v_pk_mul_f32 v[20:21], v[20:21], v[138:139] op_sel_hi:[1,0]
	v_pk_mul_f32 v[18:19], v[18:19], v[138:139] op_sel_hi:[1,0]
	v_pk_mul_f32 v[16:17], v[16:17], v[138:139] op_sel_hi:[1,0]
; DI unsigned pk2(float a, float b) { f32x2 v = {a, b}; bf2_t r = __builtin_convertvector(v, bf2_t); return __builtin_bit_cast(unsigned, r); }
; DI f32x16 mfma32(bf16x8 a, bf16x8 b, f32x16 c) { return __builtin_amdgcn_mfma_f32_32x32x16_bf16(a, b, c, 0, 0, 0); }
; DI void attn_d6_loop(char* lds, const Params& p, int layer, int first, int stride, int total) {
;     ...
;       const char* kb = lds + (64 * c + 32 * hf + lr) * KST + lh * 16;
; #pragma unroll
;       for (int ks = 0; ks < 4; ++ks) S = mfma32(*(const bf16x8*)(kb + ks * 32), qf[ks], S);
;       const int rel0 = key0 + 4 * lh - qrow;
; #pragma unroll
;       for (int r2 = 0; r2 < 16; ++r2) { const int rel = rel0 + (r2 & 3) + 8 * (r2 >> 2), v = qrow + rel;
;         const bool ok = (rel >= -64) && (rel <= 64) && (v >= 0) && (v < L); S[r2] = ok ? fmaf(-slope2, fabsf((float)rel), S[r2]) : -1e30f; }
;     ...
;       float ps = 0.f;
; #pragma unroll
;       for (int r2 = 0; r2 < 16; ++r2) { S[r2] = __builtin_amdgcn_exp2f(S[r2] - m); ps += S[r2]; }
;       l += ps;
;       bf16x8 pf[2];
; #pragma unroll
;       for (int s2 = 0; s2 < 2; ++s2) { u32x4 w; w[0] = pk2(S[8 * s2], S[8 * s2 + 1]); w[1] = pk2(S[8 * s2 + 2], S[8 * s2 + 3]); w[2] = pk2(S[8 * s2 + 4], S[8 * s2 + 5]); w[3] = pk2(S[8 * s2 + 6], S[8 * s2 + 7]);
;         pf[s2] = __builtin_bit_cast(bf16x8, w); }
;       { const int g = lane >> 4, i16 = lane & 15;
;         const unsigned vbase = (unsigned)(size_t)(lds + VOFF) + (unsigned)((64 * c + 32 * hf + 4 * (g >> 1) + (i16 >> 2)) * KST + ((g & 1) * 16 + 4 * (i16 & 3)) * 2);
; #pragma unroll
;         for (int s2 = 0; s2 < 2; ++s2) {
;           s16x4 l0, h0, l1, h1;
;           const unsigned a0 = vbase + (unsigned)(16 * s2 * KST), a1 = a0 + 8u * KST, a2 = a0 + 64u, a3 = a1 + 64u;
;           asm volatile("ds_read_b64_tr_b16 %0, %4\n\tds_read_b64_tr_b16 %1, %5\n\tds_read_b64_tr_b16 %2, %6\n\tds_read_b64_tr_b16 %3, %7\n\ts_waitcnt lgkmcnt(0)"
;                        : "=&v"(l0), "=&v"(h0), "=&v"(l1), "=&v"(h1) : "v"(a0), "v"(a1), "v"(a2), "v"(a3) : "memory");
;           O0 = mfma32(__builtin_shufflevector(l0, h0, 0, 1, 2, 3, 4, 5, 6, 7), pf[s2], O0);
;           O1 = mfma32(__builtin_shufflevector(l1, h1, 0, 1, 2, 3, 4, 5, 6, 7), pf[s2], O1);
;         } }
.LBB0_510:
	v_sub_f32_e32 v32, v32, v243
	v_exp_f32_e32 v138, v32
	v_sub_f32_e32 v32, v33, v243
	v_exp_f32_e32 v139, v32
	v_sub_f32_e32 v32, v34, v243
	v_exp_f32_e32 v140, v32
	v_sub_f32_e32 v32, v35, v243
	v_exp_f32_e32 v141, v32
	v_sub_f32_e32 v32, v36, v243
	v_exp_f32_e32 v142, v32
	v_sub_f32_e32 v32, v37, v243
	v_exp_f32_e32 v143, v32
	v_sub_f32_e32 v32, v38, v243
	v_exp_f32_e32 v144, v32
	v_sub_f32_e32 v32, v39, v243
	v_exp_f32_e32 v145, v32
	v_sub_f32_e32 v32, v40, v243
	v_exp_f32_e32 v40, v32
	v_sub_f32_e32 v32, v41, v243
	v_exp_f32_e32 v41, v32
	v_sub_f32_e32 v32, v42, v243
	v_exp_f32_e32 v42, v32
	v_sub_f32_e32 v32, v43, v243
	v_exp_f32_e32 v43, v32
	v_sub_f32_e32 v32, v44, v243
	v_exp_f32_e32 v44, v32
	v_sub_f32_e32 v32, v45, v243
	v_exp_f32_e32 v45, v32
	v_sub_f32_e32 v32, v46, v243
	v_exp_f32_e32 v46, v32
	v_sub_f32_e32 v32, v47, v243
	v_exp_f32_e32 v47, v32
	v_cvt_pk_bf16_f32 v32, v138, v139
	v_add_f32_e32 v138, 0, v138
	v_add_f32_e32 v138, v139, v138
	v_add_f32_e32 v138, v140, v138
	v_add_f32_e32 v138, v141, v138
	v_add_f32_e32 v138, v142, v138
	v_add_f32_e32 v138, v143, v138
	v_add_f32_e32 v138, v144, v138
	v_add_f32_e32 v138, v145, v138
	v_cvt_pk_bf16_f32 v36, v40, v41
	v_add_f32_e32 v40, v40, v138
	v_add_f32_e32 v40, v41, v40
	v_add_f32_e32 v40, v42, v40
	v_add_f32_e32 v40, v43, v40
	v_add_f32_e32 v40, v44, v40
	v_add_f32_e32 v40, v45, v40
	v_cvt_pk_bf16_f32 v33, v140, v141
	v_cvt_pk_bf16_f32 v34, v142, v143
	v_cvt_pk_bf16_f32 v35, v144, v145
	v_add_f32_e32 v40, v46, v40
	v_cvt_pk_bf16_f32 v37, v42, v43
	v_cvt_pk_bf16_f32 v38, v44, v45
	v_cvt_pk_bf16_f32 v39, v46, v47
	v_add_f32_e32 v138, v47, v40
	v_add_u32_e32 v139, 0x480, v120
	v_add_u32_e32 v140, 64, v120
	v_add_u32_e32 v141, 0x4c0, v120
	ds_read_b64_tr_b16 v[44:45], v120
	ds_read_b64_tr_b16 v[46:47], v139
	ds_read_b64_tr_b16 v[40:41], v140
	ds_read_b64_tr_b16 v[42:43], v141
	s_waitcnt lgkmcnt(0)
	v_add_f32_e32 v245, v245, v138
	v_mfma_f32_32x32x16_bf16 v[16:31], v[40:43], v[32:35], v[16:31]
	v_readlane_b32 s4, v254, 1
	v_readlane_b32 s5, v254, 2
	v_mfma_f32_32x32x16_bf16 v[0:15], v[44:47], v[32:35], v[0:15]
	v_add_u32_e32 v44, 0x900, v120
	v_add_u32_e32 v45, 0xd80, v120
	v_add_u32_e32 v46, 0x940, v120
	v_add_u32_e32 v47, 0xdc0, v120
	ds_read_b64_tr_b16 v[40:41], v44
	ds_read_b64_tr_b16 v[42:43], v45
	ds_read_b64_tr_b16 v[32:33], v46
	ds_read_b64_tr_b16 v[34:35], v47
	s_waitcnt lgkmcnt(0)
	s_nop 0
	v_mfma_f32_32x32x16_bf16 v[16:31], v[32:35], v[36:39], v[16:31]
	ds_read_b128 v[32:35], v203
	ds_read_b128 v[138:141], v203 offset:32
	v_mfma_f32_32x32x16_bf16 v[0:15], v[40:43], v[36:39], v[0:15]
	s_waitcnt lgkmcnt(1)
	v_mfma_f32_32x32x16_bf16 v[32:47], v[32:35], v[104:107], 0
	s_waitcnt lgkmcnt(0)
	v_mfma_f32_32x32x16_bf16 v[32:47], v[138:141], v[108:111], v[32:47]
	ds_read_b128 v[138:141], v203 offset:64
	s_waitcnt lgkmcnt(0)
	v_mfma_f32_32x32x16_bf16 v[32:47], v[138:141], v[100:103], v[32:47]
	ds_read_b128 v[138:141], v203 offset:96
	s_waitcnt lgkmcnt(0)
	v_mfma_f32_32x32x16_bf16 v[32:47], v[138:141], v[96:99], v[32:47]
	v_add_u32_e32 v138, v131, v178
	v_cmp_lt_i32_e32 vcc, -1, v138
	s_and_b64 s[74:75], s[4:5], vcc
	v_cmp_gt_i32_e32 vcc, s1, v138
	v_cvt_f32_i32_e32 v138, v178
	s_and_b64 vcc, s[74:75], vcc
	v_readlane_b32 s4, v254, 3
	v_readlane_b32 s5, v254, 4
	s_nop 3
	v_fma_f32 v32, v129, |v138|, v32
	v_add_u32_e32 v138, v131, v179
	v_cndmask_b32_e32 v32, v241, v32, vcc
	v_cmp_lt_i32_e32 vcc, -1, v138
	s_and_b64 s[74:75], s[4:5], vcc
	v_cmp_gt_i32_e32 vcc, s1, v138
	v_cvt_f32_i32_e32 v138, v179
	s_and_b64 vcc, s[74:75], vcc
	v_readlane_b32 s4, v254, 5
	v_readlane_b32 s5, v254, 6
	v_fma_f32 v33, v129, |v138|, v33
	v_add_u32_e32 v138, v131, v180
	v_cndmask_b32_e32 v33, v241, v33, vcc
	v_cmp_lt_i32_e32 vcc, -1, v138
	s_and_b64 s[74:75], s[4:5], vcc
	v_cmp_gt_i32_e32 vcc, s1, v138
	v_cvt_f32_i32_e32 v138, v180
	s_and_b64 vcc, s[74:75], vcc
	v_readlane_b32 s4, v254, 7
	v_readlane_b32 s5, v254, 8
	v_fma_f32 v34, v129, |v138|, v34
	v_add_u32_e32 v138, v131, v181
	v_cndmask_b32_e32 v34, v241, v34, vcc
	v_cmp_lt_i32_e32 vcc, -1, v138
	s_and_b64 s[74:75], s[4:5], vcc
	v_cmp_gt_i32_e32 vcc, s1, v138
	v_cvt_f32_i32_e32 v138, v181
	s_and_b64 vcc, s[74:75], vcc
	v_readlane_b32 s4, v254, 9
	v_readlane_b32 s5, v254, 10
	v_fma_f32 v35, v129, |v138|, v35
	v_add_u32_e32 v138, v131, v182
	v_cndmask_b32_e32 v35, v241, v35, vcc
	v_cmp_lt_i32_e32 vcc, -1, v138
	s_and_b64 s[74:75], s[4:5], vcc
	v_cmp_gt_i32_e32 vcc, s1, v138
	v_cvt_f32_i32_e32 v138, v182
	s_and_b64 vcc, s[74:75], vcc
	v_readlane_b32 s4, v254, 11
	v_readlane_b32 s5, v254, 12
	v_fma_f32 v36, v129, |v138|, v36
	v_add_u32_e32 v138, v131, v183
	v_cndmask_b32_e32 v36, v241, v36, vcc
	v_cmp_lt_i32_e32 vcc, -1, v138
	s_and_b64 s[74:75], s[4:5], vcc
	v_cmp_gt_i32_e32 vcc, s1, v138
	v_cvt_f32_i32_e32 v138, v183
	s_and_b64 vcc, s[74:75], vcc
	v_readlane_b32 s4, v254, 13
	v_readlane_b32 s5, v254, 14
	v_fma_f32 v37, v129, |v138|, v37
	v_add_u32_e32 v138, v131, v184
	v_cndmask_b32_e32 v37, v241, v37, vcc
	v_cmp_lt_i32_e32 vcc, -1, v138
	s_and_b64 s[74:75], s[4:5], vcc
	v_cmp_gt_i32_e32 vcc, s1, v138
	v_cvt_f32_i32_e32 v138, v184
	s_and_b64 vcc, s[74:75], vcc
	v_readlane_b32 s4, v254, 15
	v_readlane_b32 s5, v254, 16
	v_fma_f32 v38, v129, |v138|, v38
	v_add_u32_e32 v138, v131, v185
	v_cndmask_b32_e32 v38, v241, v38, vcc
	v_cmp_lt_i32_e32 vcc, -1, v138
	s_and_b64 s[74:75], s[4:5], vcc
	v_cmp_gt_i32_e32 vcc, s1, v138
	v_cvt_f32_i32_e32 v138, v185
	s_and_b64 vcc, s[74:75], vcc
	v_readlane_b32 s4, v254, 17
	v_readlane_b32 s5, v254, 18
	v_fma_f32 v39, v129, |v138|, v39
	v_add_u32_e32 v138, v131, v186
	v_cndmask_b32_e32 v39, v241, v39, vcc
; DI float max3f(float a, float b, float c) { float d; asm("v_max3_f32 %0, %1, %2, %3" : "=v"(d) : "v"(a), "v"(b), "v"(c)); return d; }
; DI void attn_d6_loop(char* lds, const Params& p, int layer, int first, int stride, int total) {
;     ...
;       for (int r2 = 0; r2 < 16; ++r2) { const int rel = rel0 + (r2 & 3) + 8 * (r2 >> 2), v = qrow + rel;
;         const bool ok = (rel >= -64) && (rel <= 64) && (v >= 0) && (v < L); S[r2] = ok ? fmaf(-slope2, fabsf((float)rel), S[r2]) : -1e30f; }
;       float mx = S[0];
; #pragma unroll
;       for (int r2 = 1; r2 < 15; r2 += 2) mx = max3f(mx, S[r2], S[r2 + 1]);
;       mx = fmaxf(mx, S[15]);
;       if (__any(mx > m + 8.f)) {
;         mx = fmaxf(mx, __shfl_xor(mx, 32));
;         const float mnew = fmaxf(m, mx);
;         const float al = __builtin_amdgcn_exp2f(m - mnew); l *= al; O0 *= al; O1 *= al;
;         m = mnew;
;       }
;       float ps = 0.f;
; #pragma unroll
;       for (int r2 = 0; r2 < 16; ++r2) { S[r2] = __builtin_amdgcn_exp2f(S[r2] - m); ps += S[r2]; }
	v_cmp_lt_i32_e32 vcc, -1, v138
	s_and_b64 s[74:75], s[4:5], vcc
	v_cmp_gt_i32_e32 vcc, s1, v138
	v_cvt_f32_i32_e32 v138, v186
	s_and_b64 vcc, s[74:75], vcc
	v_readlane_b32 s4, v254, 19
	v_readlane_b32 s5, v254, 20
	v_fma_f32 v40, v129, |v138|, v40
	v_add_u32_e32 v138, v131, v187
	v_cndmask_b32_e32 v40, v241, v40, vcc
	v_cmp_lt_i32_e32 vcc, -1, v138
	s_and_b64 s[74:75], s[4:5], vcc
	v_cmp_gt_i32_e32 vcc, s1, v138
	v_cvt_f32_i32_e32 v138, v187
	s_and_b64 vcc, s[74:75], vcc
	v_readlane_b32 s4, v254, 21
	v_readlane_b32 s5, v254, 22
	v_fma_f32 v41, v129, |v138|, v41
	v_add_u32_e32 v138, v131, v188
	v_cndmask_b32_e32 v41, v241, v41, vcc
	v_cmp_lt_i32_e32 vcc, -1, v138
	s_and_b64 s[74:75], s[4:5], vcc
	v_cmp_gt_i32_e32 vcc, s1, v138
	v_cvt_f32_i32_e32 v138, v188
	s_and_b64 vcc, s[74:75], vcc
	v_readlane_b32 s4, v254, 23
	v_readlane_b32 s5, v254, 24
	v_fma_f32 v42, v129, |v138|, v42
	v_add_u32_e32 v138, v131, v189
	v_cndmask_b32_e32 v42, v241, v42, vcc
	v_cmp_lt_i32_e32 vcc, -1, v138
	s_and_b64 s[74:75], s[4:5], vcc
	v_cmp_gt_i32_e32 vcc, s1, v138
	v_cvt_f32_i32_e32 v138, v189
	s_and_b64 vcc, s[74:75], vcc
	v_readlane_b32 s4, v254, 25
	v_readlane_b32 s5, v254, 26
	v_fma_f32 v43, v129, |v138|, v43
	v_add_u32_e32 v138, v131, v190
	v_cndmask_b32_e32 v43, v241, v43, vcc
	v_cmp_lt_i32_e32 vcc, -1, v138
	s_and_b64 s[74:75], s[4:5], vcc
	v_cmp_gt_i32_e32 vcc, s1, v138
	v_cvt_f32_i32_e32 v138, v190
	s_and_b64 vcc, s[74:75], vcc
	v_readlane_b32 s4, v254, 27
	v_readlane_b32 s5, v254, 28
	v_fma_f32 v44, v129, |v138|, v44
	v_add_u32_e32 v138, v131, v191
	v_cndmask_b32_e32 v44, v241, v44, vcc
	v_cmp_lt_i32_e32 vcc, -1, v138
	s_and_b64 s[74:75], s[4:5], vcc
	v_cmp_gt_i32_e32 vcc, s1, v138
	v_cvt_f32_i32_e32 v138, v191
	s_and_b64 vcc, s[74:75], vcc
	v_readlane_b32 s4, v254, 29
	v_readlane_b32 s5, v254, 30
	v_fma_f32 v45, v129, |v138|, v45
	v_add_u32_e32 v138, v131, v192
	v_cndmask_b32_e32 v45, v241, v45, vcc
	v_cmp_lt_i32_e32 vcc, -1, v138
	s_and_b64 s[74:75], s[4:5], vcc
	v_cmp_gt_i32_e32 vcc, s1, v138
	v_cvt_f32_i32_e32 v138, v192
	s_and_b64 vcc, s[74:75], vcc
	v_fma_f32 v46, v129, |v138|, v46
	v_add_u32_e32 v138, v131, v193
	v_cndmask_b32_e32 v46, v241, v46, vcc
	v_cmp_lt_i32_e32 vcc, -1, v138
	s_and_b64 s[74:75], s[6:7], vcc
	v_cmp_gt_i32_e32 vcc, s1, v138
	v_cvt_f32_i32_e32 v138, v193
	s_and_b64 vcc, s[74:75], vcc
	v_fma_f32 v47, v129, |v138|, v47
	v_max3_f32 v138, v32, v33, v34
	v_cndmask_b32_e32 v47, v241, v47, vcc
	v_max3_f32 v138, v138, v35, v36
	v_max3_f32 v138, v138, v37, v38
	v_max3_f32 v138, v138, v39, v40
	v_max3_f32 v138, v138, v41, v42
	v_max3_f32 v138, v138, v43, v44
	v_max3_f32 v138, v138, v45, v46
	v_max_f32_e32 v138, v138, v138
	v_max_f32_e32 v246, v138, v47
	v_cmp_gt_f32_e32 vcc, v246, v244
	s_cbranch_vccz .LBB0_512
	v_and_b32_e32 v139, 64, v226
	v_xor_b32_e32 v138, 32, v226
	v_add_u32_e32 v139, 64, v139
	v_cmp_lt_i32_e32 vcc, v138, v139
	s_nop 1
	v_cndmask_b32_e32 v138, v226, v138, vcc
	v_lshlrev_b32_e32 v138, 2, v138
	ds_bpermute_b32 v138, v138, v246
	s_waitcnt lgkmcnt(0)
	v_max3_f32 v139, v243, v246, v138
	v_sub_f32_e32 v138, v243, v139
	v_exp_f32_e32 v138, v138
	v_add_f32_e32 v244, 0x41000000, v139
	v_mov_b32_e32 v243, v139
	v_mul_f32_e32 v245, v245, v138
	v_pk_mul_f32 v[14:15], v[14:15], v[138:139] op_sel_hi:[1,0]
	v_pk_mul_f32 v[12:13], v[12:13], v[138:139] op_sel_hi:[1,0]
	v_pk_mul_f32 v[10:11], v[10:11], v[138:139] op_sel_hi:[1,0]
	v_pk_mul_f32 v[8:9], v[8:9], v[138:139] op_sel_hi:[1,0]
	v_pk_mul_f32 v[6:7], v[6:7], v[138:139] op_sel_hi:[1,0]
	v_pk_mul_f32 v[4:5], v[4:5], v[138:139] op_sel_hi:[1,0]
	v_pk_mul_f32 v[2:3], v[2:3], v[138:139] op_sel_hi:[1,0]
	v_pk_mul_f32 v[0:1], v[0:1], v[138:139] op_sel_hi:[1,0]
	v_pk_mul_f32 v[30:31], v[30:31], v[138:139] op_sel_hi:[1,0]
	v_pk_mul_f32 v[28:29], v[28:29], v[138:139] op_sel_hi:[1,0]
	v_pk_mul_f32 v[26:27], v[26:27], v[138:139] op_sel_hi:[1,0]
	v_pk_mul_f32 v[24:25], v[24:25], v[138:139] op_sel_hi:[1,0]
	v_pk_mul_f32 v[22:23], v[22:23], v[138:139] op_sel_hi:[1,0]
	v_pk_mul_f32 v[20:21], v[20:21], v[138:139] op_sel_hi:[1,0]
	v_pk_mul_f32 v[18:19], v[18:19], v[138:139] op_sel_hi:[1,0]
	v_pk_mul_f32 v[16:17], v[16:17], v[138:139] op_sel_hi:[1,0]
.LBB0_512:
	v_sub_f32_e32 v32, v32, v243
	v_exp_f32_e32 v138, v32
	v_sub_f32_e32 v32, v33, v243
	v_exp_f32_e32 v139, v32
	v_sub_f32_e32 v32, v34, v243
	v_exp_f32_e32 v140, v32
	v_sub_f32_e32 v32, v35, v243
	v_exp_f32_e32 v141, v32
	v_sub_f32_e32 v32, v36, v243
	v_exp_f32_e32 v142, v32
	v_sub_f32_e32 v32, v37, v243
	v_exp_f32_e32 v143, v32
	v_sub_f32_e32 v32, v38, v243
	v_exp_f32_e32 v144, v32
	v_sub_f32_e32 v32, v39, v243
	v_exp_f32_e32 v145, v32
	v_sub_f32_e32 v32, v40, v243
	v_exp_f32_e32 v40, v32
	v_sub_f32_e32 v32, v41, v243
	v_exp_f32_e32 v41, v32
	v_sub_f32_e32 v32, v42, v243
	v_exp_f32_e32 v42, v32
	v_sub_f32_e32 v32, v43, v243
	v_exp_f32_e32 v43, v32
	v_sub_f32_e32 v32, v44, v243
	v_exp_f32_e32 v44, v32
	v_sub_f32_e32 v32, v45, v243
	v_exp_f32_e32 v45, v32
	v_sub_f32_e32 v32, v46, v243
	v_exp_f32_e32 v46, v32
	v_sub_f32_e32 v32, v47, v243
	v_exp_f32_e32 v47, v32
	v_cvt_pk_bf16_f32 v32, v138, v139
	v_add_f32_e32 v138, 0, v138
	v_add_f32_e32 v138, v139, v138
	v_add_f32_e32 v138, v140, v138
	v_add_f32_e32 v138, v141, v138
	v_add_f32_e32 v138, v142, v138
	v_add_f32_e32 v138, v143, v138
	v_add_f32_e32 v138, v144, v138
	v_add_f32_e32 v138, v145, v138
	v_cvt_pk_bf16_f32 v36, v40, v41
	v_add_f32_e32 v40, v40, v138
	v_add_f32_e32 v40, v41, v40
	v_add_f32_e32 v40, v42, v40
	v_add_f32_e32 v40, v43, v40
	v_add_f32_e32 v40, v44, v40
	v_add_f32_e32 v40, v45, v40
	v_cvt_pk_bf16_f32 v33, v140, v141
	v_cvt_pk_bf16_f32 v34, v142, v143
	v_cvt_pk_bf16_f32 v35, v144, v145
	v_add_f32_e32 v40, v46, v40
	v_cvt_pk_bf16_f32 v37, v42, v43
	v_cvt_pk_bf16_f32 v38, v44, v45
	v_cvt_pk_bf16_f32 v39, v46, v47
	v_add_f32_e32 v138, v47, v40
	v_add_u32_e32 v139, 0x480, v122
	v_add_u32_e32 v140, 64, v122
	v_add_u32_e32 v141, 0x4c0, v122
	ds_read_b64_tr_b16 v[44:45], v122
	ds_read_b64_tr_b16 v[46:47], v139
	ds_read_b64_tr_b16 v[40:41], v140
	ds_read_b64_tr_b16 v[42:43], v141
	s_waitcnt lgkmcnt(0)
; DI f32x16 mfma32(bf16x8 a, bf16x8 b, f32x16 c) { return __builtin_amdgcn_mfma_f32_32x32x16_bf16(a, b, c, 0, 0, 0); }
; DI float max3f(float a, float b, float c) { float d; asm("v_max3_f32 %0, %1, %2, %3" : "=v"(d) : "v"(a), "v"(b), "v"(c)); return d; }
; DI void attn_d6_loop(char* lds, const Params& p, int layer, int first, int stride, int total) {
;     ...
;       const char* kb = lds + (64 * c + 32 * hf + lr) * KST + lh * 16;
; #pragma unroll
;       for (int ks = 0; ks < 4; ++ks) S = mfma32(*(const bf16x8*)(kb + ks * 32), qf[ks], S);
;       const int rel0 = key0 + 4 * lh - qrow;
; #pragma unroll
;       for (int r2 = 0; r2 < 16; ++r2) { const int rel = rel0 + (r2 & 3) + 8 * (r2 >> 2), v = qrow + rel;
;         const bool ok = (rel >= -64) && (rel <= 64) && (v >= 0) && (v < L); S[r2] = ok ? fmaf(-slope2, fabsf((float)rel), S[r2]) : -1e30f; }
;       float mx = S[0];
; #pragma unroll
;       for (int r2 = 1; r2 < 15; r2 += 2) mx = max3f(mx, S[r2], S[r2 + 1]);
;       mx = fmaxf(mx, S[15]);
;       if (__any(mx > m + 8.f)) {
;         mx = fmaxf(mx, __shfl_xor(mx, 32));
;         const float mnew = fmaxf(m, mx);
;         const float al = __builtin_amdgcn_exp2f(m - mnew); l *= al; O0 *= al; O1 *= al;
;         m = mnew;
;       }
;     ...
;           O0 = mfma32(__builtin_shufflevector(l0, h0, 0, 1, 2, 3, 4, 5, 6, 7), pf[s2], O0);
;           O1 = mfma32(__builtin_shufflevector(l1, h1, 0, 1, 2, 3, 4, 5, 6, 7), pf[s2], O1);
	v_add_f32_e32 v245, v245, v138
	v_mfma_f32_32x32x16_bf16 v[16:31], v[40:43], v[32:35], v[16:31]
	v_mfma_f32_32x32x16_bf16 v[0:15], v[44:47], v[32:35], v[0:15]
	v_add_u32_e32 v44, 0x900, v122
	v_add_u32_e32 v45, 0xd80, v122
	v_add_u32_e32 v46, 0x940, v122
	v_add_u32_e32 v47, 0xdc0, v122
	ds_read_b64_tr_b16 v[40:41], v44
	ds_read_b64_tr_b16 v[42:43], v45
	ds_read_b64_tr_b16 v[32:33], v46
	ds_read_b64_tr_b16 v[34:35], v47
	s_waitcnt lgkmcnt(0)
	s_nop 0
	v_mfma_f32_32x32x16_bf16 v[16:31], v[32:35], v[36:39], v[16:31]
	ds_read_b128 v[32:35], v204
	ds_read_b128 v[138:141], v204 offset:32
	v_mfma_f32_32x32x16_bf16 v[0:15], v[40:43], v[36:39], v[0:15]
	s_waitcnt lgkmcnt(1)
	v_mfma_f32_32x32x16_bf16 v[32:47], v[32:35], v[104:107], 0
	s_waitcnt lgkmcnt(0)
	v_mfma_f32_32x32x16_bf16 v[32:47], v[138:141], v[108:111], v[32:47]
	ds_read_b128 v[138:141], v204 offset:64
	s_waitcnt lgkmcnt(0)
	v_mfma_f32_32x32x16_bf16 v[32:47], v[138:141], v[100:103], v[32:47]
	ds_read_b128 v[138:141], v204 offset:96
	s_waitcnt lgkmcnt(0)
	v_mfma_f32_32x32x16_bf16 v[32:47], v[138:141], v[96:99], v[32:47]
	v_add_u32_e32 v138, v131, v194
	v_cmp_lt_i32_e32 vcc, -1, v138
	s_and_b64 s[74:75], s[8:9], vcc
	v_cmp_gt_i32_e32 vcc, s1, v138
	v_cvt_f32_i32_e32 v138, v194
	s_and_b64 vcc, s[74:75], vcc
	s_nop 5
	v_fma_f32 v32, v129, |v138|, v32
	v_add_u32_e32 v138, v131, v195
	v_cndmask_b32_e32 v32, v241, v32, vcc
	v_cmp_lt_i32_e32 vcc, -1, v138
	s_and_b64 s[74:75], s[10:11], vcc
	v_cmp_gt_i32_e32 vcc, s1, v138
	v_cvt_f32_i32_e32 v138, v195
	s_and_b64 vcc, s[74:75], vcc
	v_fma_f32 v33, v129, |v138|, v33
	v_add_u32_e32 v138, v131, v196
	v_cndmask_b32_e32 v33, v241, v33, vcc
	v_cmp_lt_i32_e32 vcc, -1, v138
	s_and_b64 s[74:75], s[12:13], vcc
	v_cmp_gt_i32_e32 vcc, s1, v138
	v_cvt_f32_i32_e32 v138, v196
	s_and_b64 vcc, s[74:75], vcc
	v_fma_f32 v34, v129, |v138|, v34
	v_add_u32_e32 v138, v131, v197
	v_cndmask_b32_e32 v34, v241, v34, vcc
	v_cmp_lt_i32_e32 vcc, -1, v138
	s_and_b64 s[74:75], s[44:45], vcc
	v_cmp_gt_i32_e32 vcc, s1, v138
	v_cvt_f32_i32_e32 v138, v197
	s_and_b64 vcc, s[74:75], vcc
	v_fma_f32 v35, v129, |v138|, v35
	v_add_u32_e32 v138, v131, v198
	v_cndmask_b32_e32 v35, v241, v35, vcc
	v_cmp_lt_i32_e32 vcc, -1, v138
	s_and_b64 s[74:75], s[46:47], vcc
	v_cmp_gt_i32_e32 vcc, s1, v138
	v_cvt_f32_i32_e32 v138, v198
	s_and_b64 vcc, s[74:75], vcc
	v_fma_f32 v36, v129, |v138|, v36
	v_add_u32_e32 v138, v131, v199
	v_cndmask_b32_e32 v36, v241, v36, vcc
	v_cmp_lt_i32_e32 vcc, -1, v138
	s_and_b64 s[74:75], s[48:49], vcc
	v_cmp_gt_i32_e32 vcc, s1, v138
	v_cvt_f32_i32_e32 v138, v199
	s_and_b64 vcc, s[74:75], vcc
	v_fma_f32 v37, v129, |v138|, v37
	v_add_u32_e32 v138, v131, v207
	v_cndmask_b32_e32 v37, v241, v37, vcc
	v_cmp_lt_i32_e32 vcc, -1, v138
	s_and_b64 s[74:75], s[50:51], vcc
	v_cmp_gt_i32_e32 vcc, s1, v138
	v_cvt_f32_i32_e32 v138, v207
	s_and_b64 vcc, s[74:75], vcc
	v_fma_f32 v38, v129, |v138|, v38
	v_add_u32_e32 v138, v131, v208
	v_cndmask_b32_e32 v38, v241, v38, vcc
	v_cmp_lt_i32_e32 vcc, -1, v138
	s_and_b64 s[74:75], s[52:53], vcc
	v_cmp_gt_i32_e32 vcc, s1, v138
	v_cvt_f32_i32_e32 v138, v208
	s_and_b64 vcc, s[74:75], vcc
	v_fma_f32 v39, v129, |v138|, v39
	v_add_u32_e32 v138, v131, v209
	v_cndmask_b32_e32 v39, v241, v39, vcc
	v_cmp_lt_i32_e32 vcc, -1, v138
	s_and_b64 s[74:75], s[54:55], vcc
	v_cmp_gt_i32_e32 vcc, s1, v138
	v_cvt_f32_i32_e32 v138, v209
	s_and_b64 vcc, s[74:75], vcc
	v_fma_f32 v40, v129, |v138|, v40
	v_add_u32_e32 v138, v131, v210
	v_cndmask_b32_e32 v40, v241, v40, vcc
	v_cmp_lt_i32_e32 vcc, -1, v138
	s_and_b64 s[74:75], s[56:57], vcc
	v_cmp_gt_i32_e32 vcc, s1, v138
	v_cvt_f32_i32_e32 v138, v210
	s_and_b64 vcc, s[74:75], vcc
	v_fma_f32 v41, v129, |v138|, v41
	v_add_u32_e32 v138, v131, v211
	v_cndmask_b32_e32 v41, v241, v41, vcc
	v_cmp_lt_i32_e32 vcc, -1, v138
	s_and_b64 s[74:75], s[58:59], vcc
	v_cmp_gt_i32_e32 vcc, s1, v138
	v_cvt_f32_i32_e32 v138, v211
	s_and_b64 vcc, s[74:75], vcc
	v_fma_f32 v42, v129, |v138|, v42
	v_add_u32_e32 v138, v131, v212
	v_cndmask_b32_e32 v42, v241, v42, vcc
	v_cmp_lt_i32_e32 vcc, -1, v138
	s_and_b64 s[74:75], s[60:61], vcc
	v_cmp_gt_i32_e32 vcc, s1, v138
	v_cvt_f32_i32_e32 v138, v212
	s_and_b64 vcc, s[74:75], vcc
	v_fma_f32 v43, v129, |v138|, v43
	v_add_u32_e32 v138, v131, v213
	v_cndmask_b32_e32 v43, v241, v43, vcc
	v_cmp_lt_i32_e32 vcc, -1, v138
	s_and_b64 s[74:75], s[62:63], vcc
	v_cmp_gt_i32_e32 vcc, s1, v138
	v_cvt_f32_i32_e32 v138, v213
	s_and_b64 vcc, s[74:75], vcc
	v_fma_f32 v44, v129, |v138|, v44
	v_add_u32_e32 v138, v131, v214
	v_cndmask_b32_e32 v44, v241, v44, vcc
	v_cmp_lt_i32_e32 vcc, -1, v138
	s_and_b64 s[74:75], s[64:65], vcc
	v_cmp_gt_i32_e32 vcc, s1, v138
	v_cvt_f32_i32_e32 v138, v214
	s_and_b64 vcc, s[74:75], vcc
	v_fma_f32 v45, v129, |v138|, v45
	v_add_u32_e32 v138, v131, v215
	v_cndmask_b32_e32 v45, v241, v45, vcc
	v_cmp_lt_i32_e32 vcc, -1, v138
	s_and_b64 s[74:75], s[66:67], vcc
	v_cmp_gt_i32_e32 vcc, s1, v138
	v_cvt_f32_i32_e32 v138, v215
	s_and_b64 vcc, s[74:75], vcc
	v_fma_f32 v46, v129, |v138|, v46
	v_add_u32_e32 v138, v131, v216
	v_cndmask_b32_e32 v46, v241, v46, vcc
	v_cmp_lt_i32_e32 vcc, -1, v138
	s_and_b64 s[74:75], s[68:69], vcc
	v_cmp_gt_i32_e32 vcc, s1, v138
	v_cvt_f32_i32_e32 v138, v216
	s_and_b64 vcc, s[74:75], vcc
	v_fma_f32 v47, v129, |v138|, v47
	v_max3_f32 v138, v32, v33, v34
	v_cndmask_b32_e32 v47, v241, v47, vcc
	v_max3_f32 v138, v138, v35, v36
	v_max3_f32 v138, v138, v37, v38
	v_max3_f32 v138, v138, v39, v40
	v_max3_f32 v138, v138, v41, v42
	v_max3_f32 v138, v138, v43, v44
	v_max3_f32 v138, v138, v45, v46
	v_max_f32_e32 v138, v138, v138
	v_max_f32_e32 v246, v138, v47
	v_cmp_gt_f32_e32 vcc, v246, v244
	s_cbranch_vccz .LBB0_514
	v_and_b32_e32 v139, 64, v226
	v_xor_b32_e32 v138, 32, v226
	v_add_u32_e32 v139, 64, v139
	v_cmp_lt_i32_e32 vcc, v138, v139
	s_nop 1
	v_cndmask_b32_e32 v138, v226, v138, vcc
	v_lshlrev_b32_e32 v138, 2, v138
	ds_bpermute_b32 v138, v138, v246
	s_waitcnt lgkmcnt(0)
	v_max3_f32 v139, v243, v246, v138
	v_sub_f32_e32 v138, v243, v139
	v_exp_f32_e32 v138, v138
	v_mov_b32_e32 v243, v139
	v_mul_f32_e32 v245, v245, v138
	v_pk_mul_f32 v[14:15], v[14:15], v[138:139] op_sel_hi:[1,0]
	v_pk_mul_f32 v[12:13], v[12:13], v[138:139] op_sel_hi:[1,0]
	v_pk_mul_f32 v[10:11], v[10:11], v[138:139] op_sel_hi:[1,0]
	v_pk_mul_f32 v[8:9], v[8:9], v[138:139] op_sel_hi:[1,0]
	v_pk_mul_f32 v[6:7], v[6:7], v[138:139] op_sel_hi:[1,0]
	v_pk_mul_f32 v[4:5], v[4:5], v[138:139] op_sel_hi:[1,0]
	v_pk_mul_f32 v[2:3], v[2:3], v[138:139] op_sel_hi:[1,0]
	v_pk_mul_f32 v[0:1], v[0:1], v[138:139] op_sel_hi:[1,0]
	v_pk_mul_f32 v[30:31], v[30:31], v[138:139] op_sel_hi:[1,0]
	v_pk_mul_f32 v[28:29], v[28:29], v[138:139] op_sel_hi:[1,0]
	v_pk_mul_f32 v[26:27], v[26:27], v[138:139] op_sel_hi:[1,0]
	v_pk_mul_f32 v[24:25], v[24:25], v[138:139] op_sel_hi:[1,0]
	v_pk_mul_f32 v[22:23], v[22:23], v[138:139] op_sel_hi:[1,0]
	v_pk_mul_f32 v[20:21], v[20:21], v[138:139] op_sel_hi:[1,0]
	v_pk_mul_f32 v[18:19], v[18:19], v[138:139] op_sel_hi:[1,0]
	v_pk_mul_f32 v[16:17], v[16:17], v[138:139] op_sel_hi:[1,0]
; DI unsigned pk2(float a, float b) { f32x2 v = {a, b}; bf2_t r = __builtin_convertvector(v, bf2_t); return __builtin_bit_cast(unsigned, r); }
; DI f32x16 mfma32(bf16x8 a, bf16x8 b, f32x16 c) { return __builtin_amdgcn_mfma_f32_32x32x16_bf16(a, b, c, 0, 0, 0); }
; DI void attn_d6_loop(char* lds, const Params& p, int layer, int first, int stride, int total) {
;     ...
;       float ps = 0.f;
; #pragma unroll
;       for (int r2 = 0; r2 < 16; ++r2) { S[r2] = __builtin_amdgcn_exp2f(S[r2] - m); ps += S[r2]; }
;       l += ps;
;       bf16x8 pf[2];
; #pragma unroll
;       for (int s2 = 0; s2 < 2; ++s2) { u32x4 w; w[0] = pk2(S[8 * s2], S[8 * s2 + 1]); w[1] = pk2(S[8 * s2 + 2], S[8 * s2 + 3]); w[2] = pk2(S[8 * s2 + 4], S[8 * s2 + 5]); w[3] = pk2(S[8 * s2 + 6], S[8 * s2 + 7]);
;         pf[s2] = __builtin_bit_cast(bf16x8, w); }
;       { const int g = lane >> 4, i16 = lane & 15;
;         const unsigned vbase = (unsigned)(size_t)(lds + VOFF) + (unsigned)((64 * c + 32 * hf + 4 * (g >> 1) + (i16 >> 2)) * KST + ((g & 1) * 16 + 4 * (i16 & 3)) * 2);
; #pragma unroll
;         for (int s2 = 0; s2 < 2; ++s2) {
;           s16x4 l0, h0, l1, h1;
;           const unsigned a0 = vbase + (unsigned)(16 * s2 * KST), a1 = a0 + 8u * KST, a2 = a0 + 64u, a3 = a1 + 64u;
;           asm volatile("ds_read_b64_tr_b16 %0, %4\n\tds_read_b64_tr_b16 %1, %5\n\tds_read_b64_tr_b16 %2, %6\n\tds_read_b64_tr_b16 %3, %7\n\ts_waitcnt lgkmcnt(0)"
;                        : "=&v"(l0), "=&v"(h0), "=&v"(l1), "=&v"(h1) : "v"(a0), "v"(a1), "v"(a2), "v"(a3) : "memory");
;           O0 = mfma32(__builtin_shufflevector(l0, h0, 0, 1, 2, 3, 4, 5, 6, 7), pf[s2], O0);
;           O1 = mfma32(__builtin_shufflevector(l1, h1, 0, 1, 2, 3, 4, 5, 6, 7), pf[s2], O1);
;         } }
.LBB0_514:
	v_sub_f32_e32 v32, v32, v243
	v_exp_f32_e32 v138, v32
	v_sub_f32_e32 v32, v33, v243
	v_exp_f32_e32 v139, v32
	v_sub_f32_e32 v32, v34, v243
	v_exp_f32_e32 v140, v32
	v_sub_f32_e32 v32, v35, v243
	v_exp_f32_e32 v141, v32
	v_sub_f32_e32 v32, v36, v243
	v_exp_f32_e32 v142, v32
	v_sub_f32_e32 v32, v37, v243
	v_exp_f32_e32 v143, v32
	v_sub_f32_e32 v32, v38, v243
	v_exp_f32_e32 v144, v32
	v_sub_f32_e32 v32, v39, v243
	v_exp_f32_e32 v145, v32
	v_sub_f32_e32 v32, v40, v243
	v_exp_f32_e32 v40, v32
	v_sub_f32_e32 v32, v41, v243
	v_exp_f32_e32 v41, v32
	v_sub_f32_e32 v32, v42, v243
	v_exp_f32_e32 v42, v32
	v_sub_f32_e32 v32, v43, v243
	v_exp_f32_e32 v43, v32
	v_sub_f32_e32 v32, v44, v243
	v_exp_f32_e32 v44, v32
	v_sub_f32_e32 v32, v45, v243
	v_exp_f32_e32 v45, v32
	v_sub_f32_e32 v32, v46, v243
	v_exp_f32_e32 v46, v32
	v_sub_f32_e32 v32, v47, v243
	v_exp_f32_e32 v47, v32
	v_cvt_pk_bf16_f32 v32, v138, v139
	v_add_f32_e32 v138, 0, v138
	v_add_f32_e32 v138, v139, v138
	v_add_f32_e32 v138, v140, v138
	v_add_f32_e32 v138, v141, v138
	v_add_f32_e32 v138, v142, v138
	v_add_f32_e32 v138, v143, v138
	v_add_f32_e32 v138, v144, v138
	v_add_f32_e32 v138, v145, v138
	v_cvt_pk_bf16_f32 v36, v40, v41
	v_add_f32_e32 v40, v40, v138
	v_add_f32_e32 v40, v41, v40
	v_add_f32_e32 v40, v42, v40
	v_add_f32_e32 v40, v43, v40
	v_add_f32_e32 v40, v44, v40
	v_add_f32_e32 v40, v45, v40
	v_cvt_pk_bf16_f32 v33, v140, v141
	v_cvt_pk_bf16_f32 v34, v142, v143
	v_cvt_pk_bf16_f32 v35, v144, v145
	v_add_f32_e32 v40, v46, v40
	v_cvt_pk_bf16_f32 v37, v42, v43
	v_cvt_pk_bf16_f32 v38, v44, v45
	v_cvt_pk_bf16_f32 v39, v46, v47
	v_add_f32_e32 v138, v47, v40
	v_add_u32_e32 v139, 0x480, v124
	v_add_u32_e32 v140, 64, v124
	v_add_u32_e32 v141, 0x4c0, v124
	ds_read_b64_tr_b16 v[44:45], v124
	ds_read_b64_tr_b16 v[46:47], v139
	ds_read_b64_tr_b16 v[40:41], v140
	ds_read_b64_tr_b16 v[42:43], v141
	s_waitcnt lgkmcnt(0)
	v_add_f32_e32 v244, v245, v138
	v_mfma_f32_32x32x16_bf16 v[0:15], v[44:47], v[32:35], v[0:15]
	v_add_u32_e32 v44, 0x900, v124
	v_add_u32_e32 v45, 0xd80, v124
	v_add_u32_e32 v46, 0x940, v124
	v_add_u32_e32 v47, 0xdc0, v124
	v_mfma_f32_32x32x16_bf16 v[16:31], v[40:43], v[32:35], v[16:31]
	ds_read_b64_tr_b16 v[40:41], v44
	ds_read_b64_tr_b16 v[42:43], v45
	ds_read_b64_tr_b16 v[32:33], v46
	ds_read_b64_tr_b16 v[34:35], v47
	s_waitcnt lgkmcnt(0)
	s_nop 0
	v_mfma_f32_32x32x16_bf16 v[0:15], v[40:43], v[36:39], v[0:15]
	v_mfma_f32_32x32x16_bf16 v[16:31], v[32:35], v[36:39], v[16:31]
	s_and_saveexec_b64 s[74:75], s[70:71]
	s_cbranch_execz .LBB0_518
	ds_read_b128 v[32:35], v205
	ds_read_b128 v[138:141], v205 offset:32
	v_readlane_b32 s4, v254, 31
	v_readlane_b32 s5, v254, 32
	s_waitcnt lgkmcnt(1)
	v_mfma_f32_32x32x16_bf16 v[32:47], v[32:35], v[104:107], 0
	ds_read_b128 v[104:107], v205 offset:64
	s_waitcnt lgkmcnt(1)
	v_mfma_f32_32x32x16_bf16 v[32:47], v[138:141], v[108:111], v[32:47]
	s_waitcnt lgkmcnt(0)
	v_mfma_f32_32x32x16_bf16 v[32:47], v[104:107], v[100:103], v[32:47]
	ds_read_b128 v[100:103], v205 offset:96
	s_waitcnt lgkmcnt(0)
; DI f32x16 mfma32(bf16x8 a, bf16x8 b, f32x16 c) { return __builtin_amdgcn_mfma_f32_32x32x16_bf16(a, b, c, 0, 0, 0); }
; DI float max3f(float a, float b, float c) { float d; asm("v_max3_f32 %0, %1, %2, %3" : "=v"(d) : "v"(a), "v"(b), "v"(c)); return d; }
; DI void attn_d6_loop(char* lds, const Params& p, int layer, int first, int stride, int total) {
;     ...
;       for (int ks = 0; ks < 4; ++ks) S = mfma32(*(const bf16x8*)(kb + ks * 32), qf[ks], S);
;       const int rel0 = key0 + 4 * lh - qrow;
; #pragma unroll
;       for (int r2 = 0; r2 < 16; ++r2) { const int rel = rel0 + (r2 & 3) + 8 * (r2 >> 2), v = qrow + rel;
;         const bool ok = (rel >= -64) && (rel <= 64) && (v >= 0) && (v < L); S[r2] = ok ? fmaf(-slope2, fabsf((float)rel), S[r2]) : -1e30f; }
;       float mx = S[0];
; #pragma unroll
;       for (int r2 = 1; r2 < 15; r2 += 2) mx = max3f(mx, S[r2], S[r2 + 1]);
;       mx = fmaxf(mx, S[15]);
;       if (__any(mx > m + 8.f)) {
;         mx = fmaxf(mx, __shfl_xor(mx, 32));
;         const float mnew = fmaxf(m, mx);
;         const float al = __builtin_amdgcn_exp2f(m - mnew); l *= al; O0 *= al; O1 *= al;
;         m = mnew;
;       }
	v_mfma_f32_32x32x16_bf16 v[32:47], v[100:103], v[96:99], v[32:47]
	v_add_u32_e32 v96, v131, v217
	v_cmp_lt_i32_e32 vcc, -1, v96
	s_and_b64 s[82:83], s[4:5], vcc
	v_cmp_gt_i32_e32 vcc, s1, v96
	v_cvt_f32_i32_e32 v96, v217
	s_and_b64 vcc, s[82:83], vcc
	v_readlane_b32 s4, v254, 33
	v_readlane_b32 s5, v254, 34
	s_nop 3
	v_fma_f32 v32, v129, |v96|, v32
	v_add_u32_e32 v96, v131, v218
	v_cndmask_b32_e32 v32, v241, v32, vcc
	v_cmp_lt_i32_e32 vcc, -1, v96
	s_and_b64 s[82:83], s[4:5], vcc
	v_cmp_gt_i32_e32 vcc, s1, v96
	v_cvt_f32_i32_e32 v96, v218
	s_and_b64 vcc, s[82:83], vcc
	v_readlane_b32 s4, v254, 35
	v_readlane_b32 s5, v254, 36
	v_fma_f32 v33, v129, |v96|, v33
	v_add_u32_e32 v96, v131, v219
	v_cndmask_b32_e32 v33, v241, v33, vcc
	v_cmp_lt_i32_e32 vcc, -1, v96
	s_and_b64 s[82:83], s[4:5], vcc
	v_cmp_gt_i32_e32 vcc, s1, v96
	v_cvt_f32_i32_e32 v96, v219
	s_and_b64 vcc, s[82:83], vcc
	v_readlane_b32 s4, v254, 37
	v_readlane_b32 s5, v254, 38
	v_fma_f32 v34, v129, |v96|, v34
	v_add_u32_e32 v96, v131, v220
	v_cndmask_b32_e32 v34, v241, v34, vcc
	v_cmp_lt_i32_e32 vcc, -1, v96
	s_and_b64 s[82:83], s[4:5], vcc
	v_cmp_gt_i32_e32 vcc, s1, v96
	v_cvt_f32_i32_e32 v96, v220
	s_and_b64 vcc, s[82:83], vcc
	v_readlane_b32 s4, v254, 39
	v_readlane_b32 s5, v254, 40
	v_fma_f32 v35, v129, |v96|, v35
	v_add_u32_e32 v96, v131, v221
	v_cndmask_b32_e32 v35, v241, v35, vcc
	v_cmp_lt_i32_e32 vcc, -1, v96
	s_and_b64 s[82:83], s[4:5], vcc
	v_cmp_gt_i32_e32 vcc, s1, v96
	v_cvt_f32_i32_e32 v96, v221
	s_and_b64 vcc, s[82:83], vcc
	v_readlane_b32 s4, v254, 41
	v_readlane_b32 s5, v254, 42
	v_fma_f32 v36, v129, |v96|, v36
	v_add_u32_e32 v96, v131, v227
	v_cndmask_b32_e32 v36, v241, v36, vcc
	v_cmp_lt_i32_e32 vcc, -1, v96
	s_and_b64 s[82:83], s[4:5], vcc
	v_cmp_gt_i32_e32 vcc, s1, v96
	v_cvt_f32_i32_e32 v96, v227
	s_and_b64 vcc, s[82:83], vcc
	v_readlane_b32 s4, v254, 43
	v_readlane_b32 s5, v254, 44
	v_fma_f32 v37, v129, |v96|, v37
	v_add_u32_e32 v96, v131, v228
	v_cndmask_b32_e32 v37, v241, v37, vcc
	v_cmp_lt_i32_e32 vcc, -1, v96
	s_and_b64 s[82:83], s[4:5], vcc
	v_cmp_gt_i32_e32 vcc, s1, v96
	v_cvt_f32_i32_e32 v96, v228
	s_and_b64 vcc, s[82:83], vcc
	v_readlane_b32 s4, v254, 45
	v_readlane_b32 s5, v254, 46
	v_fma_f32 v38, v129, |v96|, v38
	v_add_u32_e32 v96, v131, v229
	v_cndmask_b32_e32 v38, v241, v38, vcc
	v_cmp_lt_i32_e32 vcc, -1, v96
	s_and_b64 s[82:83], s[4:5], vcc
	v_cmp_gt_i32_e32 vcc, s1, v96
	v_cvt_f32_i32_e32 v96, v229
	s_and_b64 vcc, s[82:83], vcc
	v_readlane_b32 s4, v254, 47
	v_readlane_b32 s5, v254, 48
	v_fma_f32 v39, v129, |v96|, v39
	v_add_u32_e32 v96, v131, v230
	v_cndmask_b32_e32 v39, v241, v39, vcc
	v_cmp_lt_i32_e32 vcc, -1, v96
	s_and_b64 s[82:83], s[4:5], vcc
	v_cmp_gt_i32_e32 vcc, s1, v96
	v_cvt_f32_i32_e32 v96, v230
	s_and_b64 vcc, s[82:83], vcc
	v_readlane_b32 s4, v254, 49
	v_readlane_b32 s5, v254, 50
	v_fma_f32 v40, v129, |v96|, v40
	v_add_u32_e32 v96, v131, v231
	v_cndmask_b32_e32 v40, v241, v40, vcc
	v_cmp_lt_i32_e32 vcc, -1, v96
	s_and_b64 s[82:83], s[4:5], vcc
	v_cmp_gt_i32_e32 vcc, s1, v96
	v_cvt_f32_i32_e32 v96, v231
	s_and_b64 vcc, s[82:83], vcc
	v_readlane_b32 s4, v254, 51
	v_readlane_b32 s5, v254, 52
	v_fma_f32 v41, v129, |v96|, v41
	v_add_u32_e32 v96, v131, v232
	v_cndmask_b32_e32 v41, v241, v41, vcc
	v_cmp_lt_i32_e32 vcc, -1, v96
	s_and_b64 s[82:83], s[4:5], vcc
	v_cmp_gt_i32_e32 vcc, s1, v96
	v_cvt_f32_i32_e32 v96, v232
	s_and_b64 vcc, s[82:83], vcc
	v_readlane_b32 s4, v254, 53
	v_readlane_b32 s5, v254, 54
	v_fma_f32 v42, v129, |v96|, v42
	v_add_u32_e32 v96, v131, v233
	v_cndmask_b32_e32 v42, v241, v42, vcc
	v_cmp_lt_i32_e32 vcc, -1, v96
	s_and_b64 s[82:83], s[4:5], vcc
	v_cmp_gt_i32_e32 vcc, s1, v96
	v_cvt_f32_i32_e32 v96, v233
	s_and_b64 vcc, s[82:83], vcc
	v_readlane_b32 s4, v254, 55
	v_readlane_b32 s5, v254, 56
	v_fma_f32 v43, v129, |v96|, v43
	v_add_u32_e32 v96, v131, v234
	v_cndmask_b32_e32 v43, v241, v43, vcc
	v_cmp_lt_i32_e32 vcc, -1, v96
	s_and_b64 s[82:83], s[4:5], vcc
	v_cmp_gt_i32_e32 vcc, s1, v96
	v_cvt_f32_i32_e32 v96, v234
	s_and_b64 vcc, s[82:83], vcc
	v_readlane_b32 s4, v254, 57
	v_readlane_b32 s5, v254, 58
	v_fma_f32 v44, v129, |v96|, v44
	v_add_u32_e32 v96, v131, v235
	v_cndmask_b32_e32 v44, v241, v44, vcc
	v_cmp_lt_i32_e32 vcc, -1, v96
	s_and_b64 s[82:83], s[4:5], vcc
	v_cmp_gt_i32_e32 vcc, s1, v96
	v_cvt_f32_i32_e32 v96, v235
	s_and_b64 vcc, s[82:83], vcc
	v_readlane_b32 s4, v254, 59
	v_readlane_b32 s5, v254, 60
	v_fma_f32 v45, v129, |v96|, v45
	v_add_u32_e32 v96, v131, v236
	v_cndmask_b32_e32 v45, v241, v45, vcc
	v_cmp_lt_i32_e32 vcc, -1, v96
	s_and_b64 s[82:83], s[4:5], vcc
	v_cmp_gt_i32_e32 vcc, s1, v96
	v_cvt_f32_i32_e32 v96, v236
	s_and_b64 vcc, s[82:83], vcc
	v_readlane_b32 s4, v254, 61
	v_readlane_b32 s5, v254, 62
	v_fma_f32 v46, v129, |v96|, v46
	v_add_u32_e32 v96, v131, v237
	v_cndmask_b32_e32 v46, v241, v46, vcc
	v_cmp_lt_i32_e32 vcc, -1, v96
	s_and_b64 s[82:83], s[4:5], vcc
	v_cmp_gt_i32_e32 vcc, s1, v96
	v_cvt_f32_i32_e32 v96, v237
	s_and_b64 vcc, s[82:83], vcc
	v_add_f32_e32 v97, 0x41000000, v243
	v_fma_f32 v47, v129, |v96|, v47
	v_max3_f32 v96, v32, v33, v34
	v_cndmask_b32_e32 v47, v241, v47, vcc
	v_max3_f32 v96, v96, v35, v36
	v_max3_f32 v96, v96, v37, v38
	v_max3_f32 v96, v96, v39, v40
	v_max3_f32 v96, v96, v41, v42
	v_max3_f32 v96, v96, v43, v44
	v_max3_f32 v96, v96, v45, v46
	v_max_f32_e32 v96, v96, v96
	v_max_f32_e32 v96, v96, v47
	v_cmp_gt_f32_e32 vcc, v96, v97
	s_cbranch_vccz .LBB0_517
	v_and_b32_e32 v98, 64, v226
	v_xor_b32_e32 v97, 32, v226
	v_add_u32_e32 v98, 64, v98
	v_cmp_lt_i32_e32 vcc, v97, v98
	s_nop 1
	v_cndmask_b32_e32 v97, v226, v97, vcc
	v_lshlrev_b32_e32 v97, 2, v97
	ds_bpermute_b32 v97, v97, v96
	s_waitcnt lgkmcnt(0)
	v_max3_f32 v97, v243, v96, v97
	v_sub_f32_e32 v96, v243, v97
	v_exp_f32_e32 v96, v96
	v_mov_b32_e32 v243, v97
	v_mul_f32_e32 v244, v244, v96
	v_pk_mul_f32 v[14:15], v[14:15], v[96:97] op_sel_hi:[1,0]
	v_pk_mul_f32 v[12:13], v[12:13], v[96:97] op_sel_hi:[1,0]
	v_pk_mul_f32 v[10:11], v[10:11], v[96:97] op_sel_hi:[1,0]
	v_pk_mul_f32 v[8:9], v[8:9], v[96:97] op_sel_hi:[1,0]
	v_pk_mul_f32 v[6:7], v[6:7], v[96:97] op_sel_hi:[1,0]
	v_pk_mul_f32 v[4:5], v[4:5], v[96:97] op_sel_hi:[1,0]
	v_pk_mul_f32 v[2:3], v[2:3], v[96:97] op_sel_hi:[1,0]
	v_pk_mul_f32 v[0:1], v[0:1], v[96:97] op_sel_hi:[1,0]
	v_pk_mul_f32 v[30:31], v[30:31], v[96:97] op_sel_hi:[1,0]
	v_pk_mul_f32 v[28:29], v[28:29], v[96:97] op_sel_hi:[1,0]
	v_pk_mul_f32 v[26:27], v[26:27], v[96:97] op_sel_hi:[1,0]
	v_pk_mul_f32 v[24:25], v[24:25], v[96:97] op_sel_hi:[1,0]
	v_pk_mul_f32 v[22:23], v[22:23], v[96:97] op_sel_hi:[1,0]
	v_pk_mul_f32 v[20:21], v[20:21], v[96:97] op_sel_hi:[1,0]
	v_pk_mul_f32 v[18:19], v[18:19], v[96:97] op_sel_hi:[1,0]
	v_pk_mul_f32 v[16:17], v[16:17], v[96:97] op_sel_hi:[1,0]

; DI void attn_d6_loop(char* lds, const Params& p, int layer, int first, int stride, int total) {
;     ...
;   const float slope2 = exp2f(-(float)(2 * h + 2)) * LOG2E * (float)dl;
;   __syncthreads();
; #pragma unroll
;   for (int c = 0; c < 6; ++c) {
;     *(u32x4*)(lds + (64 * c + srow) * KST + sc * 16) = kr[c];
;     *(u32x4*)(lds + VOFF + (64 * c + srow) * KST + sc * 16) = vr[c];
;   }
;   __syncthreads();
;   if (u + stride < total) load_unit(u + stride);
;   f32x16 O0 = zero16(), O1 = zero16();
;   float m = -1e30f, l = 0.f;
; #pragma unroll
;   for (int cc_ = 0; cc_ < 3; ++cc_) { const int c = (wid >> 1) + cc_;
; #pragma unroll
;     for (int hf = 0; hf < 2; ++hf) {
;       const bool skip = (hf == 0) ? ((wid & 1) && c == (wid >> 1)) : (!(wid & 1) && c == (wid >> 1) + 2);
;       if (skip) continue;
.LBB0_1478:
	s_and_saveexec_b64 s[80:81], s[70:71]
	s_xor_b64 s[80:81], exec, s[80:81]
	s_or_saveexec_b64 s[80:81], s[80:81]
	v_cndmask_b32_e64 v1, 0, v240, s[74:75]
	v_sub_f32_e32 v0, v1, v0
	v_exp_f32_e32 v0, v0
	s_lshl_b32 s12, 1, s1
	v_cvt_f32_u32_e32 v1, s12
	v_mov_b32_e32 v14, v113
	v_ldexp_f32 v0, v0, s3
	v_mul_f32_e32 v0, 0xbfb8aa3b, v0
	v_mov_b32_e32 v15, v113
	v_mul_f32_e32 v129, v0, v1
	v_mov_b32_e32 v0, v113
	v_mov_b32_e32 v1, v113
	v_mov_b32_e32 v2, v113
	v_mov_b32_e32 v3, v113
	v_mov_b32_e32 v4, v113
	v_mov_b32_e32 v5, v113
	v_mov_b32_e32 v6, v113
	v_mov_b32_e32 v7, v113
	v_mov_b32_e32 v8, v113
	v_mov_b32_e32 v9, v113
	v_mov_b32_e32 v10, v113
	v_mov_b32_e32 v11, v113
	v_mov_b32_e32 v12, v113
	v_mov_b32_e32 v13, v113
	v_mov_b64_e32 v[30:31], v[14:15]
	s_lshr_b32 s1, 0x1000, s1
	v_mov_b32_e32 v245, 0
	v_mov_b32_e32 v243, 0xf149f2ca
	v_mov_b64_e32 v[28:29], v[12:13]
	v_mov_b64_e32 v[26:27], v[10:11]
	v_mov_b64_e32 v[24:25], v[8:9]
	v_mov_b64_e32 v[22:23], v[6:7]
	v_mov_b64_e32 v[20:21], v[4:5]
	v_mov_b64_e32 v[18:19], v[2:3]
	v_mov_b64_e32 v[16:17], v[0:1]
	s_xor_b64 exec, exec, s[80:81]
	s_cbranch_execz .LBB0_1483
; DI f32x16 mfma32(bf16x8 a, bf16x8 b, f32x16 c) { return __builtin_amdgcn_mfma_f32_32x32x16_bf16(a, b, c, 0, 0, 0); }
; DI float max3f(float a, float b, float c) { float d; asm("v_max3_f32 %0, %1, %2, %3" : "=v"(d) : "v"(a), "v"(b), "v"(c)); return d; }
; DI void attn_d6_loop(char* lds, const Params& p, int layer, int first, int stride, int total) {
;     ...
;       f32x16 S = zero16();
;       const char* kb = lds + (64 * c + 32 * hf + lr) * KST + lh * 16;
; #pragma unroll
;       for (int ks = 0; ks < 4; ++ks) S = mfma32(*(const bf16x8*)(kb + ks * 32), qf[ks], S);
;       const int rel0 = key0 + 4 * lh - qrow;
; #pragma unroll
;       for (int r2 = 0; r2 < 16; ++r2) { const int rel = rel0 + (r2 & 3) + 8 * (r2 >> 2), v = qrow + rel;
;         const bool ok = (rel >= -64) && (rel <= 64) && (v >= 0) && (v < L); S[r2] = ok ? fmaf(-slope2, fabsf((float)rel), S[r2]) : -1e30f; }
;       float mx = S[0];
; #pragma unroll
;       for (int r2 = 1; r2 < 15; r2 += 2) mx = max3f(mx, S[r2], S[r2 + 1]);
;       mx = fmaxf(mx, S[15]);
;       if (__any(mx > m + 8.f)) {
;         mx = fmaxf(mx, __shfl_xor(mx, 32));
;         const float mnew = fmaxf(m, mx);
;         const float al = __builtin_amdgcn_exp2f(m - mnew); l *= al; O0 *= al; O1 *= al;
;         m = mnew;
;       }
	ds_read_b128 v[0:3], v200
	ds_read_b128 v[16:19], v200 offset:32
	v_readlane_b32 s12, v253, 27
	v_readlane_b32 s13, v253, 28
	s_waitcnt vmcnt(3) lgkmcnt(1)
	v_mfma_f32_32x32x16_bf16 v[0:15], v[0:3], v[104:107], 0
	s_waitcnt vmcnt(2) lgkmcnt(0)
	v_mfma_f32_32x32x16_bf16 v[0:15], v[16:19], v[108:111], v[0:15]
	ds_read_b128 v[16:19], v200 offset:64
	s_waitcnt vmcnt(1) lgkmcnt(0)
	v_mfma_f32_32x32x16_bf16 v[0:15], v[16:19], v[100:103], v[0:15]
	ds_read_b128 v[16:19], v200 offset:96
	s_waitcnt vmcnt(0) lgkmcnt(0)
	v_mfma_f32_32x32x16_bf16 v[0:15], v[16:19], v[96:99], v[0:15]
	v_add_u32_e32 v16, v131, v136
	v_cmp_lt_i32_e32 vcc, -1, v16
	s_and_b64 s[74:75], s[36:37], vcc
	v_cmp_gt_i32_e32 vcc, s1, v16
	v_cvt_f32_i32_e32 v16, v136
	v_add_u32_e32 v17, 1, v136
	s_and_b64 vcc, s[74:75], vcc
	s_nop 4
	v_fma_f32 v0, v129, |v16|, v0
	v_add_u32_e32 v16, v131, v17
	v_cndmask_b32_e32 v0, v241, v0, vcc
	v_cmp_lt_i32_e32 vcc, -1, v16
	s_and_b64 s[74:75], s[40:41], vcc
	v_cmp_gt_i32_e32 vcc, s1, v16
	v_cvt_f32_i32_e32 v16, v17
	v_add_u32_e32 v17, 2, v136
	s_and_b64 vcc, s[74:75], vcc
	v_fma_f32 v1, v129, |v16|, v1
	v_add_u32_e32 v16, v131, v17
	v_cndmask_b32_e32 v1, v241, v1, vcc
	v_cmp_lt_i32_e32 vcc, -1, v16
	s_and_b64 s[74:75], s[42:43], vcc
	v_cmp_gt_i32_e32 vcc, s1, v16
	v_cvt_f32_i32_e32 v16, v17
	v_add_u32_e32 v17, 3, v136
	s_and_b64 vcc, s[74:75], vcc
	v_fma_f32 v2, v129, |v16|, v2
	v_add_u32_e32 v16, v131, v17
	v_cndmask_b32_e32 v2, v241, v2, vcc
	v_cmp_lt_i32_e32 vcc, -1, v16
	s_and_b64 s[74:75], s[84:85], vcc
	v_cmp_gt_i32_e32 vcc, s1, v16
	v_cvt_f32_i32_e32 v16, v17
	v_add_u32_e32 v17, 8, v136
	s_and_b64 vcc, s[74:75], vcc
	v_fma_f32 v3, v129, |v16|, v3
	v_add_u32_e32 v16, v131, v17
	v_cndmask_b32_e32 v3, v241, v3, vcc
	v_cmp_lt_i32_e32 vcc, -1, v16
	s_and_b64 s[74:75], s[86:87], vcc
	v_cmp_gt_i32_e32 vcc, s1, v16
	v_cvt_f32_i32_e32 v16, v17
	s_and_b64 vcc, s[74:75], vcc
	v_fma_f32 v4, v129, |v16|, v4
	v_add_u32_e32 v16, v131, v242
	v_cndmask_b32_e32 v4, v241, v4, vcc
	v_cmp_lt_i32_e32 vcc, -1, v16
	s_and_b64 s[74:75], s[92:93], vcc
	v_cmp_gt_i32_e32 vcc, s1, v16
	v_cvt_f32_i32_e32 v16, v242
	s_and_b64 vcc, s[74:75], vcc
	v_fma_f32 v5, v129, |v16|, v5
	v_add_u32_e32 v16, v131, v137
	v_cndmask_b32_e32 v5, v241, v5, vcc
	v_cmp_lt_i32_e32 vcc, -1, v16
	s_and_b64 s[74:75], s[12:13], vcc
	v_cmp_gt_i32_e32 vcc, s1, v16
	v_cvt_f32_i32_e32 v16, v137
	s_and_b64 vcc, s[74:75], vcc
	v_readlane_b32 s12, v253, 29
	v_readlane_b32 s13, v253, 30
	v_fma_f32 v6, v129, |v16|, v6
	v_add_u32_e32 v16, v131, v248
	v_cndmask_b32_e32 v6, v241, v6, vcc
	v_cmp_lt_i32_e32 vcc, -1, v16
	s_and_b64 s[74:75], s[12:13], vcc
	v_cmp_gt_i32_e32 vcc, s1, v16
	v_cvt_f32_i32_e32 v16, v248
	s_and_b64 vcc, s[74:75], vcc
	v_readlane_b32 s12, v251, 63
	v_readlane_b32 s13, v253, 0
	v_fma_f32 v7, v129, |v16|, v7
	v_add_u32_e32 v16, v131, v249
	v_cndmask_b32_e32 v7, v241, v7, vcc
	v_cmp_lt_i32_e32 vcc, -1, v16
	s_and_b64 s[74:75], s[12:13], vcc
	v_cmp_gt_i32_e32 vcc, s1, v16
	v_cvt_f32_i32_e32 v16, v249
	s_and_b64 vcc, s[74:75], vcc
	v_readlane_b32 s12, v253, 1
	v_readlane_b32 s13, v253, 2
	v_fma_f32 v8, v129, |v16|, v8
	v_add_u32_e32 v16, v131, v250
	v_cndmask_b32_e32 v8, v241, v8, vcc
	v_cmp_lt_i32_e32 vcc, -1, v16
	s_and_b64 s[74:75], s[12:13], vcc
	v_cmp_gt_i32_e32 vcc, s1, v16
	v_cvt_f32_i32_e32 v16, v250
	s_and_b64 vcc, s[74:75], vcc
	v_readlane_b32 s12, v253, 3
	v_readlane_b32 s13, v253, 4
	v_fma_f32 v9, v129, |v16|, v9
	v_add_u32_e32 v16, v131, v146
	v_cndmask_b32_e32 v9, v241, v9, vcc
	v_cmp_lt_i32_e32 vcc, -1, v16
	s_and_b64 s[74:75], s[12:13], vcc
	v_cmp_gt_i32_e32 vcc, s1, v16
	v_cvt_f32_i32_e32 v16, v146
	s_and_b64 vcc, s[74:75], vcc
	v_readlane_b32 s12, v253, 5
	v_readlane_b32 s13, v253, 6
	v_fma_f32 v10, v129, |v16|, v10
	v_add_u32_e32 v16, v131, v147
	v_cndmask_b32_e32 v10, v241, v10, vcc
	v_cmp_lt_i32_e32 vcc, -1, v16
	s_and_b64 s[74:75], s[12:13], vcc
	v_cmp_gt_i32_e32 vcc, s1, v16
	v_cvt_f32_i32_e32 v16, v147
	s_and_b64 vcc, s[74:75], vcc
	v_readlane_b32 s12, v253, 7
	v_readlane_b32 s13, v253, 8
	v_fma_f32 v11, v129, |v16|, v11
	v_add_u32_e32 v16, v131, v148
	v_cndmask_b32_e32 v11, v241, v11, vcc
	v_cmp_lt_i32_e32 vcc, -1, v16
	s_and_b64 s[74:75], s[12:13], vcc
	v_cmp_gt_i32_e32 vcc, s1, v16
	v_cvt_f32_i32_e32 v16, v148
	s_and_b64 vcc, s[74:75], vcc
	v_readlane_b32 s12, v253, 9
	v_readlane_b32 s13, v253, 10
	v_fma_f32 v12, v129, |v16|, v12
	v_add_u32_e32 v16, v131, v149
	v_cndmask_b32_e32 v12, v241, v12, vcc
	v_cmp_lt_i32_e32 vcc, -1, v16
	s_and_b64 s[74:75], s[12:13], vcc
	v_cmp_gt_i32_e32 vcc, s1, v16
	v_cvt_f32_i32_e32 v16, v149
	s_and_b64 vcc, s[74:75], vcc
	v_readlane_b32 s12, v253, 11
	v_readlane_b32 s13, v253, 12
	v_fma_f32 v13, v129, |v16|, v13
	v_add_u32_e32 v16, v131, v150
	v_cndmask_b32_e32 v13, v241, v13, vcc
	v_cmp_lt_i32_e32 vcc, -1, v16
	s_and_b64 s[74:75], s[12:13], vcc
	v_cmp_gt_i32_e32 vcc, s1, v16
	v_cvt_f32_i32_e32 v16, v150
	s_and_b64 vcc, s[74:75], vcc
	v_readlane_b32 s12, v253, 13
	v_readlane_b32 s13, v253, 14
	v_fma_f32 v14, v129, |v16|, v14
	v_add_u32_e32 v16, v131, v151
	v_cndmask_b32_e32 v14, v241, v14, vcc
	v_cmp_lt_i32_e32 vcc, -1, v16
	s_and_b64 s[74:75], s[12:13], vcc
	v_cmp_gt_i32_e32 vcc, s1, v16
	v_cvt_f32_i32_e32 v16, v151
	s_and_b64 vcc, s[74:75], vcc
	v_fma_f32 v15, v129, |v16|, v15
	v_max3_f32 v16, v0, v1, v2
	v_cndmask_b32_e32 v15, v241, v15, vcc
	v_max3_f32 v16, v16, v3, v4
	v_max3_f32 v16, v16, v5, v6
	v_max3_f32 v16, v16, v7, v8
	v_max3_f32 v16, v16, v9, v10
	v_max3_f32 v16, v16, v11, v12
	v_max3_f32 v16, v16, v13, v14
	v_max_f32_e32 v16, v16, v16
	v_max_f32_e32 v16, v16, v15
	v_cmp_lt_f32_e32 vcc, s95, v16
	s_cbranch_vccz .LBB0_1481
	v_cmp_lt_i32_e32 vcc, v209, v208
	s_nop 1
	v_cndmask_b32_e32 v17, v207, v209, vcc
	v_lshlrev_b32_e32 v17, 2, v17
	ds_bpermute_b32 v17, v17, v16
	s_waitcnt lgkmcnt(0)
	v_max3_f32 v243, v16, v17, s95
	v_sub_f32_e32 v16, 0xf149f2ca, v243
	v_exp_f32_e32 v16, v16
	s_nop 0
	v_mul_f32_e32 v32, 0, v16
	s_branch .LBB0_1482

; DI f32x16 mfma32(bf16x8 a, bf16x8 b, f32x16 c) { return __builtin_amdgcn_mfma_f32_32x32x16_bf16(a, b, c, 0, 0, 0); }
; DI float max3f(float a, float b, float c) { float d; asm("v_max3_f32 %0, %1, %2, %3" : "=v"(d) : "v"(a), "v"(b), "v"(c)); return d; }
; DI void attn_d6_loop(char* lds, const Params& p, int layer, int first, int stride, int total) {
;     ...
;       const int key0 = q0 - 64 + 64 * c + 32 * hf;
;       f32x16 S = zero16();
;       const char* kb = lds + (64 * c + 32 * hf + lr) * KST + lh * 16;
; #pragma unroll
;       for (int ks = 0; ks < 4; ++ks) S = mfma32(*(const bf16x8*)(kb + ks * 32), qf[ks], S);
;       const int rel0 = key0 + 4 * lh - qrow;
; #pragma unroll
;       for (int r2 = 0; r2 < 16; ++r2) { const int rel = rel0 + (r2 & 3) + 8 * (r2 >> 2), v = qrow + rel;
;         const bool ok = (rel >= -64) && (rel <= 64) && (v >= 0) && (v < L); S[r2] = ok ? fmaf(-slope2, fabsf((float)rel), S[r2]) : -1e30f; }
;       float mx = S[0];
; #pragma unroll
;       for (int r2 = 1; r2 < 15; r2 += 2) mx = max3f(mx, S[r2], S[r2 + 1]);
;       mx = fmaxf(mx, S[15]);
;       if (__any(mx > m + 8.f)) {
.LBB0_1483:
	s_or_b64 exec, exec, s[80:81]
	ds_read_b128 v[32:35], v201
	ds_read_b128 v[138:141], v201 offset:32
	v_readlane_b32 s16, v251, 51
	v_readlane_b32 s17, v251, 52
	v_add_f32_e32 v244, 0x41000000, v243
	s_waitcnt vmcnt(3) lgkmcnt(1)
	v_mfma_f32_32x32x16_bf16 v[32:47], v[32:35], v[104:107], 0
	v_ashrrev_i32_e32 v133, 31, v132
	s_lshl_b32 s12, s0, 6
	s_waitcnt vmcnt(2) lgkmcnt(0)
	v_mfma_f32_32x32x16_bf16 v[32:47], v[138:141], v[108:111], v[32:47]
	ds_read_b128 v[138:141], v201 offset:64
	s_waitcnt vmcnt(1) lgkmcnt(0)
	v_mfma_f32_32x32x16_bf16 v[32:47], v[138:141], v[100:103], v[32:47]
	ds_read_b128 v[138:141], v201 offset:96
	s_waitcnt vmcnt(0) lgkmcnt(0)
	v_mfma_f32_32x32x16_bf16 v[32:47], v[138:141], v[96:99], v[32:47]
	v_add_u32_e32 v138, v131, v117
	v_cmp_lt_i32_e32 vcc, -1, v138
	s_and_b64 s[74:75], s[96:97], vcc
	v_cmp_gt_i32_e32 vcc, s1, v138
	v_cvt_f32_i32_e32 v138, v117
	s_and_b64 vcc, s[74:75], vcc
	s_nop 5
	v_fma_f32 v32, v129, |v138|, v32
	v_add_u32_e32 v138, v131, v152
	v_cndmask_b32_e32 v32, v241, v32, vcc
	v_cmp_lt_i32_e32 vcc, -1, v138
	s_and_b64 s[74:75], s[16:17], vcc
	v_cmp_gt_i32_e32 vcc, s1, v138
	v_cvt_f32_i32_e32 v138, v152
	s_and_b64 vcc, s[74:75], vcc
	v_readlane_b32 s16, v251, 47
	v_readlane_b32 s17, v251, 48
	v_fma_f32 v33, v129, |v138|, v33
	v_add_u32_e32 v138, v131, v153
	v_cndmask_b32_e32 v33, v241, v33, vcc
	v_cmp_lt_i32_e32 vcc, -1, v138
	s_and_b64 s[74:75], s[16:17], vcc
	v_cmp_gt_i32_e32 vcc, s1, v138
	v_cvt_f32_i32_e32 v138, v153
	s_and_b64 vcc, s[74:75], vcc
	v_readlane_b32 s16, v251, 49
	v_readlane_b32 s17, v251, 50
	v_fma_f32 v34, v129, |v138|, v34
	v_add_u32_e32 v138, v131, v154
	v_cndmask_b32_e32 v34, v241, v34, vcc
	v_cmp_lt_i32_e32 vcc, -1, v138
	s_and_b64 s[74:75], s[16:17], vcc
	v_cmp_gt_i32_e32 vcc, s1, v138
	v_cvt_f32_i32_e32 v138, v154
	s_and_b64 vcc, s[74:75], vcc
	v_readlane_b32 s16, v251, 37
	v_readlane_b32 s17, v251, 38
	v_fma_f32 v35, v129, |v138|, v35
	v_add_u32_e32 v138, v131, v155
	v_cndmask_b32_e32 v35, v241, v35, vcc
	v_cmp_lt_i32_e32 vcc, -1, v138
	s_and_b64 s[74:75], s[16:17], vcc
	v_cmp_gt_i32_e32 vcc, s1, v138
	v_cvt_f32_i32_e32 v138, v155
	s_and_b64 vcc, s[74:75], vcc
	v_readlane_b32 s16, v251, 39
	v_readlane_b32 s17, v251, 40
	v_fma_f32 v36, v129, |v138|, v36
	v_add_u32_e32 v138, v131, v156
	v_cndmask_b32_e32 v36, v241, v36, vcc
	v_cmp_lt_i32_e32 vcc, -1, v138
	s_and_b64 s[74:75], s[16:17], vcc
	v_cmp_gt_i32_e32 vcc, s1, v138
	v_cvt_f32_i32_e32 v138, v156
	s_and_b64 vcc, s[74:75], vcc
	v_readlane_b32 s16, v251, 41
	v_readlane_b32 s17, v251, 42
	v_fma_f32 v37, v129, |v138|, v37
	v_add_u32_e32 v138, v131, v157
	v_cndmask_b32_e32 v37, v241, v37, vcc
	v_cmp_lt_i32_e32 vcc, -1, v138
	s_and_b64 s[74:75], s[16:17], vcc
	v_cmp_gt_i32_e32 vcc, s1, v138
	v_cvt_f32_i32_e32 v138, v157
	s_and_b64 vcc, s[74:75], vcc
	v_readlane_b32 s16, v251, 43
	v_readlane_b32 s17, v251, 44
	v_fma_f32 v38, v129, |v138|, v38
	v_add_u32_e32 v138, v131, v158
	v_cndmask_b32_e32 v38, v241, v38, vcc
	v_cmp_lt_i32_e32 vcc, -1, v138
	s_and_b64 s[74:75], s[16:17], vcc
	v_cmp_gt_i32_e32 vcc, s1, v138
	v_cvt_f32_i32_e32 v138, v158
	s_and_b64 vcc, s[74:75], vcc
	v_readlane_b32 s16, v251, 45
	v_readlane_b32 s17, v251, 46
	v_fma_f32 v39, v129, |v138|, v39
	v_add_u32_e32 v138, v131, v159
	v_cndmask_b32_e32 v39, v241, v39, vcc
	v_cmp_lt_i32_e32 vcc, -1, v138
	s_and_b64 s[74:75], s[16:17], vcc
	v_cmp_gt_i32_e32 vcc, s1, v138
	v_cvt_f32_i32_e32 v138, v159
	s_and_b64 vcc, s[74:75], vcc
	v_readlane_b32 s16, v253, 31
	v_readlane_b32 s17, v253, 32
	v_fma_f32 v40, v129, |v138|, v40
	v_add_u32_e32 v138, v131, v160
	v_cndmask_b32_e32 v40, v241, v40, vcc
	v_cmp_lt_i32_e32 vcc, -1, v138
	s_and_b64 s[74:75], s[16:17], vcc
	v_cmp_gt_i32_e32 vcc, s1, v138
	v_cvt_f32_i32_e32 v138, v160
	s_and_b64 vcc, s[74:75], vcc
	v_readlane_b32 s16, v253, 33
	v_readlane_b32 s17, v253, 34
	v_fma_f32 v41, v129, |v138|, v41
	v_add_u32_e32 v138, v131, v161
	v_cndmask_b32_e32 v41, v241, v41, vcc
	v_cmp_lt_i32_e32 vcc, -1, v138
	s_and_b64 s[74:75], s[16:17], vcc
	v_cmp_gt_i32_e32 vcc, s1, v138
	v_cvt_f32_i32_e32 v138, v161
	s_and_b64 vcc, s[74:75], vcc
	v_readlane_b32 s16, v253, 35
	v_readlane_b32 s17, v253, 36
	v_fma_f32 v42, v129, |v138|, v42
	v_add_u32_e32 v138, v131, v162
	v_cndmask_b32_e32 v42, v241, v42, vcc
	v_cmp_lt_i32_e32 vcc, -1, v138
	s_and_b64 s[74:75], s[16:17], vcc
	v_cmp_gt_i32_e32 vcc, s1, v138
	v_cvt_f32_i32_e32 v138, v162
	s_and_b64 vcc, s[74:75], vcc
	v_readlane_b32 s16, v253, 37
	v_readlane_b32 s17, v253, 38
	v_fma_f32 v43, v129, |v138|, v43
	v_add_u32_e32 v138, v131, v163
	v_cndmask_b32_e32 v43, v241, v43, vcc
	v_cmp_lt_i32_e32 vcc, -1, v138
	s_and_b64 s[74:75], s[16:17], vcc
	v_cmp_gt_i32_e32 vcc, s1, v138
	v_cvt_f32_i32_e32 v138, v163
	s_and_b64 vcc, s[74:75], vcc
	v_readlane_b32 s16, v253, 39
	v_readlane_b32 s17, v253, 40
	v_fma_f32 v44, v129, |v138|, v44
	v_add_u32_e32 v138, v131, v164
	v_cndmask_b32_e32 v44, v241, v44, vcc
	v_cmp_lt_i32_e32 vcc, -1, v138
	s_and_b64 s[74:75], s[16:17], vcc
	v_cmp_gt_i32_e32 vcc, s1, v138
	v_cvt_f32_i32_e32 v138, v164
	s_and_b64 vcc, s[74:75], vcc
	v_readlane_b32 s16, v253, 41
	v_readlane_b32 s17, v253, 42
	v_fma_f32 v45, v129, |v138|, v45
	v_add_u32_e32 v138, v131, v165
	v_cndmask_b32_e32 v45, v241, v45, vcc
	v_cmp_lt_i32_e32 vcc, -1, v138
	s_and_b64 s[74:75], s[16:17], vcc
	v_cmp_gt_i32_e32 vcc, s1, v138
	v_cvt_f32_i32_e32 v138, v165
	s_and_b64 vcc, s[74:75], vcc
	v_readlane_b32 s16, v253, 43
	v_readlane_b32 s17, v253, 44
	v_fma_f32 v46, v129, |v138|, v46
	v_add_u32_e32 v138, v131, v166
	v_cndmask_b32_e32 v46, v241, v46, vcc
	v_cmp_lt_i32_e32 vcc, -1, v138
	s_and_b64 s[74:75], s[16:17], vcc
	v_cmp_gt_i32_e32 vcc, s1, v138
	v_cvt_f32_i32_e32 v138, v166
	s_and_b64 vcc, s[74:75], vcc
	v_fma_f32 v47, v129, |v138|, v47
	v_max3_f32 v138, v32, v33, v34
	v_cndmask_b32_e32 v47, v241, v47, vcc
	v_max3_f32 v138, v138, v35, v36
	v_max3_f32 v138, v138, v37, v38
	v_max3_f32 v138, v138, v39, v40
	v_max3_f32 v138, v138, v41, v42
	v_max3_f32 v138, v138, v43, v44
	v_max3_f32 v138, v138, v45, v46
	v_max_f32_e32 v138, v138, v138
	v_max_f32_e32 v246, v138, v47
	v_cmp_gt_f32_e32 vcc, v246, v244
	s_cbranch_vccz .LBB0_1485
; DI unsigned pk2(float a, float b) { f32x2 v = {a, b}; bf2_t r = __builtin_convertvector(v, bf2_t); return __builtin_bit_cast(unsigned, r); }
; DI f32x16 mfma32(bf16x8 a, bf16x8 b, f32x16 c) { return __builtin_amdgcn_mfma_f32_32x32x16_bf16(a, b, c, 0, 0, 0); }
; DI void attn_d6_loop(char* lds, const Params& p, int layer, int first, int stride, int total) {
;     ...
;       if (__any(mx > m + 8.f)) {
;         mx = fmaxf(mx, __shfl_xor(mx, 32));
;         const float mnew = fmaxf(m, mx);
;         const float al = __builtin_amdgcn_exp2f(m - mnew); l *= al; O0 *= al; O1 *= al;
;         m = mnew;
;       }
;       float ps = 0.f;
; #pragma unroll
;       for (int r2 = 0; r2 < 16; ++r2) { S[r2] = __builtin_amdgcn_exp2f(S[r2] - m); ps += S[r2]; }
;       l += ps;
;       bf16x8 pf[2];
; #pragma unroll
;       for (int s2 = 0; s2 < 2; ++s2) { u32x4 w; w[0] = pk2(S[8 * s2], S[8 * s2 + 1]); w[1] = pk2(S[8 * s2 + 2], S[8 * s2 + 3]); w[2] = pk2(S[8 * s2 + 4], S[8 * s2 + 5]); w[3] = pk2(S[8 * s2 + 6], S[8 * s2 + 7]);
;         pf[s2] = __builtin_bit_cast(bf16x8, w); }
;       { const int g = lane >> 4, i16 = lane & 15;
;         const unsigned vbase = (unsigned)(size_t)(lds + VOFF) + (unsigned)((64 * c + 32 * hf + 4 * (g >> 1) + (i16 >> 2)) * KST + ((g & 1) * 16 + 4 * (i16 & 3)) * 2);
; #pragma unroll
;         for (int s2 = 0; s2 < 2; ++s2) {
;           s16x4 l0, h0, l1, h1;
;           const unsigned a0 = vbase + (unsigned)(16 * s2 * KST), a1 = a0 + 8u * KST, a2 = a0 + 64u, a3 = a1 + 64u;
;           asm volatile("ds_read_b64_tr_b16 %0, %4\n\tds_read_b64_tr_b16 %1, %5\n\tds_read_b64_tr_b16 %2, %6\n\tds_read_b64_tr_b16 %3, %7\n\ts_waitcnt lgkmcnt(0)"
;                        : "=&v"(l0), "=&v"(h0), "=&v"(l1), "=&v"(h1) : "v"(a0), "v"(a1), "v"(a2), "v"(a3) : "memory");
;           O0 = mfma32(__builtin_shufflevector(l0, h0, 0, 1, 2, 3, 4, 5, 6, 7), pf[s2], O0);
;           O1 = mfma32(__builtin_shufflevector(l1, h1, 0, 1, 2, 3, 4, 5, 6, 7), pf[s2], O1);
;         } }
	v_cmp_lt_i32_e32 vcc, v209, v208
	s_nop 1
	v_cndmask_b32_e32 v138, v207, v209, vcc
	v_lshlrev_b32_e32 v138, 2, v138
	ds_bpermute_b32 v138, v138, v246
	s_waitcnt lgkmcnt(0)
	v_max3_f32 v139, v243, v246, v138
	v_sub_f32_e32 v138, v243, v139
	v_exp_f32_e32 v138, v138
	v_add_f32_e32 v244, 0x41000000, v139
	v_mov_b32_e32 v243, v139
	v_mul_f32_e32 v245, v245, v138
	v_pk_mul_f32 v[14:15], v[14:15], v[138:139] op_sel_hi:[1,0]
	v_pk_mul_f32 v[12:13], v[12:13], v[138:139] op_sel_hi:[1,0]
	v_pk_mul_f32 v[10:11], v[10:11], v[138:139] op_sel_hi:[1,0]
	v_pk_mul_f32 v[8:9], v[8:9], v[138:139] op_sel_hi:[1,0]
	v_pk_mul_f32 v[6:7], v[6:7], v[138:139] op_sel_hi:[1,0]
	v_pk_mul_f32 v[4:5], v[4:5], v[138:139] op_sel_hi:[1,0]
	v_pk_mul_f32 v[2:3], v[2:3], v[138:139] op_sel_hi:[1,0]
	v_pk_mul_f32 v[0:1], v[0:1], v[138:139] op_sel_hi:[1,0]
	v_pk_mul_f32 v[30:31], v[30:31], v[138:139] op_sel_hi:[1,0]
	v_pk_mul_f32 v[28:29], v[28:29], v[138:139] op_sel_hi:[1,0]
	v_pk_mul_f32 v[26:27], v[26:27], v[138:139] op_sel_hi:[1,0]
	v_pk_mul_f32 v[24:25], v[24:25], v[138:139] op_sel_hi:[1,0]
	v_pk_mul_f32 v[22:23], v[22:23], v[138:139] op_sel_hi:[1,0]
	v_pk_mul_f32 v[20:21], v[20:21], v[138:139] op_sel_hi:[1,0]
	v_pk_mul_f32 v[18:19], v[18:19], v[138:139] op_sel_hi:[1,0]
	v_pk_mul_f32 v[16:17], v[16:17], v[138:139] op_sel_hi:[1,0]
.LBB0_1485:
	v_sub_f32_e32 v32, v32, v243
	v_exp_f32_e32 v138, v32
	v_sub_f32_e32 v32, v33, v243
	v_exp_f32_e32 v139, v32
	v_sub_f32_e32 v32, v34, v243
	v_exp_f32_e32 v140, v32
	v_sub_f32_e32 v32, v35, v243
	v_exp_f32_e32 v141, v32
	v_sub_f32_e32 v32, v36, v243
	v_exp_f32_e32 v142, v32
	v_sub_f32_e32 v32, v37, v243
	v_exp_f32_e32 v143, v32
	v_sub_f32_e32 v32, v38, v243
	v_exp_f32_e32 v144, v32
	v_sub_f32_e32 v32, v39, v243
	v_exp_f32_e32 v145, v32
	v_sub_f32_e32 v32, v40, v243
	v_exp_f32_e32 v40, v32
	v_sub_f32_e32 v32, v41, v243
	v_exp_f32_e32 v41, v32
	v_sub_f32_e32 v32, v42, v243
	v_exp_f32_e32 v42, v32
	v_sub_f32_e32 v32, v43, v243
	v_exp_f32_e32 v43, v32
	v_sub_f32_e32 v32, v44, v243
	v_exp_f32_e32 v44, v32
	v_sub_f32_e32 v32, v45, v243
	v_exp_f32_e32 v45, v32
	v_sub_f32_e32 v32, v46, v243
	v_exp_f32_e32 v46, v32
	v_sub_f32_e32 v32, v47, v243
	v_exp_f32_e32 v47, v32
	v_cvt_pk_bf16_f32 v32, v138, v139
	v_add_f32_e32 v138, 0, v138
	v_add_f32_e32 v138, v139, v138
	v_add_f32_e32 v138, v140, v138
	v_add_f32_e32 v138, v141, v138
	v_add_f32_e32 v138, v142, v138
	v_add_f32_e32 v138, v143, v138
	v_add_f32_e32 v138, v144, v138
	v_add_f32_e32 v138, v145, v138
	v_cvt_pk_bf16_f32 v36, v40, v41
	v_add_f32_e32 v40, v40, v138
	v_add_f32_e32 v40, v41, v40
	v_add_f32_e32 v40, v42, v40
	v_add_f32_e32 v40, v43, v40
	v_add_f32_e32 v40, v44, v40
	v_add_f32_e32 v40, v45, v40
	v_cvt_pk_bf16_f32 v33, v140, v141
	v_cvt_pk_bf16_f32 v34, v142, v143
	v_cvt_pk_bf16_f32 v35, v144, v145
	v_add_f32_e32 v40, v46, v40
	v_cvt_pk_bf16_f32 v37, v42, v43
	v_cvt_pk_bf16_f32 v38, v44, v45
	v_cvt_pk_bf16_f32 v39, v46, v47
	v_add_f32_e32 v138, v47, v40
	v_add_u32_e32 v139, 0x480, v118
	v_add_u32_e32 v140, 64, v118
	v_add_u32_e32 v141, 0x4c0, v118
	ds_read_b64_tr_b16 v[44:45], v118
	ds_read_b64_tr_b16 v[46:47], v139
	ds_read_b64_tr_b16 v[40:41], v140
	ds_read_b64_tr_b16 v[42:43], v141
	s_waitcnt lgkmcnt(0)
	v_add_f32_e32 v245, v245, v138
	v_mfma_f32_32x32x16_bf16 v[16:31], v[40:43], v[32:35], v[16:31]
	v_readlane_b32 s16, v253, 45
	v_readlane_b32 s17, v253, 46
	v_mfma_f32_32x32x16_bf16 v[0:15], v[44:47], v[32:35], v[0:15]
	v_add_u32_e32 v44, 0x900, v118
	v_add_u32_e32 v45, 0xd80, v118
	v_add_u32_e32 v46, 0x940, v118
	v_add_u32_e32 v47, 0xdc0, v118
	ds_read_b64_tr_b16 v[40:41], v44
	ds_read_b64_tr_b16 v[42:43], v45
	ds_read_b64_tr_b16 v[32:33], v46
	ds_read_b64_tr_b16 v[34:35], v47
	s_waitcnt lgkmcnt(0)
	s_nop 0
	v_mfma_f32_32x32x16_bf16 v[16:31], v[32:35], v[36:39], v[16:31]
	ds_read_b128 v[32:35], v202
	ds_read_b128 v[138:141], v202 offset:32
	v_mfma_f32_32x32x16_bf16 v[0:15], v[40:43], v[36:39], v[0:15]
	s_waitcnt lgkmcnt(1)
	v_mfma_f32_32x32x16_bf16 v[32:47], v[32:35], v[104:107], 0
	s_waitcnt lgkmcnt(0)
	v_mfma_f32_32x32x16_bf16 v[32:47], v[138:141], v[108:111], v[32:47]
	ds_read_b128 v[138:141], v202 offset:64
	s_waitcnt lgkmcnt(0)
	v_mfma_f32_32x32x16_bf16 v[32:47], v[138:141], v[100:103], v[32:47]
	ds_read_b128 v[138:141], v202 offset:96
	s_waitcnt lgkmcnt(0)
; DI f32x16 mfma32(bf16x8 a, bf16x8 b, f32x16 c) { return __builtin_amdgcn_mfma_f32_32x32x16_bf16(a, b, c, 0, 0, 0); }
; DI float max3f(float a, float b, float c) { float d; asm("v_max3_f32 %0, %1, %2, %3" : "=v"(d) : "v"(a), "v"(b), "v"(c)); return d; }
; DI void attn_d6_loop(char* lds, const Params& p, int layer, int first, int stride, int total) {
;     ...
;       for (int ks = 0; ks < 4; ++ks) S = mfma32(*(const bf16x8*)(kb + ks * 32), qf[ks], S);
;       const int rel0 = key0 + 4 * lh - qrow;
; #pragma unroll
;       for (int r2 = 0; r2 < 16; ++r2) { const int rel = rel0 + (r2 & 3) + 8 * (r2 >> 2), v = qrow + rel;
;         const bool ok = (rel >= -64) && (rel <= 64) && (v >= 0) && (v < L); S[r2] = ok ? fmaf(-slope2, fabsf((float)rel), S[r2]) : -1e30f; }
;       float mx = S[0];
; #pragma unroll
;       for (int r2 = 1; r2 < 15; r2 += 2) mx = max3f(mx, S[r2], S[r2 + 1]);
;       mx = fmaxf(mx, S[15]);
;       if (__any(mx > m + 8.f)) {
;         mx = fmaxf(mx, __shfl_xor(mx, 32));
;         const float mnew = fmaxf(m, mx);
;         const float al = __builtin_amdgcn_exp2f(m - mnew); l *= al; O0 *= al; O1 *= al;
;         m = mnew;
;       }
	v_mfma_f32_32x32x16_bf16 v[32:47], v[138:141], v[96:99], v[32:47]
	v_add_u32_e32 v138, v131, v119
	v_cmp_lt_i32_e32 vcc, -1, v138
	s_and_b64 s[74:75], s[16:17], vcc
	v_cmp_gt_i32_e32 vcc, s1, v138
	v_cvt_f32_i32_e32 v138, v119
	s_and_b64 vcc, s[74:75], vcc
	v_readlane_b32 s16, v253, 47
	v_readlane_b32 s17, v253, 48
	s_nop 3
	v_fma_f32 v32, v129, |v138|, v32
	v_add_u32_e32 v138, v131, v167
	v_cndmask_b32_e32 v32, v241, v32, vcc
	v_cmp_lt_i32_e32 vcc, -1, v138
	s_and_b64 s[74:75], s[16:17], vcc
	v_cmp_gt_i32_e32 vcc, s1, v138
	v_cvt_f32_i32_e32 v138, v167
	s_and_b64 vcc, s[74:75], vcc
	v_readlane_b32 s16, v253, 49
	v_readlane_b32 s17, v253, 50
	v_fma_f32 v33, v129, |v138|, v33
	v_add_u32_e32 v138, v131, v121
	v_cndmask_b32_e32 v33, v241, v33, vcc
	v_cmp_lt_i32_e32 vcc, -1, v138
	s_and_b64 s[74:75], s[16:17], vcc
	v_cmp_gt_i32_e32 vcc, s1, v138
	v_cvt_f32_i32_e32 v138, v121
	s_and_b64 vcc, s[74:75], vcc
	v_readlane_b32 s16, v253, 51
	v_readlane_b32 s17, v253, 52
	v_fma_f32 v34, v129, |v138|, v34
	v_add_u32_e32 v138, v131, v123
	v_cndmask_b32_e32 v34, v241, v34, vcc
	v_cmp_lt_i32_e32 vcc, -1, v138
	s_and_b64 s[74:75], s[16:17], vcc
	v_cmp_gt_i32_e32 vcc, s1, v138
	v_cvt_f32_i32_e32 v138, v123
	s_and_b64 vcc, s[74:75], vcc
	v_readlane_b32 s16, v253, 53
	v_readlane_b32 s17, v253, 54
	v_fma_f32 v35, v129, |v138|, v35
	v_add_u32_e32 v138, v131, v125
	v_cndmask_b32_e32 v35, v241, v35, vcc
	v_cmp_lt_i32_e32 vcc, -1, v138
	s_and_b64 s[74:75], s[16:17], vcc
	v_cmp_gt_i32_e32 vcc, s1, v138
	v_cvt_f32_i32_e32 v138, v125
	s_and_b64 vcc, s[74:75], vcc
	v_readlane_b32 s16, v253, 55
	v_readlane_b32 s17, v253, 56
	v_fma_f32 v36, v129, |v138|, v36
	v_add_u32_e32 v138, v131, v127
	v_cndmask_b32_e32 v36, v241, v36, vcc
	v_cmp_lt_i32_e32 vcc, -1, v138
	s_and_b64 s[74:75], s[16:17], vcc
	v_cmp_gt_i32_e32 vcc, s1, v138
	v_cvt_f32_i32_e32 v138, v127
	s_and_b64 vcc, s[74:75], vcc
	v_readlane_b32 s16, v253, 57
	v_readlane_b32 s17, v253, 58
	v_fma_f32 v37, v129, |v138|, v37
	v_add_u32_e32 v138, v131, v168
	v_cndmask_b32_e32 v37, v241, v37, vcc
	v_cmp_lt_i32_e32 vcc, -1, v138
	s_and_b64 s[74:75], s[16:17], vcc
	v_cmp_gt_i32_e32 vcc, s1, v138
	v_cvt_f32_i32_e32 v138, v168
	s_and_b64 vcc, s[74:75], vcc
	v_readlane_b32 s16, v253, 59
	v_readlane_b32 s17, v253, 60
	v_fma_f32 v38, v129, |v138|, v38
	v_add_u32_e32 v138, v131, v169
	v_cndmask_b32_e32 v38, v241, v38, vcc
	v_cmp_lt_i32_e32 vcc, -1, v138
	s_and_b64 s[74:75], s[16:17], vcc
	v_cmp_gt_i32_e32 vcc, s1, v138
	v_cvt_f32_i32_e32 v138, v169
	s_and_b64 vcc, s[74:75], vcc
	v_readlane_b32 s16, v253, 61
	v_readlane_b32 s17, v253, 62
	v_fma_f32 v39, v129, |v138|, v39
	v_add_u32_e32 v138, v131, v170
	v_cndmask_b32_e32 v39, v241, v39, vcc
	v_cmp_lt_i32_e32 vcc, -1, v138
	s_and_b64 s[74:75], s[16:17], vcc
	v_cmp_gt_i32_e32 vcc, s1, v138
	v_cvt_f32_i32_e32 v138, v170
	s_and_b64 vcc, s[74:75], vcc
	v_readlane_b32 s16, v253, 63
	v_readlane_b32 s17, v254, 0
	v_fma_f32 v40, v129, |v138|, v40
	v_add_u32_e32 v138, v131, v171
	v_cndmask_b32_e32 v40, v241, v40, vcc
	v_cmp_lt_i32_e32 vcc, -1, v138
	s_and_b64 s[74:75], s[16:17], vcc
	v_cmp_gt_i32_e32 vcc, s1, v138
	v_cvt_f32_i32_e32 v138, v171
	s_and_b64 vcc, s[74:75], vcc
	v_readlane_b32 s16, v254, 1
	v_readlane_b32 s17, v254, 2
	v_fma_f32 v41, v129, |v138|, v41
	v_add_u32_e32 v138, v131, v172
	v_cndmask_b32_e32 v41, v241, v41, vcc
	v_cmp_lt_i32_e32 vcc, -1, v138
	s_and_b64 s[74:75], s[16:17], vcc
	v_cmp_gt_i32_e32 vcc, s1, v138
	v_cvt_f32_i32_e32 v138, v172
	s_and_b64 vcc, s[74:75], vcc
	v_readlane_b32 s16, v254, 3
	v_readlane_b32 s17, v254, 4
	v_fma_f32 v42, v129, |v138|, v42
	v_add_u32_e32 v138, v131, v173
	v_cndmask_b32_e32 v42, v241, v42, vcc
	v_cmp_lt_i32_e32 vcc, -1, v138
	s_and_b64 s[74:75], s[16:17], vcc
	v_cmp_gt_i32_e32 vcc, s1, v138
	v_cvt_f32_i32_e32 v138, v173
	s_and_b64 vcc, s[74:75], vcc
	v_readlane_b32 s16, v254, 5
	v_readlane_b32 s17, v254, 6
	v_fma_f32 v43, v129, |v138|, v43
	v_add_u32_e32 v138, v131, v174
	v_cndmask_b32_e32 v43, v241, v43, vcc
	v_cmp_lt_i32_e32 vcc, -1, v138
	s_and_b64 s[74:75], s[16:17], vcc
	v_cmp_gt_i32_e32 vcc, s1, v138
	v_cvt_f32_i32_e32 v138, v174
	s_and_b64 vcc, s[74:75], vcc
	v_readlane_b32 s16, v254, 7
	v_readlane_b32 s17, v254, 8
	v_fma_f32 v44, v129, |v138|, v44
	v_add_u32_e32 v138, v131, v175
	v_cndmask_b32_e32 v44, v241, v44, vcc
	v_cmp_lt_i32_e32 vcc, -1, v138
	s_and_b64 s[74:75], s[16:17], vcc
	v_cmp_gt_i32_e32 vcc, s1, v138
	v_cvt_f32_i32_e32 v138, v175
	s_and_b64 vcc, s[74:75], vcc
	v_readlane_b32 s16, v254, 9
	v_readlane_b32 s17, v254, 10
	v_fma_f32 v45, v129, |v138|, v45
	v_add_u32_e32 v138, v131, v176
	v_cndmask_b32_e32 v45, v241, v45, vcc
	v_cmp_lt_i32_e32 vcc, -1, v138
	s_and_b64 s[74:75], s[16:17], vcc
	v_cmp_gt_i32_e32 vcc, s1, v138
	v_cvt_f32_i32_e32 v138, v176
	s_and_b64 vcc, s[74:75], vcc
	v_readlane_b32 s16, v254, 11
	v_readlane_b32 s17, v254, 12
	v_fma_f32 v46, v129, |v138|, v46
	v_add_u32_e32 v138, v131, v177
	v_cndmask_b32_e32 v46, v241, v46, vcc
	v_cmp_lt_i32_e32 vcc, -1, v138
	s_and_b64 s[74:75], s[16:17], vcc
	v_cmp_gt_i32_e32 vcc, s1, v138
	v_cvt_f32_i32_e32 v138, v177
	s_and_b64 vcc, s[74:75], vcc
	v_fma_f32 v47, v129, |v138|, v47
	v_max3_f32 v138, v32, v33, v34
	v_cndmask_b32_e32 v47, v241, v47, vcc
	v_max3_f32 v138, v138, v35, v36
	v_max3_f32 v138, v138, v37, v38
	v_max3_f32 v138, v138, v39, v40
	v_max3_f32 v138, v138, v41, v42
	v_max3_f32 v138, v138, v43, v44
	v_max3_f32 v138, v138, v45, v46
	v_max_f32_e32 v138, v138, v138
	v_max_f32_e32 v246, v138, v47
	v_cmp_gt_f32_e32 vcc, v246, v244
	s_cbranch_vccz .LBB0_1487
	v_cmp_lt_i32_e32 vcc, v209, v208
	s_nop 1
	v_cndmask_b32_e32 v138, v207, v209, vcc
	v_lshlrev_b32_e32 v138, 2, v138
	ds_bpermute_b32 v138, v138, v246
	s_waitcnt lgkmcnt(0)
	v_max3_f32 v139, v243, v246, v138
	v_sub_f32_e32 v138, v243, v139
	v_exp_f32_e32 v138, v138
	v_add_f32_e32 v244, 0x41000000, v139
	v_mov_b32_e32 v243, v139
	v_mul_f32_e32 v245, v245, v138
	v_pk_mul_f32 v[14:15], v[14:15], v[138:139] op_sel_hi:[1,0]
	v_pk_mul_f32 v[12:13], v[12:13], v[138:139] op_sel_hi:[1,0]
	v_pk_mul_f32 v[10:11], v[10:11], v[138:139] op_sel_hi:[1,0]
	v_pk_mul_f32 v[8:9], v[8:9], v[138:139] op_sel_hi:[1,0]
	v_pk_mul_f32 v[6:7], v[6:7], v[138:139] op_sel_hi:[1,0]
	v_pk_mul_f32 v[4:5], v[4:5], v[138:139] op_sel_hi:[1,0]
	v_pk_mul_f32 v[2:3], v[2:3], v[138:139] op_sel_hi:[1,0]
	v_pk_mul_f32 v[0:1], v[0:1], v[138:139] op_sel_hi:[1,0]
	v_pk_mul_f32 v[30:31], v[30:31], v[138:139] op_sel_hi:[1,0]
	v_pk_mul_f32 v[28:29], v[28:29], v[138:139] op_sel_hi:[1,0]
	v_pk_mul_f32 v[26:27], v[26:27], v[138:139] op_sel_hi:[1,0]
	v_pk_mul_f32 v[24:25], v[24:25], v[138:139] op_sel_hi:[1,0]
	v_pk_mul_f32 v[22:23], v[22:23], v[138:139] op_sel_hi:[1,0]
	v_pk_mul_f32 v[20:21], v[20:21], v[138:139] op_sel_hi:[1,0]
	v_pk_mul_f32 v[18:19], v[18:19], v[138:139] op_sel_hi:[1,0]
	v_pk_mul_f32 v[16:17], v[16:17], v[138:139] op_sel_hi:[1,0]
; DI unsigned pk2(float a, float b) { f32x2 v = {a, b}; bf2_t r = __builtin_convertvector(v, bf2_t); return __builtin_bit_cast(unsigned, r); }
; DI f32x16 mfma32(bf16x8 a, bf16x8 b, f32x16 c) { return __builtin_amdgcn_mfma_f32_32x32x16_bf16(a, b, c, 0, 0, 0); }
; DI void attn_d6_loop(char* lds, const Params& p, int layer, int first, int stride, int total) {
;     ...
;       const char* kb = lds + (64 * c + 32 * hf + lr) * KST + lh * 16;
; #pragma unroll
;       for (int ks = 0; ks < 4; ++ks) S = mfma32(*(const bf16x8*)(kb + ks * 32), qf[ks], S);
;       const int rel0 = key0 + 4 * lh - qrow;
; #pragma unroll
;       for (int r2 = 0; r2 < 16; ++r2) { const int rel = rel0 + (r2 & 3) + 8 * (r2 >> 2), v = qrow + rel;
;         const bool ok = (rel >= -64) && (rel <= 64) && (v >= 0) && (v < L); S[r2] = ok ? fmaf(-slope2, fabsf((float)rel), S[r2]) : -1e30f; }
;     ...
;       float ps = 0.f;
; #pragma unroll
;       for (int r2 = 0; r2 < 16; ++r2) { S[r2] = __builtin_amdgcn_exp2f(S[r2] - m); ps += S[r2]; }
;       l += ps;
;       bf16x8 pf[2];
; #pragma unroll
;       for (int s2 = 0; s2 < 2; ++s2) { u32x4 w; w[0] = pk2(S[8 * s2], S[8 * s2 + 1]); w[1] = pk2(S[8 * s2 + 2], S[8 * s2 + 3]); w[2] = pk2(S[8 * s2 + 4], S[8 * s2 + 5]); w[3] = pk2(S[8 * s2 + 6], S[8 * s2 + 7]);
;         pf[s2] = __builtin_bit_cast(bf16x8, w); }
;       { const int g = lane >> 4, i16 = lane & 15;
;         const unsigned vbase = (unsigned)(size_t)(lds + VOFF) + (unsigned)((64 * c + 32 * hf + 4 * (g >> 1) + (i16 >> 2)) * KST + ((g & 1) * 16 + 4 * (i16 & 3)) * 2);
; #pragma unroll
;         for (int s2 = 0; s2 < 2; ++s2) {
;           s16x4 l0, h0, l1, h1;
;           const unsigned a0 = vbase + (unsigned)(16 * s2 * KST), a1 = a0 + 8u * KST, a2 = a0 + 64u, a3 = a1 + 64u;
;           asm volatile("ds_read_b64_tr_b16 %0, %4\n\tds_read_b64_tr_b16 %1, %5\n\tds_read_b64_tr_b16 %2, %6\n\tds_read_b64_tr_b16 %3, %7\n\ts_waitcnt lgkmcnt(0)"
;                        : "=&v"(l0), "=&v"(h0), "=&v"(l1), "=&v"(h1) : "v"(a0), "v"(a1), "v"(a2), "v"(a3) : "memory");
;           O0 = mfma32(__builtin_shufflevector(l0, h0, 0, 1, 2, 3, 4, 5, 6, 7), pf[s2], O0);
;           O1 = mfma32(__builtin_shufflevector(l1, h1, 0, 1, 2, 3, 4, 5, 6, 7), pf[s2], O1);
;         } }
.LBB0_1487:
	v_sub_f32_e32 v32, v32, v243
	v_exp_f32_e32 v138, v32
	v_sub_f32_e32 v32, v33, v243
	v_exp_f32_e32 v139, v32
	v_sub_f32_e32 v32, v34, v243
	v_exp_f32_e32 v140, v32
	v_sub_f32_e32 v32, v35, v243
	v_exp_f32_e32 v141, v32
	v_sub_f32_e32 v32, v36, v243
	v_exp_f32_e32 v142, v32
	v_sub_f32_e32 v32, v37, v243
	v_exp_f32_e32 v143, v32
	v_sub_f32_e32 v32, v38, v243
	v_exp_f32_e32 v144, v32
	v_sub_f32_e32 v32, v39, v243
	v_exp_f32_e32 v145, v32
	v_sub_f32_e32 v32, v40, v243
	v_exp_f32_e32 v40, v32
	v_sub_f32_e32 v32, v41, v243
	v_exp_f32_e32 v41, v32
	v_sub_f32_e32 v32, v42, v243
	v_exp_f32_e32 v42, v32
	v_sub_f32_e32 v32, v43, v243
	v_exp_f32_e32 v43, v32
	v_sub_f32_e32 v32, v44, v243
	v_exp_f32_e32 v44, v32
	v_sub_f32_e32 v32, v45, v243
	v_exp_f32_e32 v45, v32
	v_sub_f32_e32 v32, v46, v243
	v_exp_f32_e32 v46, v32
	v_sub_f32_e32 v32, v47, v243
	v_exp_f32_e32 v47, v32
	v_cvt_pk_bf16_f32 v32, v138, v139
	v_add_f32_e32 v138, 0, v138
	v_add_f32_e32 v138, v139, v138
	v_add_f32_e32 v138, v140, v138
	v_add_f32_e32 v138, v141, v138
	v_add_f32_e32 v138, v142, v138
	v_add_f32_e32 v138, v143, v138
	v_add_f32_e32 v138, v144, v138
	v_add_f32_e32 v138, v145, v138
	v_cvt_pk_bf16_f32 v36, v40, v41
	v_add_f32_e32 v40, v40, v138
	v_add_f32_e32 v40, v41, v40
	v_add_f32_e32 v40, v42, v40
	v_add_f32_e32 v40, v43, v40
	v_add_f32_e32 v40, v44, v40
	v_add_f32_e32 v40, v45, v40
	v_cvt_pk_bf16_f32 v33, v140, v141
	v_cvt_pk_bf16_f32 v34, v142, v143
	v_cvt_pk_bf16_f32 v35, v144, v145
	v_add_f32_e32 v40, v46, v40
	v_cvt_pk_bf16_f32 v37, v42, v43
	v_cvt_pk_bf16_f32 v38, v44, v45
	v_cvt_pk_bf16_f32 v39, v46, v47
	v_add_f32_e32 v138, v47, v40
	v_add_u32_e32 v139, 0x480, v120
	v_add_u32_e32 v140, 64, v120
	v_add_u32_e32 v141, 0x4c0, v120
	ds_read_b64_tr_b16 v[44:45], v120
	ds_read_b64_tr_b16 v[46:47], v139
	ds_read_b64_tr_b16 v[40:41], v140
	ds_read_b64_tr_b16 v[42:43], v141
	s_waitcnt lgkmcnt(0)
	v_add_f32_e32 v245, v245, v138
	v_mfma_f32_32x32x16_bf16 v[16:31], v[40:43], v[32:35], v[16:31]
	v_readlane_b32 s16, v254, 13
	v_readlane_b32 s17, v254, 14
	v_mfma_f32_32x32x16_bf16 v[0:15], v[44:47], v[32:35], v[0:15]
	v_add_u32_e32 v44, 0x900, v120
	v_add_u32_e32 v45, 0xd80, v120
	v_add_u32_e32 v46, 0x940, v120
	v_add_u32_e32 v47, 0xdc0, v120
	ds_read_b64_tr_b16 v[40:41], v44
	ds_read_b64_tr_b16 v[42:43], v45
	ds_read_b64_tr_b16 v[32:33], v46
	ds_read_b64_tr_b16 v[34:35], v47
	s_waitcnt lgkmcnt(0)
	s_nop 0
	v_mfma_f32_32x32x16_bf16 v[16:31], v[32:35], v[36:39], v[16:31]
	ds_read_b128 v[32:35], v203
	ds_read_b128 v[138:141], v203 offset:32
	v_mfma_f32_32x32x16_bf16 v[0:15], v[40:43], v[36:39], v[0:15]
	s_waitcnt lgkmcnt(1)
	v_mfma_f32_32x32x16_bf16 v[32:47], v[32:35], v[104:107], 0
	s_waitcnt lgkmcnt(0)
	v_mfma_f32_32x32x16_bf16 v[32:47], v[138:141], v[108:111], v[32:47]
	ds_read_b128 v[138:141], v203 offset:64
	s_waitcnt lgkmcnt(0)
	v_mfma_f32_32x32x16_bf16 v[32:47], v[138:141], v[100:103], v[32:47]
	ds_read_b128 v[138:141], v203 offset:96
	s_waitcnt lgkmcnt(0)
	v_mfma_f32_32x32x16_bf16 v[32:47], v[138:141], v[96:99], v[32:47]
	v_add_u32_e32 v138, v131, v178
	v_cmp_lt_i32_e32 vcc, -1, v138
	s_and_b64 s[74:75], s[16:17], vcc
	v_cmp_gt_i32_e32 vcc, s1, v138
	v_cvt_f32_i32_e32 v138, v178
	s_and_b64 vcc, s[74:75], vcc
	v_readlane_b32 s16, v254, 15
	v_readlane_b32 s17, v254, 16
	s_nop 3
	v_fma_f32 v32, v129, |v138|, v32
	v_add_u32_e32 v138, v131, v179
	v_cndmask_b32_e32 v32, v241, v32, vcc
	v_cmp_lt_i32_e32 vcc, -1, v138
	s_and_b64 s[74:75], s[16:17], vcc
	v_cmp_gt_i32_e32 vcc, s1, v138
	v_cvt_f32_i32_e32 v138, v179
	s_and_b64 vcc, s[74:75], vcc
	v_readlane_b32 s16, v254, 17
	v_readlane_b32 s17, v254, 18
	v_fma_f32 v33, v129, |v138|, v33
	v_add_u32_e32 v138, v131, v180
	v_cndmask_b32_e32 v33, v241, v33, vcc
	v_cmp_lt_i32_e32 vcc, -1, v138
	s_and_b64 s[74:75], s[16:17], vcc
	v_cmp_gt_i32_e32 vcc, s1, v138
	v_cvt_f32_i32_e32 v138, v180
	s_and_b64 vcc, s[74:75], vcc
	v_readlane_b32 s16, v254, 19
	v_readlane_b32 s17, v254, 20
	v_fma_f32 v34, v129, |v138|, v34
	v_add_u32_e32 v138, v131, v181
	v_cndmask_b32_e32 v34, v241, v34, vcc
	v_cmp_lt_i32_e32 vcc, -1, v138
	s_and_b64 s[74:75], s[16:17], vcc
	v_cmp_gt_i32_e32 vcc, s1, v138
	v_cvt_f32_i32_e32 v138, v181
	s_and_b64 vcc, s[74:75], vcc
	v_readlane_b32 s16, v254, 21
	v_readlane_b32 s17, v254, 22
	v_fma_f32 v35, v129, |v138|, v35
	v_add_u32_e32 v138, v131, v182
	v_cndmask_b32_e32 v35, v241, v35, vcc
	v_cmp_lt_i32_e32 vcc, -1, v138
	s_and_b64 s[74:75], s[16:17], vcc
	v_cmp_gt_i32_e32 vcc, s1, v138
	v_cvt_f32_i32_e32 v138, v182
	s_and_b64 vcc, s[74:75], vcc
	v_readlane_b32 s16, v254, 23
	v_readlane_b32 s17, v254, 24
	v_fma_f32 v36, v129, |v138|, v36
	v_add_u32_e32 v138, v131, v183
	v_cndmask_b32_e32 v36, v241, v36, vcc
	v_cmp_lt_i32_e32 vcc, -1, v138
	s_and_b64 s[74:75], s[16:17], vcc
	v_cmp_gt_i32_e32 vcc, s1, v138
	v_cvt_f32_i32_e32 v138, v183
	s_and_b64 vcc, s[74:75], vcc
	v_readlane_b32 s16, v254, 25
	v_readlane_b32 s17, v254, 26
	v_fma_f32 v37, v129, |v138|, v37
	v_add_u32_e32 v138, v131, v184
	v_cndmask_b32_e32 v37, v241, v37, vcc
	v_cmp_lt_i32_e32 vcc, -1, v138
	s_and_b64 s[74:75], s[16:17], vcc
	v_cmp_gt_i32_e32 vcc, s1, v138
	v_cvt_f32_i32_e32 v138, v184
	s_and_b64 vcc, s[74:75], vcc
	v_readlane_b32 s16, v254, 27
	v_readlane_b32 s17, v254, 28
	v_fma_f32 v38, v129, |v138|, v38
	v_add_u32_e32 v138, v131, v185
	v_cndmask_b32_e32 v38, v241, v38, vcc
	v_cmp_lt_i32_e32 vcc, -1, v138
	s_and_b64 s[74:75], s[16:17], vcc
	v_cmp_gt_i32_e32 vcc, s1, v138
	v_cvt_f32_i32_e32 v138, v185
	s_and_b64 vcc, s[74:75], vcc
	v_readlane_b32 s16, v254, 29
	v_readlane_b32 s17, v254, 30
	v_fma_f32 v39, v129, |v138|, v39
	v_add_u32_e32 v138, v131, v186
; DI unsigned pk2(float a, float b) { f32x2 v = {a, b}; bf2_t r = __builtin_convertvector(v, bf2_t); return __builtin_bit_cast(unsigned, r); }
; DI float max3f(float a, float b, float c) { float d; asm("v_max3_f32 %0, %1, %2, %3" : "=v"(d) : "v"(a), "v"(b), "v"(c)); return d; }
; DI void attn_d6_loop(char* lds, const Params& p, int layer, int first, int stride, int total) {
;     ...
;       for (int r2 = 0; r2 < 16; ++r2) { const int rel = rel0 + (r2 & 3) + 8 * (r2 >> 2), v = qrow + rel;
;         const bool ok = (rel >= -64) && (rel <= 64) && (v >= 0) && (v < L); S[r2] = ok ? fmaf(-slope2, fabsf((float)rel), S[r2]) : -1e30f; }
;       float mx = S[0];
; #pragma unroll
;       for (int r2 = 1; r2 < 15; r2 += 2) mx = max3f(mx, S[r2], S[r2 + 1]);
;       mx = fmaxf(mx, S[15]);
;       if (__any(mx > m + 8.f)) {
;         mx = fmaxf(mx, __shfl_xor(mx, 32));
;         const float mnew = fmaxf(m, mx);
;         const float al = __builtin_amdgcn_exp2f(m - mnew); l *= al; O0 *= al; O1 *= al;
;         m = mnew;
;       }
;       float ps = 0.f;
; #pragma unroll
;       for (int r2 = 0; r2 < 16; ++r2) { S[r2] = __builtin_amdgcn_exp2f(S[r2] - m); ps += S[r2]; }
;       l += ps;
;       bf16x8 pf[2];
; #pragma unroll
;       for (int s2 = 0; s2 < 2; ++s2) { u32x4 w; w[0] = pk2(S[8 * s2], S[8 * s2 + 1]); w[1] = pk2(S[8 * s2 + 2], S[8 * s2 + 3]); w[2] = pk2(S[8 * s2 + 4], S[8 * s2 + 5]); w[3] = pk2(S[8 * s2 + 6], S[8 * s2 + 7]);
;         pf[s2] = __builtin_bit_cast(bf16x8, w); }
	v_cndmask_b32_e32 v39, v241, v39, vcc
	v_cmp_lt_i32_e32 vcc, -1, v138
	s_and_b64 s[74:75], s[16:17], vcc
	v_cmp_gt_i32_e32 vcc, s1, v138
	v_cvt_f32_i32_e32 v138, v186
	s_and_b64 vcc, s[74:75], vcc
	v_readlane_b32 s16, v255, 9
	v_readlane_b32 s17, v255, 10
	v_fma_f32 v40, v129, |v138|, v40
	v_add_u32_e32 v138, v131, v187
	v_cndmask_b32_e32 v40, v241, v40, vcc
	v_cmp_lt_i32_e32 vcc, -1, v138
	s_and_b64 s[74:75], s[16:17], vcc
	v_cmp_gt_i32_e32 vcc, s1, v138
	v_cvt_f32_i32_e32 v138, v187
	s_and_b64 vcc, s[74:75], vcc
	v_readlane_b32 s16, v253, 15
	v_readlane_b32 s17, v253, 16
	v_fma_f32 v41, v129, |v138|, v41
	v_add_u32_e32 v138, v131, v188
	v_cndmask_b32_e32 v41, v241, v41, vcc
	v_cmp_lt_i32_e32 vcc, -1, v138
	s_and_b64 s[74:75], s[16:17], vcc
	v_cmp_gt_i32_e32 vcc, s1, v138
	v_cvt_f32_i32_e32 v138, v188
	s_and_b64 vcc, s[74:75], vcc
	v_readlane_b32 s16, v253, 17
	v_readlane_b32 s17, v253, 18
	v_fma_f32 v42, v129, |v138|, v42
	v_add_u32_e32 v138, v131, v189
	v_cndmask_b32_e32 v42, v241, v42, vcc
	v_cmp_lt_i32_e32 vcc, -1, v138
	s_and_b64 s[74:75], s[16:17], vcc
	v_cmp_gt_i32_e32 vcc, s1, v138
	v_cvt_f32_i32_e32 v138, v189
	s_and_b64 vcc, s[74:75], vcc
	v_readlane_b32 s16, v253, 19
	v_readlane_b32 s17, v253, 20
	v_fma_f32 v43, v129, |v138|, v43
	v_add_u32_e32 v138, v131, v190
	v_cndmask_b32_e32 v43, v241, v43, vcc
	v_cmp_lt_i32_e32 vcc, -1, v138
	s_and_b64 s[74:75], s[16:17], vcc
	v_cmp_gt_i32_e32 vcc, s1, v138
	v_cvt_f32_i32_e32 v138, v190
	s_and_b64 vcc, s[74:75], vcc
	v_readlane_b32 s16, v253, 21
	v_readlane_b32 s17, v253, 22
	v_fma_f32 v44, v129, |v138|, v44
	v_add_u32_e32 v138, v131, v191
	v_cndmask_b32_e32 v44, v241, v44, vcc
	v_cmp_lt_i32_e32 vcc, -1, v138
	s_and_b64 s[74:75], s[16:17], vcc
	v_cmp_gt_i32_e32 vcc, s1, v138
	v_cvt_f32_i32_e32 v138, v191
	s_and_b64 vcc, s[74:75], vcc
	v_fma_f32 v45, v129, |v138|, v45
	v_add_u32_e32 v138, v131, v192
	v_cndmask_b32_e32 v45, v241, v45, vcc
	v_cmp_lt_i32_e32 vcc, -1, v138
	s_and_b64 s[74:75], s[4:5], vcc
	v_cmp_gt_i32_e32 vcc, s1, v138
	v_cvt_f32_i32_e32 v138, v192
	s_and_b64 vcc, s[74:75], vcc
	v_fma_f32 v46, v129, |v138|, v46
	v_add_u32_e32 v138, v131, v193
	v_cndmask_b32_e32 v46, v241, v46, vcc
	v_cmp_lt_i32_e32 vcc, -1, v138
	s_and_b64 s[74:75], s[76:77], vcc
	v_cmp_gt_i32_e32 vcc, s1, v138
	v_cvt_f32_i32_e32 v138, v193
	s_and_b64 vcc, s[74:75], vcc
	v_fma_f32 v47, v129, |v138|, v47
	v_max3_f32 v138, v32, v33, v34
	v_cndmask_b32_e32 v47, v241, v47, vcc
	v_max3_f32 v138, v138, v35, v36
	v_max3_f32 v138, v138, v37, v38
	v_max3_f32 v138, v138, v39, v40
	v_max3_f32 v138, v138, v41, v42
	v_max3_f32 v138, v138, v43, v44
	v_max3_f32 v138, v138, v45, v46
	v_max_f32_e32 v138, v138, v138
	v_max_f32_e32 v246, v138, v47
	v_cmp_gt_f32_e32 vcc, v246, v244
	s_cbranch_vccz .LBB0_1489
	v_cmp_lt_i32_e32 vcc, v209, v208
	s_nop 1
	v_cndmask_b32_e32 v138, v207, v209, vcc
	v_lshlrev_b32_e32 v138, 2, v138
	ds_bpermute_b32 v138, v138, v246
	s_waitcnt lgkmcnt(0)
	v_max3_f32 v139, v243, v246, v138
	v_sub_f32_e32 v138, v243, v139
	v_exp_f32_e32 v138, v138
	v_add_f32_e32 v244, 0x41000000, v139
	v_mov_b32_e32 v243, v139
	v_mul_f32_e32 v245, v245, v138
	v_pk_mul_f32 v[14:15], v[14:15], v[138:139] op_sel_hi:[1,0]
	v_pk_mul_f32 v[12:13], v[12:13], v[138:139] op_sel_hi:[1,0]
	v_pk_mul_f32 v[10:11], v[10:11], v[138:139] op_sel_hi:[1,0]
	v_pk_mul_f32 v[8:9], v[8:9], v[138:139] op_sel_hi:[1,0]
	v_pk_mul_f32 v[6:7], v[6:7], v[138:139] op_sel_hi:[1,0]
	v_pk_mul_f32 v[4:5], v[4:5], v[138:139] op_sel_hi:[1,0]
	v_pk_mul_f32 v[2:3], v[2:3], v[138:139] op_sel_hi:[1,0]
	v_pk_mul_f32 v[0:1], v[0:1], v[138:139] op_sel_hi:[1,0]
	v_pk_mul_f32 v[30:31], v[30:31], v[138:139] op_sel_hi:[1,0]
	v_pk_mul_f32 v[28:29], v[28:29], v[138:139] op_sel_hi:[1,0]
	v_pk_mul_f32 v[26:27], v[26:27], v[138:139] op_sel_hi:[1,0]
	v_pk_mul_f32 v[24:25], v[24:25], v[138:139] op_sel_hi:[1,0]
	v_pk_mul_f32 v[22:23], v[22:23], v[138:139] op_sel_hi:[1,0]
	v_pk_mul_f32 v[20:21], v[20:21], v[138:139] op_sel_hi:[1,0]
	v_pk_mul_f32 v[18:19], v[18:19], v[138:139] op_sel_hi:[1,0]
	v_pk_mul_f32 v[16:17], v[16:17], v[138:139] op_sel_hi:[1,0]
.LBB0_1489:
	v_sub_f32_e32 v32, v32, v243
	v_exp_f32_e32 v138, v32
	v_sub_f32_e32 v32, v33, v243
	v_exp_f32_e32 v139, v32
	v_sub_f32_e32 v32, v34, v243
	v_exp_f32_e32 v140, v32
	v_sub_f32_e32 v32, v35, v243
	v_exp_f32_e32 v141, v32
	v_sub_f32_e32 v32, v36, v243
	v_exp_f32_e32 v142, v32
	v_sub_f32_e32 v32, v37, v243
	v_exp_f32_e32 v143, v32
	v_sub_f32_e32 v32, v38, v243
	v_exp_f32_e32 v144, v32
	v_sub_f32_e32 v32, v39, v243
	v_exp_f32_e32 v145, v32
	v_sub_f32_e32 v32, v40, v243
	v_exp_f32_e32 v40, v32
	v_sub_f32_e32 v32, v41, v243
	v_exp_f32_e32 v41, v32
	v_sub_f32_e32 v32, v42, v243
	v_exp_f32_e32 v42, v32
	v_sub_f32_e32 v32, v43, v243
	v_exp_f32_e32 v43, v32
	v_sub_f32_e32 v32, v44, v243
	v_exp_f32_e32 v44, v32
	v_sub_f32_e32 v32, v45, v243
	v_exp_f32_e32 v45, v32
	v_sub_f32_e32 v32, v46, v243
	v_exp_f32_e32 v46, v32
	v_sub_f32_e32 v32, v47, v243
	v_exp_f32_e32 v47, v32
	v_cvt_pk_bf16_f32 v32, v138, v139
	v_add_f32_e32 v138, 0, v138
	v_add_f32_e32 v138, v139, v138
	v_add_f32_e32 v138, v140, v138
	v_add_f32_e32 v138, v141, v138
	v_add_f32_e32 v138, v142, v138
	v_add_f32_e32 v138, v143, v138
	v_add_f32_e32 v138, v144, v138
	v_add_f32_e32 v138, v145, v138
	v_cvt_pk_bf16_f32 v36, v40, v41
	v_add_f32_e32 v40, v40, v138
	v_add_f32_e32 v40, v41, v40
	v_add_f32_e32 v40, v42, v40
	v_add_f32_e32 v40, v43, v40
	v_add_f32_e32 v40, v44, v40
	v_add_f32_e32 v40, v45, v40
	v_cvt_pk_bf16_f32 v33, v140, v141
	v_cvt_pk_bf16_f32 v34, v142, v143
	v_cvt_pk_bf16_f32 v35, v144, v145
	v_add_f32_e32 v40, v46, v40
	v_cvt_pk_bf16_f32 v37, v42, v43
	v_cvt_pk_bf16_f32 v38, v44, v45
	v_cvt_pk_bf16_f32 v39, v46, v47
	v_add_f32_e32 v138, v47, v40
	v_add_u32_e32 v139, 0x480, v122
	v_add_u32_e32 v140, 64, v122
	v_add_u32_e32 v141, 0x4c0, v122
	ds_read_b64_tr_b16 v[44:45], v122
	ds_read_b64_tr_b16 v[46:47], v139
	ds_read_b64_tr_b16 v[40:41], v140
	ds_read_b64_tr_b16 v[42:43], v141
	s_waitcnt lgkmcnt(0)
; DI f32x16 mfma32(bf16x8 a, bf16x8 b, f32x16 c) { return __builtin_amdgcn_mfma_f32_32x32x16_bf16(a, b, c, 0, 0, 0); }
; DI void attn_d6_loop(char* lds, const Params& p, int layer, int first, int stride, int total) {
;     ...
;       for (int ks = 0; ks < 4; ++ks) S = mfma32(*(const bf16x8*)(kb + ks * 32), qf[ks], S);
;       const int rel0 = key0 + 4 * lh - qrow;
; #pragma unroll
;       for (int r2 = 0; r2 < 16; ++r2) { const int rel = rel0 + (r2 & 3) + 8 * (r2 >> 2), v = qrow + rel;
;         const bool ok = (rel >= -64) && (rel <= 64) && (v >= 0) && (v < L); S[r2] = ok ? fmaf(-slope2, fabsf((float)rel), S[r2]) : -1e30f; }
;       float mx = S[0];
; #pragma unroll
;       for (int r2 = 1; r2 < 15; r2 += 2) mx = max3f(mx, S[r2], S[r2 + 1]);
;       mx = fmaxf(mx, S[15]);
;       if (__any(mx > m + 8.f)) {
;         mx = fmaxf(mx, __shfl_xor(mx, 32));
;         const float mnew = fmaxf(m, mx);
;         const float al = __builtin_amdgcn_exp2f(m - mnew); l *= al; O0 *= al; O1 *= al;
;         m = mnew;
;       }
;       float ps = 0.f;
; #pragma unroll
;       for (int r2 = 0; r2 < 16; ++r2) { S[r2] = __builtin_amdgcn_exp2f(S[r2] - m); ps += S[r2]; }
;       l += ps;
;       bf16x8 pf[2];
; #pragma unroll
;       for (int s2 = 0; s2 < 2; ++s2) { u32x4 w; w[0] = pk2(S[8 * s2], S[8 * s2 + 1]); w[1] = pk2(S[8 * s2 + 2], S[8 * s2 + 3]); w[2] = pk2(S[8 * s2 + 4], S[8 * s2 + 5]); w[3] = pk2(S[8 * s2 + 6], S[8 * s2 + 7]);
;         pf[s2] = __builtin_bit_cast(bf16x8, w); }
;       { const int g = lane >> 4, i16 = lane & 15;
;         const unsigned vbase = (unsigned)(size_t)(lds + VOFF) + (unsigned)((64 * c + 32 * hf + 4 * (g >> 1) + (i16 >> 2)) * KST + ((g & 1) * 16 + 4 * (i16 & 3)) * 2);
; #pragma unroll
;         for (int s2 = 0; s2 < 2; ++s2) {
;           s16x4 l0, h0, l1, h1;
;           const unsigned a0 = vbase + (unsigned)(16 * s2 * KST), a1 = a0 + 8u * KST, a2 = a0 + 64u, a3 = a1 + 64u;
;           asm volatile("ds_read_b64_tr_b16 %0, %4\n\tds_read_b64_tr_b16 %1, %5\n\tds_read_b64_tr_b16 %2, %6\n\tds_read_b64_tr_b16 %3, %7\n\ts_waitcnt lgkmcnt(0)"
;                        : "=&v"(l0), "=&v"(h0), "=&v"(l1), "=&v"(h1) : "v"(a0), "v"(a1), "v"(a2), "v"(a3) : "memory");
;           O0 = mfma32(__builtin_shufflevector(l0, h0, 0, 1, 2, 3, 4, 5, 6, 7), pf[s2], O0);
;           O1 = mfma32(__builtin_shufflevector(l1, h1, 0, 1, 2, 3, 4, 5, 6, 7), pf[s2], O1);
;         } }
	v_add_f32_e32 v245, v245, v138
	v_mfma_f32_32x32x16_bf16 v[16:31], v[40:43], v[32:35], v[16:31]
	v_mfma_f32_32x32x16_bf16 v[0:15], v[44:47], v[32:35], v[0:15]
	v_add_u32_e32 v44, 0x900, v122
	v_add_u32_e32 v45, 0xd80, v122
	v_add_u32_e32 v46, 0x940, v122
	v_add_u32_e32 v47, 0xdc0, v122
	ds_read_b64_tr_b16 v[40:41], v44
	ds_read_b64_tr_b16 v[42:43], v45
	ds_read_b64_tr_b16 v[32:33], v46
	ds_read_b64_tr_b16 v[34:35], v47
	s_waitcnt lgkmcnt(0)
	s_nop 0
	v_mfma_f32_32x32x16_bf16 v[16:31], v[32:35], v[36:39], v[16:31]
	ds_read_b128 v[32:35], v204
	ds_read_b128 v[138:141], v204 offset:32
	v_mfma_f32_32x32x16_bf16 v[0:15], v[40:43], v[36:39], v[0:15]
	s_waitcnt lgkmcnt(1)
	v_mfma_f32_32x32x16_bf16 v[32:47], v[32:35], v[104:107], 0
	s_waitcnt lgkmcnt(0)
	v_mfma_f32_32x32x16_bf16 v[32:47], v[138:141], v[108:111], v[32:47]
	ds_read_b128 v[138:141], v204 offset:64
	s_waitcnt lgkmcnt(0)
	v_mfma_f32_32x32x16_bf16 v[32:47], v[138:141], v[100:103], v[32:47]
	ds_read_b128 v[138:141], v204 offset:96
	s_waitcnt lgkmcnt(0)
	v_mfma_f32_32x32x16_bf16 v[32:47], v[138:141], v[96:99], v[32:47]
	v_add_u32_e32 v138, v131, v194
	v_cmp_lt_i32_e32 vcc, -1, v138
	s_and_b64 s[74:75], s[6:7], vcc
	v_cmp_gt_i32_e32 vcc, s1, v138
	v_cvt_f32_i32_e32 v138, v194
	s_and_b64 vcc, s[74:75], vcc
	s_nop 5
	v_fma_f32 v32, v129, |v138|, v32
	v_add_u32_e32 v138, v131, v195
	v_cndmask_b32_e32 v32, v241, v32, vcc
	v_cmp_lt_i32_e32 vcc, -1, v138
	s_and_b64 s[74:75], s[8:9], vcc
	v_cmp_gt_i32_e32 vcc, s1, v138
	v_cvt_f32_i32_e32 v138, v195
	s_and_b64 vcc, s[74:75], vcc
	v_fma_f32 v33, v129, |v138|, v33
	v_add_u32_e32 v138, v131, v196
	v_cndmask_b32_e32 v33, v241, v33, vcc
	v_cmp_lt_i32_e32 vcc, -1, v138
	s_and_b64 s[74:75], s[10:11], vcc
	v_cmp_gt_i32_e32 vcc, s1, v138
	v_cvt_f32_i32_e32 v138, v196
	s_and_b64 vcc, s[74:75], vcc
	v_fma_f32 v34, v129, |v138|, v34
	v_add_u32_e32 v138, v131, v197
	v_cndmask_b32_e32 v34, v241, v34, vcc
	v_cmp_lt_i32_e32 vcc, -1, v138
	s_and_b64 s[74:75], s[44:45], vcc
	v_cmp_gt_i32_e32 vcc, s1, v138
	v_cvt_f32_i32_e32 v138, v197
	s_and_b64 vcc, s[74:75], vcc
	v_fma_f32 v35, v129, |v138|, v35
	v_add_u32_e32 v138, v131, v198
	v_cndmask_b32_e32 v35, v241, v35, vcc
	v_cmp_lt_i32_e32 vcc, -1, v138
	s_and_b64 s[74:75], s[46:47], vcc
	v_cmp_gt_i32_e32 vcc, s1, v138
	v_cvt_f32_i32_e32 v138, v198
	s_and_b64 vcc, s[74:75], vcc
	v_fma_f32 v36, v129, |v138|, v36
	v_add_u32_e32 v138, v131, v199
	v_cndmask_b32_e32 v36, v241, v36, vcc
	v_cmp_lt_i32_e32 vcc, -1, v138
	s_and_b64 s[74:75], s[48:49], vcc
	v_cmp_gt_i32_e32 vcc, s1, v138
	v_cvt_f32_i32_e32 v138, v199
	s_and_b64 vcc, s[74:75], vcc
	v_fma_f32 v37, v129, |v138|, v37
	v_add_u32_e32 v138, v131, v210
	v_cndmask_b32_e32 v37, v241, v37, vcc
	v_cmp_lt_i32_e32 vcc, -1, v138
	s_and_b64 s[74:75], s[50:51], vcc
	v_cmp_gt_i32_e32 vcc, s1, v138
	v_cvt_f32_i32_e32 v138, v210
	s_and_b64 vcc, s[74:75], vcc
	v_fma_f32 v38, v129, |v138|, v38
	v_add_u32_e32 v138, v131, v211
	v_cndmask_b32_e32 v38, v241, v38, vcc
	v_cmp_lt_i32_e32 vcc, -1, v138
	s_and_b64 s[74:75], s[52:53], vcc
	v_cmp_gt_i32_e32 vcc, s1, v138
	v_cvt_f32_i32_e32 v138, v211
	s_and_b64 vcc, s[74:75], vcc
	v_fma_f32 v39, v129, |v138|, v39
	v_add_u32_e32 v138, v131, v212
	v_cndmask_b32_e32 v39, v241, v39, vcc
	v_cmp_lt_i32_e32 vcc, -1, v138
	s_and_b64 s[74:75], s[54:55], vcc
	v_cmp_gt_i32_e32 vcc, s1, v138
	v_cvt_f32_i32_e32 v138, v212
	s_and_b64 vcc, s[74:75], vcc
	v_fma_f32 v40, v129, |v138|, v40
	v_add_u32_e32 v138, v131, v213
	v_cndmask_b32_e32 v40, v241, v40, vcc
	v_cmp_lt_i32_e32 vcc, -1, v138
	s_and_b64 s[74:75], s[56:57], vcc
	v_cmp_gt_i32_e32 vcc, s1, v138
	v_cvt_f32_i32_e32 v138, v213
	s_and_b64 vcc, s[74:75], vcc
	v_fma_f32 v41, v129, |v138|, v41
	v_add_u32_e32 v138, v131, v214
	v_cndmask_b32_e32 v41, v241, v41, vcc
	v_cmp_lt_i32_e32 vcc, -1, v138
	s_and_b64 s[74:75], s[58:59], vcc
	v_cmp_gt_i32_e32 vcc, s1, v138
	v_cvt_f32_i32_e32 v138, v214
	s_and_b64 vcc, s[74:75], vcc
	v_fma_f32 v42, v129, |v138|, v42
	v_add_u32_e32 v138, v131, v215
	v_cndmask_b32_e32 v42, v241, v42, vcc
	v_cmp_lt_i32_e32 vcc, -1, v138
	s_and_b64 s[74:75], s[60:61], vcc
	v_cmp_gt_i32_e32 vcc, s1, v138
	v_cvt_f32_i32_e32 v138, v215
	s_and_b64 vcc, s[74:75], vcc
	v_fma_f32 v43, v129, |v138|, v43
	v_add_u32_e32 v138, v131, v216
	v_cndmask_b32_e32 v43, v241, v43, vcc
	v_cmp_lt_i32_e32 vcc, -1, v138
	s_and_b64 s[74:75], s[62:63], vcc
	v_cmp_gt_i32_e32 vcc, s1, v138
	v_cvt_f32_i32_e32 v138, v216
	s_and_b64 vcc, s[74:75], vcc
	v_fma_f32 v44, v129, |v138|, v44
	v_add_u32_e32 v138, v131, v217
	v_cndmask_b32_e32 v44, v241, v44, vcc
	v_cmp_lt_i32_e32 vcc, -1, v138
	s_and_b64 s[74:75], s[64:65], vcc
	v_cmp_gt_i32_e32 vcc, s1, v138
	v_cvt_f32_i32_e32 v138, v217
	s_and_b64 vcc, s[74:75], vcc
	v_fma_f32 v45, v129, |v138|, v45
	v_add_u32_e32 v138, v131, v218
	v_cndmask_b32_e32 v45, v241, v45, vcc
	v_cmp_lt_i32_e32 vcc, -1, v138
	s_and_b64 s[74:75], s[66:67], vcc
	v_cmp_gt_i32_e32 vcc, s1, v138
	v_cvt_f32_i32_e32 v138, v218
	s_and_b64 vcc, s[74:75], vcc
	v_fma_f32 v46, v129, |v138|, v46
	v_add_u32_e32 v138, v131, v219
	v_cndmask_b32_e32 v46, v241, v46, vcc
	v_cmp_lt_i32_e32 vcc, -1, v138
	s_and_b64 s[74:75], s[68:69], vcc
	v_cmp_gt_i32_e32 vcc, s1, v138
	v_cvt_f32_i32_e32 v138, v219
	s_and_b64 vcc, s[74:75], vcc
	v_fma_f32 v47, v129, |v138|, v47
	v_max3_f32 v138, v32, v33, v34
	v_cndmask_b32_e32 v47, v241, v47, vcc
	v_max3_f32 v138, v138, v35, v36
	v_max3_f32 v138, v138, v37, v38
	v_max3_f32 v138, v138, v39, v40
	v_max3_f32 v138, v138, v41, v42
	v_max3_f32 v138, v138, v43, v44
	v_max3_f32 v138, v138, v45, v46
	v_max_f32_e32 v138, v138, v138
	v_max_f32_e32 v246, v138, v47
	v_cmp_gt_f32_e32 vcc, v246, v244
	s_cbranch_vccz .LBB0_1491
	v_cmp_lt_i32_e32 vcc, v209, v208
	s_nop 1
	v_cndmask_b32_e32 v138, v207, v209, vcc
	v_lshlrev_b32_e32 v138, 2, v138
	ds_bpermute_b32 v138, v138, v246
	s_waitcnt lgkmcnt(0)
	v_max3_f32 v139, v243, v246, v138
	v_sub_f32_e32 v138, v243, v139
	v_exp_f32_e32 v138, v138
	v_mov_b32_e32 v243, v139
	v_mul_f32_e32 v245, v245, v138
	v_pk_mul_f32 v[14:15], v[14:15], v[138:139] op_sel_hi:[1,0]
	v_pk_mul_f32 v[12:13], v[12:13], v[138:139] op_sel_hi:[1,0]
	v_pk_mul_f32 v[10:11], v[10:11], v[138:139] op_sel_hi:[1,0]
	v_pk_mul_f32 v[8:9], v[8:9], v[138:139] op_sel_hi:[1,0]
	v_pk_mul_f32 v[6:7], v[6:7], v[138:139] op_sel_hi:[1,0]
	v_pk_mul_f32 v[4:5], v[4:5], v[138:139] op_sel_hi:[1,0]
	v_pk_mul_f32 v[2:3], v[2:3], v[138:139] op_sel_hi:[1,0]
	v_pk_mul_f32 v[0:1], v[0:1], v[138:139] op_sel_hi:[1,0]
	v_pk_mul_f32 v[30:31], v[30:31], v[138:139] op_sel_hi:[1,0]
	v_pk_mul_f32 v[28:29], v[28:29], v[138:139] op_sel_hi:[1,0]
	v_pk_mul_f32 v[26:27], v[26:27], v[138:139] op_sel_hi:[1,0]
	v_pk_mul_f32 v[24:25], v[24:25], v[138:139] op_sel_hi:[1,0]
	v_pk_mul_f32 v[22:23], v[22:23], v[138:139] op_sel_hi:[1,0]
	v_pk_mul_f32 v[20:21], v[20:21], v[138:139] op_sel_hi:[1,0]
	v_pk_mul_f32 v[18:19], v[18:19], v[138:139] op_sel_hi:[1,0]
	v_pk_mul_f32 v[16:17], v[16:17], v[138:139] op_sel_hi:[1,0]
; DI void attn_d6_loop(char* lds, const Params& p, int layer, int first, int stride, int total) {
;     ...
;   for (int cc_ = 0; cc_ < 3; ++cc_) { const int c = (wid >> 1) + cc_;
; #pragma unroll
;     for (int hf = 0; hf < 2; ++hf) {
;       const bool skip = (hf == 0) ? ((wid & 1) && c == (wid >> 1)) : (!(wid & 1) && c == (wid >> 1) + 2);
;       if (skip) continue;
;       const int key0 = q0 - 64 + 64 * c + 32 * hf;
;       f32x16 S = zero16();
;       const char* kb = lds + (64 * c + 32 * hf + lr) * KST + lh * 16;
; #pragma unroll
;       for (int ks = 0; ks < 4; ++ks) S = mfma32(*(const bf16x8*)(kb + ks * 32), qf[ks], S);
;       const int rel0 = key0 + 4 * lh - qrow;
; #pragma unroll
;       for (int r2 = 0; r2 < 16; ++r2) { const int rel = rel0 + (r2 & 3) + 8 * (r2 >> 2), v = qrow + rel;
;         const bool ok = (rel >= -64) && (rel <= 64) && (v >= 0) && (v < L); S[r2] = ok ? fmaf(-slope2, fabsf((float)rel), S[r2]) : -1e30f; }
;       float mx = S[0];
; #pragma unroll
;       for (int r2 = 1; r2 < 15; r2 += 2) mx = max3f(mx, S[r2], S[r2 + 1]);
;       mx = fmaxf(mx, S[15]);
;       if (__any(mx > m + 8.f)) {
;         mx = fmaxf(mx, __shfl_xor(mx, 32));
;         const float mnew = fmaxf(m, mx);
;         const float al = __builtin_amdgcn_exp2f(m - mnew); l *= al; O0 *= al; O1 *= al;
;         m = mnew;
;       }
;       float ps = 0.f;
; #pragma unroll
;       for (int r2 = 0; r2 < 16; ++r2) { S[r2] = __builtin_amdgcn_exp2f(S[r2] - m); ps += S[r2]; }
;       l += ps;
;       bf16x8 pf[2];
; #pragma unroll
;       for (int s2 = 0; s2 < 2; ++s2) { u32x4 w; w[0] = pk2(S[8 * s2], S[8 * s2 + 1]); w[1] = pk2(S[8 * s2 + 2], S[8 * s2 + 3]); w[2] = pk2(S[8 * s2 + 4], S[8 * s2 + 5]); w[3] = pk2(S[8 * s2 + 6], S[8 * s2 + 7]);
;         pf[s2] = __builtin_bit_cast(bf16x8, w); }
;       { const int g = lane >> 4, i16 = lane & 15;
;         const unsigned vbase = (unsigned)(size_t)(lds + VOFF) + (unsigned)((64 * c + 32 * hf + 4 * (g >> 1) + (i16 >> 2)) * KST + ((g & 1) * 16 + 4 * (i16 & 3)) * 2);
; #pragma unroll
;         for (int s2 = 0; s2 < 2; ++s2) {
;           s16x4 l0, h0, l1, h1;
;           const unsigned a0 = vbase + (unsigned)(16 * s2 * KST), a1 = a0 + 8u * KST, a2 = a0 + 64u, a3 = a1 + 64u;
;           asm volatile("ds_read_b64_tr_b16 %0, %4\n\tds_read_b64_tr_b16 %1, %5\n\tds_read_b64_tr_b16 %2, %6\n\tds_read_b64_tr_b16 %3, %7\n\ts_waitcnt lgkmcnt(0)"
.LBB0_1491:
	v_sub_f32_e32 v32, v32, v243
	v_exp_f32_e32 v138, v32
	v_sub_f32_e32 v32, v33, v243
	v_exp_f32_e32 v139, v32
	v_sub_f32_e32 v32, v34, v243
	v_exp_f32_e32 v140, v32
	v_sub_f32_e32 v32, v35, v243
	v_exp_f32_e32 v141, v32
	v_sub_f32_e32 v32, v36, v243
	v_exp_f32_e32 v142, v32
	v_sub_f32_e32 v32, v37, v243
	v_exp_f32_e32 v143, v32
	v_sub_f32_e32 v32, v38, v243
	v_exp_f32_e32 v144, v32
	v_sub_f32_e32 v32, v39, v243
	v_exp_f32_e32 v145, v32
	v_sub_f32_e32 v32, v40, v243
	v_exp_f32_e32 v40, v32
	v_sub_f32_e32 v32, v41, v243
	v_exp_f32_e32 v41, v32
	v_sub_f32_e32 v32, v42, v243
	v_exp_f32_e32 v42, v32
	v_sub_f32_e32 v32, v43, v243
	v_exp_f32_e32 v43, v32
	v_sub_f32_e32 v32, v44, v243
	v_exp_f32_e32 v44, v32
	v_sub_f32_e32 v32, v45, v243
	v_exp_f32_e32 v45, v32
	v_sub_f32_e32 v32, v46, v243
	v_exp_f32_e32 v46, v32
	v_sub_f32_e32 v32, v47, v243
	v_exp_f32_e32 v47, v32
	v_cvt_pk_bf16_f32 v32, v138, v139
	v_add_f32_e32 v138, 0, v138
	v_add_f32_e32 v138, v139, v138
	v_add_f32_e32 v138, v140, v138
	v_add_f32_e32 v138, v141, v138
	v_add_f32_e32 v138, v142, v138
	v_add_f32_e32 v138, v143, v138
	v_add_f32_e32 v138, v144, v138
	v_add_f32_e32 v138, v145, v138
	v_cvt_pk_bf16_f32 v36, v40, v41
	v_add_f32_e32 v40, v40, v138
	v_add_f32_e32 v40, v41, v40
	v_add_f32_e32 v40, v42, v40
	v_add_f32_e32 v40, v43, v40
	v_add_f32_e32 v40, v44, v40
	v_add_f32_e32 v40, v45, v40
	v_cvt_pk_bf16_f32 v33, v140, v141
	v_cvt_pk_bf16_f32 v34, v142, v143
	v_cvt_pk_bf16_f32 v35, v144, v145
	v_add_f32_e32 v40, v46, v40
	v_cvt_pk_bf16_f32 v37, v42, v43
	v_cvt_pk_bf16_f32 v38, v44, v45
	v_cvt_pk_bf16_f32 v39, v46, v47
	v_add_f32_e32 v138, v47, v40
	v_add_u32_e32 v139, 0x480, v124
	v_add_u32_e32 v140, 64, v124
	v_add_u32_e32 v141, 0x4c0, v124
	ds_read_b64_tr_b16 v[44:45], v124
	ds_read_b64_tr_b16 v[46:47], v139
	ds_read_b64_tr_b16 v[40:41], v140
	ds_read_b64_tr_b16 v[42:43], v141
	s_waitcnt lgkmcnt(0)
	v_add_f32_e32 v244, v245, v138
	v_mfma_f32_32x32x16_bf16 v[0:15], v[44:47], v[32:35], v[0:15]
	v_add_u32_e32 v44, 0x900, v124
	v_add_u32_e32 v45, 0xd80, v124
	v_add_u32_e32 v46, 0x940, v124
	v_add_u32_e32 v47, 0xdc0, v124
	v_mfma_f32_32x32x16_bf16 v[16:31], v[40:43], v[32:35], v[16:31]
	ds_read_b64_tr_b16 v[40:41], v44
	ds_read_b64_tr_b16 v[42:43], v45
	ds_read_b64_tr_b16 v[32:33], v46
	ds_read_b64_tr_b16 v[34:35], v47
	s_waitcnt lgkmcnt(0)
	s_nop 0
	v_mfma_f32_32x32x16_bf16 v[0:15], v[40:43], v[36:39], v[0:15]
	v_mfma_f32_32x32x16_bf16 v[16:31], v[32:35], v[36:39], v[16:31]
	s_and_saveexec_b64 s[74:75], s[70:71]
	s_cbranch_execz .LBB0_1495
	ds_read_b128 v[32:35], v205
	ds_read_b128 v[138:141], v205 offset:32
	v_readlane_b32 s16, v254, 31
	v_readlane_b32 s17, v254, 32
	s_waitcnt lgkmcnt(1)
	v_mfma_f32_32x32x16_bf16 v[32:47], v[32:35], v[104:107], 0
	ds_read_b128 v[104:107], v205 offset:64
	s_waitcnt lgkmcnt(1)
	v_mfma_f32_32x32x16_bf16 v[32:47], v[138:141], v[108:111], v[32:47]
	s_waitcnt lgkmcnt(0)
	v_mfma_f32_32x32x16_bf16 v[32:47], v[104:107], v[100:103], v[32:47]
	ds_read_b128 v[100:103], v205 offset:96
	s_waitcnt lgkmcnt(0)
; DI float max3f(float a, float b, float c) { float d; asm("v_max3_f32 %0, %1, %2, %3" : "=v"(d) : "v"(a), "v"(b), "v"(c)); return d; }
; DI void attn_d6_loop(char* lds, const Params& p, int layer, int first, int stride, int total) {
;     ...
;       const int rel0 = key0 + 4 * lh - qrow;
; #pragma unroll
;       for (int r2 = 0; r2 < 16; ++r2) { const int rel = rel0 + (r2 & 3) + 8 * (r2 >> 2), v = qrow + rel;
;         const bool ok = (rel >= -64) && (rel <= 64) && (v >= 0) && (v < L); S[r2] = ok ? fmaf(-slope2, fabsf((float)rel), S[r2]) : -1e30f; }
;       float mx = S[0];
; #pragma unroll
;       for (int r2 = 1; r2 < 15; r2 += 2) mx = max3f(mx, S[r2], S[r2 + 1]);
;       mx = fmaxf(mx, S[15]);
;       if (__any(mx > m + 8.f)) {
;         mx = fmaxf(mx, __shfl_xor(mx, 32));
;         const float mnew = fmaxf(m, mx);
;         const float al = __builtin_amdgcn_exp2f(m - mnew); l *= al; O0 *= al; O1 *= al;
;         m = mnew;
;       }
	v_mfma_f32_32x32x16_bf16 v[32:47], v[100:103], v[96:99], v[32:47]
	v_add_u32_e32 v96, v131, v220
	v_cmp_lt_i32_e32 vcc, -1, v96
	s_and_b64 s[80:81], s[16:17], vcc
	v_cmp_gt_i32_e32 vcc, s1, v96
	v_cvt_f32_i32_e32 v96, v220
	s_and_b64 vcc, s[80:81], vcc
	v_readlane_b32 s16, v254, 33
	v_readlane_b32 s17, v254, 34
	s_nop 3
	v_fma_f32 v32, v129, |v96|, v32
	v_add_u32_e32 v96, v131, v221
	v_cndmask_b32_e32 v32, v241, v32, vcc
	v_cmp_lt_i32_e32 vcc, -1, v96
	s_and_b64 s[80:81], s[16:17], vcc
	v_cmp_gt_i32_e32 vcc, s1, v96
	v_cvt_f32_i32_e32 v96, v221
	s_and_b64 vcc, s[80:81], vcc
	v_readlane_b32 s16, v254, 35
	v_readlane_b32 s17, v254, 36
	v_fma_f32 v33, v129, |v96|, v33
	v_add_u32_e32 v96, v131, v222
	v_cndmask_b32_e32 v33, v241, v33, vcc
	v_cmp_lt_i32_e32 vcc, -1, v96
	s_and_b64 s[80:81], s[16:17], vcc
	v_cmp_gt_i32_e32 vcc, s1, v96
	v_cvt_f32_i32_e32 v96, v222
	s_and_b64 vcc, s[80:81], vcc
	v_readlane_b32 s16, v254, 37
	v_readlane_b32 s17, v254, 38
	v_fma_f32 v34, v129, |v96|, v34
	v_add_u32_e32 v96, v131, v223
	v_cndmask_b32_e32 v34, v241, v34, vcc
	v_cmp_lt_i32_e32 vcc, -1, v96
	s_and_b64 s[80:81], s[16:17], vcc
	v_cmp_gt_i32_e32 vcc, s1, v96
	v_cvt_f32_i32_e32 v96, v223
	s_and_b64 vcc, s[80:81], vcc
	v_readlane_b32 s16, v254, 39
	v_readlane_b32 s17, v254, 40
	v_fma_f32 v35, v129, |v96|, v35
	v_add_u32_e32 v96, v131, v224
	v_cndmask_b32_e32 v35, v241, v35, vcc
	v_cmp_lt_i32_e32 vcc, -1, v96
	s_and_b64 s[80:81], s[16:17], vcc
	v_cmp_gt_i32_e32 vcc, s1, v96
	v_cvt_f32_i32_e32 v96, v224
	s_and_b64 vcc, s[80:81], vcc
	v_readlane_b32 s16, v254, 41
	v_readlane_b32 s17, v254, 42
	v_fma_f32 v36, v129, |v96|, v36
	v_add_u32_e32 v96, v131, v225
	v_cndmask_b32_e32 v36, v241, v36, vcc
	v_cmp_lt_i32_e32 vcc, -1, v96
	s_and_b64 s[80:81], s[16:17], vcc
	v_cmp_gt_i32_e32 vcc, s1, v96
	v_cvt_f32_i32_e32 v96, v225
	s_and_b64 vcc, s[80:81], vcc
	v_readlane_b32 s16, v254, 43
	v_readlane_b32 s17, v254, 44
	v_fma_f32 v37, v129, |v96|, v37
	v_add_u32_e32 v96, v131, v230
	v_cndmask_b32_e32 v37, v241, v37, vcc
	v_cmp_lt_i32_e32 vcc, -1, v96
	s_and_b64 s[80:81], s[16:17], vcc
	v_cmp_gt_i32_e32 vcc, s1, v96
	v_cvt_f32_i32_e32 v96, v230
	s_and_b64 vcc, s[80:81], vcc
	v_readlane_b32 s16, v254, 45
	v_readlane_b32 s17, v254, 46
	v_fma_f32 v38, v129, |v96|, v38
	v_add_u32_e32 v96, v131, v231
	v_cndmask_b32_e32 v38, v241, v38, vcc
	v_cmp_lt_i32_e32 vcc, -1, v96
	s_and_b64 s[80:81], s[16:17], vcc
	v_cmp_gt_i32_e32 vcc, s1, v96
	v_cvt_f32_i32_e32 v96, v231
	s_and_b64 vcc, s[80:81], vcc
	v_readlane_b32 s16, v254, 47
	v_readlane_b32 s17, v254, 48
	v_fma_f32 v39, v129, |v96|, v39
	v_add_u32_e32 v96, v131, v232
	v_cndmask_b32_e32 v39, v241, v39, vcc
	v_cmp_lt_i32_e32 vcc, -1, v96
	s_and_b64 s[80:81], s[16:17], vcc
	v_cmp_gt_i32_e32 vcc, s1, v96
	v_cvt_f32_i32_e32 v96, v232
	s_and_b64 vcc, s[80:81], vcc
	v_readlane_b32 s16, v254, 49
	v_readlane_b32 s17, v254, 50
	v_fma_f32 v40, v129, |v96|, v40
	v_add_u32_e32 v96, v131, v233
	v_cndmask_b32_e32 v40, v241, v40, vcc
	v_cmp_lt_i32_e32 vcc, -1, v96
	s_and_b64 s[80:81], s[16:17], vcc
	v_cmp_gt_i32_e32 vcc, s1, v96
	v_cvt_f32_i32_e32 v96, v233
	s_and_b64 vcc, s[80:81], vcc
	v_readlane_b32 s16, v254, 51
	v_readlane_b32 s17, v254, 52
	v_fma_f32 v41, v129, |v96|, v41
	v_add_u32_e32 v96, v131, v234
	v_cndmask_b32_e32 v41, v241, v41, vcc
	v_cmp_lt_i32_e32 vcc, -1, v96
	s_and_b64 s[80:81], s[16:17], vcc
	v_cmp_gt_i32_e32 vcc, s1, v96
	v_cvt_f32_i32_e32 v96, v234
	s_and_b64 vcc, s[80:81], vcc
	v_readlane_b32 s16, v254, 53
	v_readlane_b32 s17, v254, 54
	v_fma_f32 v42, v129, |v96|, v42
	v_add_u32_e32 v96, v131, v235
	v_cndmask_b32_e32 v42, v241, v42, vcc
	v_cmp_lt_i32_e32 vcc, -1, v96
	s_and_b64 s[80:81], s[16:17], vcc
	v_cmp_gt_i32_e32 vcc, s1, v96
	v_cvt_f32_i32_e32 v96, v235
	s_and_b64 vcc, s[80:81], vcc
	v_readlane_b32 s16, v254, 55
	v_readlane_b32 s17, v254, 56
	v_fma_f32 v43, v129, |v96|, v43
	v_add_u32_e32 v96, v131, v236
	v_cndmask_b32_e32 v43, v241, v43, vcc
	v_cmp_lt_i32_e32 vcc, -1, v96
	s_and_b64 s[80:81], s[16:17], vcc
	v_cmp_gt_i32_e32 vcc, s1, v96
	v_cvt_f32_i32_e32 v96, v236
	s_and_b64 vcc, s[80:81], vcc
	v_readlane_b32 s16, v254, 57
	v_readlane_b32 s17, v254, 58
	v_fma_f32 v44, v129, |v96|, v44
	v_add_u32_e32 v96, v131, v237
	v_cndmask_b32_e32 v44, v241, v44, vcc
	v_cmp_lt_i32_e32 vcc, -1, v96
	s_and_b64 s[80:81], s[16:17], vcc
	v_cmp_gt_i32_e32 vcc, s1, v96
	v_cvt_f32_i32_e32 v96, v237
	s_and_b64 vcc, s[80:81], vcc
	v_readlane_b32 s16, v254, 59
	v_readlane_b32 s17, v254, 60
	v_fma_f32 v45, v129, |v96|, v45
	v_add_u32_e32 v96, v131, v238
	v_cndmask_b32_e32 v45, v241, v45, vcc
	v_cmp_lt_i32_e32 vcc, -1, v96
	s_and_b64 s[80:81], s[16:17], vcc
	v_cmp_gt_i32_e32 vcc, s1, v96
	v_cvt_f32_i32_e32 v96, v238
	s_and_b64 vcc, s[80:81], vcc
	v_readlane_b32 s16, v254, 61
	v_readlane_b32 s17, v254, 62
	v_fma_f32 v46, v129, |v96|, v46
	v_add_u32_e32 v96, v131, v239
	v_cndmask_b32_e32 v46, v241, v46, vcc
	v_cmp_lt_i32_e32 vcc, -1, v96
	s_and_b64 s[80:81], s[16:17], vcc
	v_cmp_gt_i32_e32 vcc, s1, v96
	v_cvt_f32_i32_e32 v96, v239
	s_and_b64 vcc, s[80:81], vcc
	v_add_f32_e32 v97, 0x41000000, v243
	v_fma_f32 v47, v129, |v96|, v47
	v_max3_f32 v96, v32, v33, v34
	v_cndmask_b32_e32 v47, v241, v47, vcc
	v_max3_f32 v96, v96, v35, v36
	v_max3_f32 v96, v96, v37, v38
	v_max3_f32 v96, v96, v39, v40
	v_max3_f32 v96, v96, v41, v42
	v_max3_f32 v96, v96, v43, v44
	v_max3_f32 v96, v96, v45, v46
	v_max_f32_e32 v96, v96, v96
	v_max_f32_e32 v96, v96, v47
	v_cmp_gt_f32_e32 vcc, v96, v97
	s_cbranch_vccz .LBB0_1494
	v_cmp_lt_i32_e32 vcc, v209, v208
	s_nop 1
	v_cndmask_b32_e32 v97, v207, v209, vcc
	v_lshlrev_b32_e32 v97, 2, v97
	ds_bpermute_b32 v97, v97, v96
	s_waitcnt lgkmcnt(0)
	v_max3_f32 v97, v243, v96, v97
	v_sub_f32_e32 v96, v243, v97
	v_exp_f32_e32 v96, v96
	v_mov_b32_e32 v243, v97
	v_mul_f32_e32 v244, v244, v96
	v_pk_mul_f32 v[14:15], v[14:15], v[96:97] op_sel_hi:[1,0]
	v_pk_mul_f32 v[12:13], v[12:13], v[96:97] op_sel_hi:[1,0]
	v_pk_mul_f32 v[10:11], v[10:11], v[96:97] op_sel_hi:[1,0]
	v_pk_mul_f32 v[8:9], v[8:9], v[96:97] op_sel_hi:[1,0]
	v_pk_mul_f32 v[6:7], v[6:7], v[96:97] op_sel_hi:[1,0]
	v_pk_mul_f32 v[4:5], v[4:5], v[96:97] op_sel_hi:[1,0]
	v_pk_mul_f32 v[2:3], v[2:3], v[96:97] op_sel_hi:[1,0]
	v_pk_mul_f32 v[0:1], v[0:1], v[96:97] op_sel_hi:[1,0]
	v_pk_mul_f32 v[30:31], v[30:31], v[96:97] op_sel_hi:[1,0]
	v_pk_mul_f32 v[28:29], v[28:29], v[96:97] op_sel_hi:[1,0]
	v_pk_mul_f32 v[26:27], v[26:27], v[96:97] op_sel_hi:[1,0]
	v_pk_mul_f32 v[24:25], v[24:25], v[96:97] op_sel_hi:[1,0]
	v_pk_mul_f32 v[22:23], v[22:23], v[96:97] op_sel_hi:[1,0]
	v_pk_mul_f32 v[20:21], v[20:21], v[96:97] op_sel_hi:[1,0]
	v_pk_mul_f32 v[18:19], v[18:19], v[96:97] op_sel_hi:[1,0]
	v_pk_mul_f32 v[16:17], v[16:17], v[96:97] op_sel_hi:[1,0]
